# v37 + softmax chain trim + K-loop vmcnt/lgkmcnt waits merged into one s_waitcnt at 32 phase boundaries
# speedup vs baseline: 1.0051x; 1.0051x over previous
; #define PG8_STAGE(bufoff, gbase, voff) do { _Pragma("unroll") for (int _i = 0; _i < 2; ++_i) \
;         __builtin_amdgcn_global_load_lds((const unsigned*)((const char*)(gbase) + (voff)[_i]), (PG8_LAS unsigned*)(lds + (bufoff) + ldsw + _i * 8192), 16, 0, 0); } while (0)
; #define PG8_LDA(dst, b, h) do { _Pragma("unroll") for (int m = 0; m < 4; ++m) _Pragma("unroll") for (int k = 0; k < 2; ++k) dst[m][k] = *(const PG8_LAS bf16x8*)(lds + PG8_SA(b, h) + aoff + m * 2048 + k * 1024); } while (0)
; #define PG8_LDB(dst, b, h) do { _Pragma("unroll") for (int n = 0; n < 2; ++n) _Pragma("unroll") for (int k = 0; k < 2; ++k) dst[n][k] = *(const PG8_LAS bf16x8*)(lds + PG8_SB(b, h) + boff + n * 2048 + k * 1024); } while (0)
; #define PG8_WAIT_V(n) asm volatile("s_waitcnt vmcnt(" #n ")" ::: "memory")
; #define PG8_WAIT_L(n) asm volatile("s_waitcnt lgkmcnt(" #n ")" ::: "memory")
; #define PG8_BAR __builtin_amdgcn_s_barrier()
; #define PG8_SCHED __builtin_amdgcn_sched_barrier(0)
; template <class Epi, class Sched, bool ALIGN_EPI = false, bool SP2 = false, bool F16 = false>
; __device__ __forceinline__ void gemm_phase(PG8_LAS unsigned char* lds, const Gemm g, const Sched& S, const Epi& E) {
;     ...
;         for (int t = 0; t < nt; t += 2) {
;             const bool last = (t == nt - 2);
;             const char* a1 = cA + (size_t)(t + 1) * kstep;
;             const char* a2 = last ? nA : cA + (size_t)(t + 2) * kstep; const char* b2 = last ? nB : cB + (size_t)(t + 2) * kstep;
;             const char* a3 = a2 + kstep; const char* b3 = b2 + kstep;
;             if (last && has_next) S.a_ready(nxt);
;             if constexpr (SP2) {
;             PG8_LDB(B0, 0, 0); PG8_LDB(B1, 0, 1); PG8_SCHED; PG8_LDA(At, 0, 0); PG8_STAGE(PG8_SA(1, 1), a1 + hstepA, voffA);
;             PG8_WAIT_V(8); PG8_WAIT_L(0); PG8_BAR; PG8_MMA(0, 0, At, B0); PG8_MMA(0, 1, At, B1); PG8_BAR; PG8_SCHED;
;             PG8_LDA(At, 0, 1); PG8_STAGE(PG8_SB(0, 0), b2, voffB); PG8_STAGE(PG8_SB(0, 1), b2 + hstepB, voffB); PG8_STAGE(PG8_SA(0, 0), a2, voffA);
;             PG8_WAIT_V(8); PG8_WAIT_L(0); PG8_BAR; PG8_MMA(1, 0, At, B0); PG8_MMA(1, 1, At, B1); PG8_BAR; PG8_SCHED;
.Lpk_gu:
	s_add_i32 s82, s54, 2
	s_add_u32 s83, s52, 0x80
	s_addc_u32 s55, s53, 0
	s_add_i32 vcc_lo, 0, 0x10000
	s_cmp_eq_u32 s74, s54
	s_cselect_b32 s55, s39, s55
	s_cselect_b32 s54, s38, s83
	s_cselect_b32 s95, s47, s81
	s_cselect_b32 s94, s46, s80
	s_add_i32 s83, 0, 0x14000
	ds_read_b128 v[130:133], v139
	ds_read_b128 v[134:137], v139 offset:1024
	ds_read_b128 v[152:155], v139 offset:2048
	ds_read_b128 v[156:159], v139 offset:3072
	ds_read_b128 v[160:163], v141
	ds_read_b128 v[166:169], v141 offset:1024
	ds_read_b128 v[184:187], v141 offset:2048
	ds_read_b128 v[188:191], v141 offset:3072
	s_add_i32 m0, s22, 0xc000
	ds_read_b128 v[192:195], v183
	ds_read_b128 v[204:207], v183 offset:1024
	ds_read_b128 v[208:211], v183 offset:2048
	ds_read_b128 v[212:215], v183 offset:3072
	ds_read_b128 v[216:219], v183 offset:4096
	ds_read_b128 v[220:223], v183 offset:5120
	ds_read_b128 v[224:227], v183 offset:6144
	ds_read_b128 v[228:231], v183 offset:7168
	global_load_lds_dwordx4 v148, s[52:53]
	s_add_i32 m0, s22, 0xe000
	s_nop 0
	global_load_lds_dwordx4 v150, s[52:53]
	s_waitcnt vmcnt(8) lgkmcnt(0)
	s_setprio 1
	s_barrier
	v_mfma_f32_16x16x32_f16 v[122:125], v[130:133], v[192:195], 0
	v_mfma_f32_16x16x32_f16 v[114:117], v[152:155], v[192:195], 0
	v_mfma_f32_16x16x32_f16 v[106:109], v[130:133], v[208:211], 0
	v_mfma_f32_16x16x32_f16 v[98:101], v[152:155], v[208:211], 0
	v_mfma_f32_16x16x32_f16 v[90:93], v[130:133], v[216:219], 0
	v_mfma_f32_16x16x32_f16 v[82:85], v[152:155], v[216:219], 0
	v_mfma_f32_16x16x32_f16 v[74:77], v[130:133], v[224:227], 0
	v_mfma_f32_16x16x32_f16 v[66:69], v[152:155], v[224:227], 0
	v_mfma_f32_16x16x32_f16 v[122:125], v[134:137], v[204:207], v[122:125]
	v_mfma_f32_16x16x32_f16 v[114:117], v[156:159], v[204:207], v[114:117]
	v_mfma_f32_16x16x32_f16 v[106:109], v[134:137], v[212:215], v[106:109]
	v_mfma_f32_16x16x32_f16 v[98:101], v[156:159], v[212:215], v[98:101]
	v_mfma_f32_16x16x32_f16 v[90:93], v[134:137], v[220:223], v[90:93]
	v_mfma_f32_16x16x32_f16 v[82:85], v[156:159], v[220:223], v[82:85]
	v_mfma_f32_16x16x32_f16 v[74:77], v[134:137], v[228:231], v[74:77]
	v_mfma_f32_16x16x32_f16 v[66:69], v[156:159], v[228:231], v[66:69]
	v_mfma_f32_16x16x32_f16 v[126:129], v[160:163], v[192:195], 0
	v_mfma_f32_16x16x32_f16 v[118:121], v[184:187], v[192:195], 0
	v_mfma_f32_16x16x32_f16 v[110:113], v[160:163], v[208:211], 0
	v_mfma_f32_16x16x32_f16 v[102:105], v[184:187], v[208:211], 0
	v_mfma_f32_16x16x32_f16 v[94:97], v[160:163], v[216:219], 0
	v_mfma_f32_16x16x32_f16 v[86:89], v[184:187], v[216:219], 0
	v_mfma_f32_16x16x32_f16 v[78:81], v[160:163], v[224:227], 0
	v_mfma_f32_16x16x32_f16 v[70:73], v[184:187], v[224:227], 0
	v_mfma_f32_16x16x32_f16 v[126:129], v[166:169], v[204:207], v[126:129]
	v_mfma_f32_16x16x32_f16 v[118:121], v[188:191], v[204:207], v[118:121]
	v_mfma_f32_16x16x32_f16 v[110:113], v[166:169], v[212:215], v[110:113]
	v_mfma_f32_16x16x32_f16 v[102:105], v[188:191], v[212:215], v[102:105]
	v_mfma_f32_16x16x32_f16 v[94:97], v[166:169], v[220:223], v[94:97]
	v_mfma_f32_16x16x32_f16 v[86:89], v[188:191], v[220:223], v[86:89]
	v_mfma_f32_16x16x32_f16 v[78:81], v[166:169], v[228:231], v[78:81]
	v_mfma_f32_16x16x32_f16 v[70:73], v[188:191], v[228:231], v[70:73]
	s_barrier
	s_setprio 0
	s_add_i32 vcc_lo, vcc_lo, s2
	s_mov_b32 m0, vcc_lo
	s_nop 0
	global_load_lds_dwordx4 v142, s[94:95]
	ds_read_b128 v[192:195], v183 offset:16384
	ds_read_b128 v[204:207], v183 offset:17408
	ds_read_b128 v[208:211], v183 offset:18432
	ds_read_b128 v[212:215], v183 offset:19456
	ds_read_b128 v[216:219], v183 offset:20480
	ds_read_b128 v[220:223], v183 offset:21504
	ds_read_b128 v[224:227], v183 offset:22528
	ds_read_b128 v[228:231], v183 offset:23552
	s_add_i32 m0, vcc_lo, 0x2000
	s_nop 0
	global_load_lds_dwordx4 v138, s[94:95]
	s_add_i32 s83, s83, s2
	s_add_u32 s94, s94, s48
	s_addc_u32 s95, s95, 0
	s_mov_b32 m0, s83
	s_nop 0
	global_load_lds_dwordx4 v142, s[94:95]
	s_add_i32 m0, s83, 0x2000
	s_nop 0
	global_load_lds_dwordx4 v138, s[94:95]
	s_mov_b32 m0, s22
	s_nop 0
	global_load_lds_dwordx4 v144, s[54:55]
	s_mov_b32 m0, s33
	s_nop 0
	global_load_lds_dwordx4 v140, s[54:55]
	s_waitcnt vmcnt(8) lgkmcnt(0)
	s_setprio 1
	s_barrier
	v_mfma_f32_16x16x32_f16 v[58:61], v[130:133], v[192:195], 0
	v_mfma_f32_16x16x32_f16 v[50:53], v[152:155], v[192:195], 0
	v_mfma_f32_16x16x32_f16 v[42:45], v[130:133], v[208:211], 0
	v_mfma_f32_16x16x32_f16 v[34:37], v[152:155], v[208:211], 0
	v_mfma_f32_16x16x32_f16 v[26:29], v[130:133], v[216:219], 0
	v_mfma_f32_16x16x32_f16 v[18:21], v[152:155], v[216:219], 0
	v_mfma_f32_16x16x32_f16 v[10:13], v[130:133], v[224:227], 0
	v_mfma_f32_16x16x32_f16 v[6:9], v[152:155], v[224:227], 0
	v_mfma_f32_16x16x32_f16 v[58:61], v[134:137], v[204:207], v[58:61]
	v_mfma_f32_16x16x32_f16 v[50:53], v[156:159], v[204:207], v[50:53]
	v_mfma_f32_16x16x32_f16 v[42:45], v[134:137], v[212:215], v[42:45]
	v_mfma_f32_16x16x32_f16 v[34:37], v[156:159], v[212:215], v[34:37]
	v_mfma_f32_16x16x32_f16 v[26:29], v[134:137], v[220:223], v[26:29]
	v_mfma_f32_16x16x32_f16 v[18:21], v[156:159], v[220:223], v[18:21]
	v_mfma_f32_16x16x32_f16 v[10:13], v[134:137], v[228:231], v[10:13]
	v_mfma_f32_16x16x32_f16 v[6:9], v[156:159], v[228:231], v[6:9]
	v_mfma_f32_16x16x32_f16 v[62:65], v[160:163], v[192:195], 0
	v_mfma_f32_16x16x32_f16 v[54:57], v[184:187], v[192:195], 0
	v_mfma_f32_16x16x32_f16 v[46:49], v[160:163], v[208:211], 0
	v_mfma_f32_16x16x32_f16 v[38:41], v[184:187], v[208:211], 0
	v_mfma_f32_16x16x32_f16 v[30:33], v[160:163], v[216:219], 0
	v_mfma_f32_16x16x32_f16 v[22:25], v[184:187], v[216:219], 0
	v_mfma_f32_16x16x32_f16 v[14:17], v[160:163], v[224:227], 0
	v_mfma_f32_16x16x32_f16 v[2:5], v[184:187], v[224:227], 0
	v_mfma_f32_16x16x32_f16 v[62:65], v[166:169], v[204:207], v[62:65]
	v_mfma_f32_16x16x32_f16 v[54:57], v[188:191], v[204:207], v[54:57]
	v_mfma_f32_16x16x32_f16 v[46:49], v[166:169], v[212:215], v[46:49]
	v_mfma_f32_16x16x32_f16 v[38:41], v[188:191], v[212:215], v[38:41]
	v_mfma_f32_16x16x32_f16 v[30:33], v[166:169], v[220:223], v[30:33]
	v_mfma_f32_16x16x32_f16 v[22:25], v[188:191], v[220:223], v[22:25]
	v_mfma_f32_16x16x32_f16 v[14:17], v[166:169], v[228:231], v[14:17]
	v_mfma_f32_16x16x32_f16 v[2:5], v[188:191], v[228:231], v[2:5]
	s_barrier
; #define PG8_STAGE(bufoff, gbase, voff) do { _Pragma("unroll") for (int _i = 0; _i < 2; ++_i) \
;         __builtin_amdgcn_global_load_lds((const unsigned*)((const char*)(gbase) + (voff)[_i]), (PG8_LAS unsigned*)(lds + (bufoff) + ldsw + _i * 8192), 16, 0, 0); } while (0)
; #define PG8_LDA(dst, b, h) do { _Pragma("unroll") for (int m = 0; m < 4; ++m) _Pragma("unroll") for (int k = 0; k < 2; ++k) dst[m][k] = *(const PG8_LAS bf16x8*)(lds + PG8_SA(b, h) + aoff + m * 2048 + k * 1024); } while (0)
; #define PG8_LDB(dst, b, h) do { _Pragma("unroll") for (int n = 0; n < 2; ++n) _Pragma("unroll") for (int k = 0; k < 2; ++k) dst[n][k] = *(const PG8_LAS bf16x8*)(lds + PG8_SB(b, h) + boff + n * 2048 + k * 1024); } while (0)
; #define PG8_WAIT_V(n) asm volatile("s_waitcnt vmcnt(" #n ")" ::: "memory")
; #define PG8_WAIT_L(n) asm volatile("s_waitcnt lgkmcnt(" #n ")" ::: "memory")
; #define PG8_BAR __builtin_amdgcn_s_barrier()
; #define PG8_SCHED __builtin_amdgcn_sched_barrier(0)
; template <class Epi, class Sched, bool ALIGN_EPI = false, bool SP2 = false, bool F16 = false>
; __device__ __forceinline__ void gemm_phase(PG8_LAS unsigned char* lds, const Gemm g, const Sched& S, const Epi& E) {
;     ...
;             PG8_LDB(B0, 1, 0); PG8_LDB(B1, 1, 1); PG8_SCHED; PG8_LDA(At, 1, 0); PG8_STAGE(PG8_SA(0, 1), a2 + hstepA, voffA);
;             PG8_WAIT_V(8); PG8_WAIT_L(0); PG8_BAR; PG8_MMA(0, 0, At, B0); PG8_MMA(0, 1, At, B1); PG8_BAR; PG8_SCHED;
;             PG8_LDA(At, 1, 1); PG8_STAGE(PG8_SB(1, 0), b3, voffB); PG8_STAGE(PG8_SB(1, 1), b3 + hstepB, voffB); PG8_STAGE(PG8_SA(1, 0), a3, voffA);
;             PG8_WAIT_V(8); PG8_WAIT_L(0); PG8_BAR; PG8_MMA(1, 0, At, B0); PG8_MMA(1, 1, At, B1); PG8_BAR; PG8_SCHED;
	s_setprio 0
	s_add_i32 s83, 0, 0x18000
	s_add_i32 s94, 0, 0x1c000
	ds_read_b128 v[130:133], v143
	ds_read_b128 v[134:137], v143 offset:1024
	ds_read_b128 v[152:155], v143 offset:2048
	ds_read_b128 v[156:159], v143 offset:3072
	ds_read_b128 v[160:163], v145
	ds_read_b128 v[166:169], v145 offset:1024
	ds_read_b128 v[184:187], v145 offset:2048
	ds_read_b128 v[188:191], v145 offset:3072
	s_add_u32 s54, s54, s8
	s_addc_u32 s55, s55, 0
	s_mov_b32 m0, s12
	ds_read_b128 v[192:195], v183 offset:32768
	ds_read_b128 v[204:207], v183 offset:33792
	ds_read_b128 v[208:211], v183 offset:34816
	ds_read_b128 v[212:215], v183 offset:35840
	ds_read_b128 v[216:219], v183 offset:36864
	ds_read_b128 v[220:223], v183 offset:37888
	ds_read_b128 v[224:227], v183 offset:38912
	ds_read_b128 v[228:231], v183 offset:39936
	global_load_lds_dwordx4 v144, s[54:55]
	s_mov_b32 m0, s13
	s_nop 0
	global_load_lds_dwordx4 v140, s[54:55]
	s_waitcnt vmcnt(8) lgkmcnt(0)
	s_setprio 1
	s_barrier
	v_mfma_f32_16x16x32_f16 v[122:125], v[130:133], v[192:195], v[122:125]
	v_mfma_f32_16x16x32_f16 v[114:117], v[152:155], v[192:195], v[114:117]
	v_mfma_f32_16x16x32_f16 v[106:109], v[130:133], v[208:211], v[106:109]
	v_mfma_f32_16x16x32_f16 v[98:101], v[152:155], v[208:211], v[98:101]
	v_mfma_f32_16x16x32_f16 v[90:93], v[130:133], v[216:219], v[90:93]
	v_mfma_f32_16x16x32_f16 v[82:85], v[152:155], v[216:219], v[82:85]
	v_mfma_f32_16x16x32_f16 v[74:77], v[130:133], v[224:227], v[74:77]
	v_mfma_f32_16x16x32_f16 v[66:69], v[152:155], v[224:227], v[66:69]
	v_mfma_f32_16x16x32_f16 v[122:125], v[134:137], v[204:207], v[122:125]
	v_mfma_f32_16x16x32_f16 v[114:117], v[156:159], v[204:207], v[114:117]
	v_mfma_f32_16x16x32_f16 v[106:109], v[134:137], v[212:215], v[106:109]
	v_mfma_f32_16x16x32_f16 v[98:101], v[156:159], v[212:215], v[98:101]
	v_mfma_f32_16x16x32_f16 v[90:93], v[134:137], v[220:223], v[90:93]
	v_mfma_f32_16x16x32_f16 v[82:85], v[156:159], v[220:223], v[82:85]
	v_mfma_f32_16x16x32_f16 v[74:77], v[134:137], v[228:231], v[74:77]
	v_mfma_f32_16x16x32_f16 v[66:69], v[156:159], v[228:231], v[66:69]
	v_mfma_f32_16x16x32_f16 v[126:129], v[160:163], v[192:195], v[126:129]
	v_mfma_f32_16x16x32_f16 v[118:121], v[184:187], v[192:195], v[118:121]
	v_mfma_f32_16x16x32_f16 v[110:113], v[160:163], v[208:211], v[110:113]
	v_mfma_f32_16x16x32_f16 v[102:105], v[184:187], v[208:211], v[102:105]
	v_mfma_f32_16x16x32_f16 v[94:97], v[160:163], v[216:219], v[94:97]
	v_mfma_f32_16x16x32_f16 v[86:89], v[184:187], v[216:219], v[86:89]
	v_mfma_f32_16x16x32_f16 v[78:81], v[160:163], v[224:227], v[78:81]
	v_mfma_f32_16x16x32_f16 v[70:73], v[184:187], v[224:227], v[70:73]
	v_mfma_f32_16x16x32_f16 v[126:129], v[166:169], v[204:207], v[126:129]
	v_mfma_f32_16x16x32_f16 v[118:121], v[188:191], v[204:207], v[118:121]
	v_mfma_f32_16x16x32_f16 v[110:113], v[166:169], v[212:215], v[110:113]
	v_mfma_f32_16x16x32_f16 v[102:105], v[188:191], v[212:215], v[102:105]
	v_mfma_f32_16x16x32_f16 v[94:97], v[166:169], v[220:223], v[94:97]
	v_mfma_f32_16x16x32_f16 v[86:89], v[188:191], v[220:223], v[86:89]
	v_mfma_f32_16x16x32_f16 v[78:81], v[166:169], v[228:231], v[78:81]
	v_mfma_f32_16x16x32_f16 v[70:73], v[188:191], v[228:231], v[70:73]
	s_barrier
	s_setprio 0
	s_add_i32 s54, s83, s2
	s_add_i32 vcc_hi, s82, -2
	s_cmp_eq_u32 s74, vcc_hi
	s_cselect_b32 s99, s47, s81
	s_cselect_b32 s98, s46, s80
	s_add_u32 s98, s98, s92
	s_addc_u32 s99, s99, s93
	s_mov_b32 m0, s54
	s_nop 0
	global_load_lds_dwordx4 v142, s[98:99]
	ds_read_b128 v[192:195], v183 offset:49152
	ds_read_b128 v[204:207], v183 offset:50176
	ds_read_b128 v[208:211], v183 offset:51200
	ds_read_b128 v[212:215], v183 offset:52224
	ds_read_b128 v[216:219], v183 offset:53248
	ds_read_b128 v[220:223], v183 offset:54272
	ds_read_b128 v[224:227], v183 offset:55296
	ds_read_b128 v[228:231], v183 offset:56320
	s_add_i32 m0, s54, 0x2000
	s_nop 0
	global_load_lds_dwordx4 v138, s[98:99]
	s_add_i32 s54, s94, s2
	s_add_u32 s98, s98, s48
	s_addc_u32 s99, s99, 0
	s_mov_b32 m0, s54
	s_nop 0
	global_load_lds_dwordx4 v142, s[98:99]
	s_add_i32 m0, s54, 0x2000
	s_nop 0
	global_load_lds_dwordx4 v138, s[98:99]
	s_add_u32 s98, s52, 0x80
	s_addc_u32 s99, s53, 0
	s_cmp_eq_u32 s74, vcc_hi
	s_cselect_b32 s99, s39, s99
	s_cselect_b32 s98, s38, s98
	s_add_u32 s98, s98, s92
	s_addc_u32 s99, s99, s93
	s_mov_b32 m0, s35
	s_nop 0
	global_load_lds_dwordx4 v144, s[98:99]
	s_mov_b32 m0, s59
	s_nop 0
	global_load_lds_dwordx4 v140, s[98:99]
	s_waitcnt vmcnt(8) lgkmcnt(0)
	s_setprio 1
	s_barrier
	v_mfma_f32_16x16x32_f16 v[58:61], v[130:133], v[192:195], v[58:61]
	v_mfma_f32_16x16x32_f16 v[50:53], v[152:155], v[192:195], v[50:53]
	v_mfma_f32_16x16x32_f16 v[42:45], v[130:133], v[208:211], v[42:45]
	v_mfma_f32_16x16x32_f16 v[34:37], v[152:155], v[208:211], v[34:37]
	v_mfma_f32_16x16x32_f16 v[26:29], v[130:133], v[216:219], v[26:29]
	v_mfma_f32_16x16x32_f16 v[18:21], v[152:155], v[216:219], v[18:21]
	v_mfma_f32_16x16x32_f16 v[10:13], v[130:133], v[224:227], v[10:13]
	v_mfma_f32_16x16x32_f16 v[6:9], v[152:155], v[224:227], v[6:9]
	v_mfma_f32_16x16x32_f16 v[58:61], v[134:137], v[204:207], v[58:61]
	v_mfma_f32_16x16x32_f16 v[50:53], v[156:159], v[204:207], v[50:53]
	v_mfma_f32_16x16x32_f16 v[42:45], v[134:137], v[212:215], v[42:45]
	v_mfma_f32_16x16x32_f16 v[34:37], v[156:159], v[212:215], v[34:37]
	v_mfma_f32_16x16x32_f16 v[26:29], v[134:137], v[220:223], v[26:29]
	v_mfma_f32_16x16x32_f16 v[18:21], v[156:159], v[220:223], v[18:21]
	v_mfma_f32_16x16x32_f16 v[10:13], v[134:137], v[228:231], v[10:13]
	v_mfma_f32_16x16x32_f16 v[6:9], v[156:159], v[228:231], v[6:9]
	v_mfma_f32_16x16x32_f16 v[62:65], v[160:163], v[192:195], v[62:65]
	v_mfma_f32_16x16x32_f16 v[54:57], v[184:187], v[192:195], v[54:57]
	v_mfma_f32_16x16x32_f16 v[46:49], v[160:163], v[208:211], v[46:49]
	v_mfma_f32_16x16x32_f16 v[38:41], v[184:187], v[208:211], v[38:41]
	v_mfma_f32_16x16x32_f16 v[30:33], v[160:163], v[216:219], v[30:33]
	v_mfma_f32_16x16x32_f16 v[22:25], v[184:187], v[216:219], v[22:25]
	v_mfma_f32_16x16x32_f16 v[14:17], v[160:163], v[224:227], v[14:17]
	v_mfma_f32_16x16x32_f16 v[2:5], v[184:187], v[224:227], v[2:5]
	v_mfma_f32_16x16x32_f16 v[62:65], v[166:169], v[204:207], v[62:65]
	v_mfma_f32_16x16x32_f16 v[54:57], v[188:191], v[204:207], v[54:57]
	v_mfma_f32_16x16x32_f16 v[46:49], v[166:169], v[212:215], v[46:49]
	v_mfma_f32_16x16x32_f16 v[38:41], v[188:191], v[212:215], v[38:41]
	v_mfma_f32_16x16x32_f16 v[30:33], v[166:169], v[220:223], v[30:33]
	v_mfma_f32_16x16x32_f16 v[22:25], v[188:191], v[220:223], v[22:25]
	v_mfma_f32_16x16x32_f16 v[14:17], v[166:169], v[228:231], v[14:17]
	v_mfma_f32_16x16x32_f16 v[2:5], v[188:191], v[228:231], v[2:5]
	s_barrier
	s_setprio 0
	s_add_u32 s52, s52, 0x100
	s_addc_u32 s53, s53, 0
	s_add_u32 s80, s80, 0x100
	s_addc_u32 s81, s81, 0
	s_cmp_ge_u32 s82, s65
	s_mov_b32 s54, s82
	s_cbranch_scc1 .LBB0_311
; #define PG8_STAGE(bufoff, gbase, voff) do { _Pragma("unroll") for (int _i = 0; _i < 2; ++_i) \
;         __builtin_amdgcn_global_load_lds((const unsigned*)((const char*)(gbase) + (voff)[_i]), (PG8_LAS unsigned*)(lds + (bufoff) + ldsw + _i * 8192), 16, 0, 0); } while (0)
; #define PG8_LDA(dst, b, h) do { _Pragma("unroll") for (int m = 0; m < 4; ++m) _Pragma("unroll") for (int k = 0; k < 2; ++k) dst[m][k] = *(const PG8_LAS bf16x8*)(lds + PG8_SA(b, h) + aoff + m * 2048 + k * 1024); } while (0)
; #define PG8_LDB(dst, b, h) do { _Pragma("unroll") for (int n = 0; n < 2; ++n) _Pragma("unroll") for (int k = 0; k < 2; ++k) dst[n][k] = *(const PG8_LAS bf16x8*)(lds + PG8_SB(b, h) + boff + n * 2048 + k * 1024); } while (0)
; #define PG8_WAIT_V(n) asm volatile("s_waitcnt vmcnt(" #n ")" ::: "memory")
; #define PG8_WAIT_L(n) asm volatile("s_waitcnt lgkmcnt(" #n ")" ::: "memory")
; #define PG8_BAR __builtin_amdgcn_s_barrier()
; #define PG8_SCHED __builtin_amdgcn_sched_barrier(0)
; template <class Epi, class Sched, bool ALIGN_EPI = false, bool SP2 = false, bool F16 = false>
; __device__ __forceinline__ void gemm_phase(PG8_LAS unsigned char* lds, const Gemm g, const Sched& S, const Epi& E) {
;     ...
;             PG8_LDB(B0, 0, 0); PG8_LDB(B1, 0, 1); PG8_SCHED; PG8_LDA(At, 0, 0); PG8_STAGE(PG8_SA(1, 1), a1 + hstepA, voffA);
;             PG8_WAIT_V(8); PG8_WAIT_L(0); PG8_BAR; PG8_MMA(0, 0, At, B0); PG8_MMA(0, 1, At, B1); PG8_BAR; PG8_SCHED;
;             PG8_LDA(At, 0, 1); PG8_STAGE(PG8_SB(0, 0), b2, voffB); PG8_STAGE(PG8_SB(0, 1), b2 + hstepB, voffB); PG8_STAGE(PG8_SA(0, 0), a2, voffA);
;             PG8_WAIT_V(8); PG8_WAIT_L(0); PG8_BAR; PG8_MMA(1, 0, At, B0); PG8_MMA(1, 1, At, B1); PG8_BAR; PG8_SCHED;
.LBB0_310:
	s_add_i32 s82, s54, 2
	s_add_u32 s83, s52, 0x80
	s_addc_u32 s55, s53, 0
	s_add_i32 vcc_lo, 0, 0x10000
	s_cmp_eq_u32 s74, s54
	s_cselect_b32 s55, s39, s55
	s_cselect_b32 s54, s38, s83
	s_cselect_b32 s95, s47, s81
	s_cselect_b32 s94, s46, s80
	s_add_i32 s83, 0, 0x14000
	ds_read_b128 v[130:133], v139
	ds_read_b128 v[134:137], v139 offset:1024
	ds_read_b128 v[152:155], v139 offset:2048
	ds_read_b128 v[156:159], v139 offset:3072
	ds_read_b128 v[160:163], v141
	ds_read_b128 v[166:169], v141 offset:1024
	ds_read_b128 v[184:187], v141 offset:2048
	ds_read_b128 v[188:191], v141 offset:3072
	s_add_i32 m0, s22, 0xc000
	ds_read_b128 v[192:195], v183
	ds_read_b128 v[204:207], v183 offset:1024
	ds_read_b128 v[208:211], v183 offset:2048
	ds_read_b128 v[212:215], v183 offset:3072
	ds_read_b128 v[216:219], v183 offset:4096
	ds_read_b128 v[220:223], v183 offset:5120
	ds_read_b128 v[224:227], v183 offset:6144
	ds_read_b128 v[228:231], v183 offset:7168
	global_load_lds_dwordx4 v148, s[52:53]
	s_add_i32 m0, s22, 0xe000
	s_nop 0
	global_load_lds_dwordx4 v150, s[52:53]
	s_waitcnt vmcnt(8) lgkmcnt(0)
	s_setprio 1
	s_barrier
	v_mfma_f32_16x16x32_f16 v[122:125], v[130:133], v[192:195], v[122:125]
	v_mfma_f32_16x16x32_f16 v[114:117], v[152:155], v[192:195], v[114:117]
	v_mfma_f32_16x16x32_f16 v[106:109], v[130:133], v[208:211], v[106:109]
	v_mfma_f32_16x16x32_f16 v[98:101], v[152:155], v[208:211], v[98:101]
	v_mfma_f32_16x16x32_f16 v[90:93], v[130:133], v[216:219], v[90:93]
	v_mfma_f32_16x16x32_f16 v[82:85], v[152:155], v[216:219], v[82:85]
	v_mfma_f32_16x16x32_f16 v[74:77], v[130:133], v[224:227], v[74:77]
	v_mfma_f32_16x16x32_f16 v[66:69], v[152:155], v[224:227], v[66:69]
	v_mfma_f32_16x16x32_f16 v[122:125], v[134:137], v[204:207], v[122:125]
	v_mfma_f32_16x16x32_f16 v[114:117], v[156:159], v[204:207], v[114:117]
	v_mfma_f32_16x16x32_f16 v[106:109], v[134:137], v[212:215], v[106:109]
	v_mfma_f32_16x16x32_f16 v[98:101], v[156:159], v[212:215], v[98:101]
	v_mfma_f32_16x16x32_f16 v[90:93], v[134:137], v[220:223], v[90:93]
	v_mfma_f32_16x16x32_f16 v[82:85], v[156:159], v[220:223], v[82:85]
	v_mfma_f32_16x16x32_f16 v[74:77], v[134:137], v[228:231], v[74:77]
	v_mfma_f32_16x16x32_f16 v[66:69], v[156:159], v[228:231], v[66:69]
	v_mfma_f32_16x16x32_f16 v[126:129], v[160:163], v[192:195], v[126:129]
	v_mfma_f32_16x16x32_f16 v[118:121], v[184:187], v[192:195], v[118:121]
	v_mfma_f32_16x16x32_f16 v[110:113], v[160:163], v[208:211], v[110:113]
	v_mfma_f32_16x16x32_f16 v[102:105], v[184:187], v[208:211], v[102:105]
	v_mfma_f32_16x16x32_f16 v[94:97], v[160:163], v[216:219], v[94:97]
	v_mfma_f32_16x16x32_f16 v[86:89], v[184:187], v[216:219], v[86:89]
	v_mfma_f32_16x16x32_f16 v[78:81], v[160:163], v[224:227], v[78:81]
	v_mfma_f32_16x16x32_f16 v[70:73], v[184:187], v[224:227], v[70:73]
	v_mfma_f32_16x16x32_f16 v[126:129], v[166:169], v[204:207], v[126:129]
	v_mfma_f32_16x16x32_f16 v[118:121], v[188:191], v[204:207], v[118:121]
	v_mfma_f32_16x16x32_f16 v[110:113], v[166:169], v[212:215], v[110:113]
	v_mfma_f32_16x16x32_f16 v[102:105], v[188:191], v[212:215], v[102:105]
	v_mfma_f32_16x16x32_f16 v[94:97], v[166:169], v[220:223], v[94:97]
	v_mfma_f32_16x16x32_f16 v[86:89], v[188:191], v[220:223], v[86:89]
	v_mfma_f32_16x16x32_f16 v[78:81], v[166:169], v[228:231], v[78:81]
	v_mfma_f32_16x16x32_f16 v[70:73], v[188:191], v[228:231], v[70:73]
	s_barrier
	s_setprio 0
	s_add_i32 vcc_lo, vcc_lo, s2
	s_mov_b32 m0, vcc_lo
	s_nop 0
	global_load_lds_dwordx4 v142, s[94:95]
	ds_read_b128 v[192:195], v183 offset:16384
	ds_read_b128 v[204:207], v183 offset:17408
	ds_read_b128 v[208:211], v183 offset:18432
	ds_read_b128 v[212:215], v183 offset:19456
	ds_read_b128 v[216:219], v183 offset:20480
	ds_read_b128 v[220:223], v183 offset:21504
	ds_read_b128 v[224:227], v183 offset:22528
	ds_read_b128 v[228:231], v183 offset:23552
	s_add_i32 m0, vcc_lo, 0x2000
	s_nop 0
	global_load_lds_dwordx4 v138, s[94:95]
	s_add_i32 s83, s83, s2
	s_add_u32 s94, s94, s48
	s_addc_u32 s95, s95, 0
	s_mov_b32 m0, s83
	s_nop 0
	global_load_lds_dwordx4 v142, s[94:95]
	s_add_i32 m0, s83, 0x2000
	s_nop 0
	global_load_lds_dwordx4 v138, s[94:95]
	s_mov_b32 m0, s22
	s_nop 0
	global_load_lds_dwordx4 v144, s[54:55]
	s_mov_b32 m0, s33
	s_nop 0
	global_load_lds_dwordx4 v140, s[54:55]
	s_waitcnt vmcnt(8) lgkmcnt(0)
	s_setprio 1
	s_barrier
	v_mfma_f32_16x16x32_f16 v[58:61], v[130:133], v[192:195], v[58:61]
	v_mfma_f32_16x16x32_f16 v[50:53], v[152:155], v[192:195], v[50:53]
	v_mfma_f32_16x16x32_f16 v[42:45], v[130:133], v[208:211], v[42:45]
	v_mfma_f32_16x16x32_f16 v[34:37], v[152:155], v[208:211], v[34:37]
	v_mfma_f32_16x16x32_f16 v[26:29], v[130:133], v[216:219], v[26:29]
	v_mfma_f32_16x16x32_f16 v[18:21], v[152:155], v[216:219], v[18:21]
	v_mfma_f32_16x16x32_f16 v[10:13], v[130:133], v[224:227], v[10:13]
	v_mfma_f32_16x16x32_f16 v[6:9], v[152:155], v[224:227], v[6:9]
	v_mfma_f32_16x16x32_f16 v[58:61], v[134:137], v[204:207], v[58:61]
	v_mfma_f32_16x16x32_f16 v[50:53], v[156:159], v[204:207], v[50:53]
	v_mfma_f32_16x16x32_f16 v[42:45], v[134:137], v[212:215], v[42:45]
	v_mfma_f32_16x16x32_f16 v[34:37], v[156:159], v[212:215], v[34:37]
	v_mfma_f32_16x16x32_f16 v[26:29], v[134:137], v[220:223], v[26:29]
	v_mfma_f32_16x16x32_f16 v[18:21], v[156:159], v[220:223], v[18:21]
	v_mfma_f32_16x16x32_f16 v[10:13], v[134:137], v[228:231], v[10:13]
	v_mfma_f32_16x16x32_f16 v[6:9], v[156:159], v[228:231], v[6:9]
	v_mfma_f32_16x16x32_f16 v[62:65], v[160:163], v[192:195], v[62:65]
	v_mfma_f32_16x16x32_f16 v[54:57], v[184:187], v[192:195], v[54:57]
	v_mfma_f32_16x16x32_f16 v[46:49], v[160:163], v[208:211], v[46:49]
	v_mfma_f32_16x16x32_f16 v[38:41], v[184:187], v[208:211], v[38:41]
	v_mfma_f32_16x16x32_f16 v[30:33], v[160:163], v[216:219], v[30:33]
	v_mfma_f32_16x16x32_f16 v[22:25], v[184:187], v[216:219], v[22:25]
	v_mfma_f32_16x16x32_f16 v[14:17], v[160:163], v[224:227], v[14:17]
	v_mfma_f32_16x16x32_f16 v[2:5], v[184:187], v[224:227], v[2:5]
	v_mfma_f32_16x16x32_f16 v[62:65], v[166:169], v[204:207], v[62:65]
	v_mfma_f32_16x16x32_f16 v[54:57], v[188:191], v[204:207], v[54:57]
	v_mfma_f32_16x16x32_f16 v[46:49], v[166:169], v[212:215], v[46:49]
	v_mfma_f32_16x16x32_f16 v[38:41], v[188:191], v[212:215], v[38:41]
	v_mfma_f32_16x16x32_f16 v[30:33], v[166:169], v[220:223], v[30:33]
	v_mfma_f32_16x16x32_f16 v[22:25], v[188:191], v[220:223], v[22:25]
	v_mfma_f32_16x16x32_f16 v[14:17], v[166:169], v[228:231], v[14:17]
	v_mfma_f32_16x16x32_f16 v[2:5], v[188:191], v[228:231], v[2:5]
	s_barrier
; #define PG8_STAGE(bufoff, gbase, voff) do { _Pragma("unroll") for (int _i = 0; _i < 2; ++_i) \
;         __builtin_amdgcn_global_load_lds((const unsigned*)((const char*)(gbase) + (voff)[_i]), (PG8_LAS unsigned*)(lds + (bufoff) + ldsw + _i * 8192), 16, 0, 0); } while (0)
; #define PG8_LDA(dst, b, h) do { _Pragma("unroll") for (int m = 0; m < 4; ++m) _Pragma("unroll") for (int k = 0; k < 2; ++k) dst[m][k] = *(const PG8_LAS bf16x8*)(lds + PG8_SA(b, h) + aoff + m * 2048 + k * 1024); } while (0)
; #define PG8_LDB(dst, b, h) do { _Pragma("unroll") for (int n = 0; n < 2; ++n) _Pragma("unroll") for (int k = 0; k < 2; ++k) dst[n][k] = *(const PG8_LAS bf16x8*)(lds + PG8_SB(b, h) + boff + n * 2048 + k * 1024); } while (0)
; #define PG8_WAIT_V(n) asm volatile("s_waitcnt vmcnt(" #n ")" ::: "memory")
; #define PG8_WAIT_L(n) asm volatile("s_waitcnt lgkmcnt(" #n ")" ::: "memory")
; #define PG8_BAR __builtin_amdgcn_s_barrier()
; #define PG8_SCHED __builtin_amdgcn_sched_barrier(0)
; template <class Epi, class Sched, bool ALIGN_EPI = false, bool SP2 = false, bool F16 = false>
; __device__ __forceinline__ void gemm_phase(PG8_LAS unsigned char* lds, const Gemm g, const Sched& S, const Epi& E) {
;     ...
;             PG8_LDB(B0, 1, 0); PG8_LDB(B1, 1, 1); PG8_SCHED; PG8_LDA(At, 1, 0); PG8_STAGE(PG8_SA(0, 1), a2 + hstepA, voffA);
;             PG8_WAIT_V(8); PG8_WAIT_L(0); PG8_BAR; PG8_MMA(0, 0, At, B0); PG8_MMA(0, 1, At, B1); PG8_BAR; PG8_SCHED;
;             PG8_LDA(At, 1, 1); PG8_STAGE(PG8_SB(1, 0), b3, voffB); PG8_STAGE(PG8_SB(1, 1), b3 + hstepB, voffB); PG8_STAGE(PG8_SA(1, 0), a3, voffA);
;             PG8_WAIT_V(8); PG8_WAIT_L(0); PG8_BAR; PG8_MMA(1, 0, At, B0); PG8_MMA(1, 1, At, B1); PG8_BAR; PG8_SCHED;
	s_setprio 0
	s_add_i32 s83, 0, 0x18000
	s_add_i32 s94, 0, 0x1c000
	ds_read_b128 v[130:133], v143
	ds_read_b128 v[134:137], v143 offset:1024
	ds_read_b128 v[152:155], v143 offset:2048
	ds_read_b128 v[156:159], v143 offset:3072
	ds_read_b128 v[160:163], v145
	ds_read_b128 v[166:169], v145 offset:1024
	ds_read_b128 v[184:187], v145 offset:2048
	ds_read_b128 v[188:191], v145 offset:3072
	s_add_u32 s54, s54, s8
	s_addc_u32 s55, s55, 0
	s_mov_b32 m0, s12
	ds_read_b128 v[192:195], v183 offset:32768
	ds_read_b128 v[204:207], v183 offset:33792
	ds_read_b128 v[208:211], v183 offset:34816
	ds_read_b128 v[212:215], v183 offset:35840
	ds_read_b128 v[216:219], v183 offset:36864
	ds_read_b128 v[220:223], v183 offset:37888
	ds_read_b128 v[224:227], v183 offset:38912
	ds_read_b128 v[228:231], v183 offset:39936
	global_load_lds_dwordx4 v144, s[54:55]
	s_mov_b32 m0, s13
	s_nop 0
	global_load_lds_dwordx4 v140, s[54:55]
	s_waitcnt vmcnt(8) lgkmcnt(0)
	s_setprio 1
	s_barrier
	v_mfma_f32_16x16x32_f16 v[122:125], v[130:133], v[192:195], v[122:125]
	v_mfma_f32_16x16x32_f16 v[114:117], v[152:155], v[192:195], v[114:117]
	v_mfma_f32_16x16x32_f16 v[106:109], v[130:133], v[208:211], v[106:109]
	v_mfma_f32_16x16x32_f16 v[98:101], v[152:155], v[208:211], v[98:101]
	v_mfma_f32_16x16x32_f16 v[90:93], v[130:133], v[216:219], v[90:93]
	v_mfma_f32_16x16x32_f16 v[82:85], v[152:155], v[216:219], v[82:85]
	v_mfma_f32_16x16x32_f16 v[74:77], v[130:133], v[224:227], v[74:77]
	v_mfma_f32_16x16x32_f16 v[66:69], v[152:155], v[224:227], v[66:69]
	v_mfma_f32_16x16x32_f16 v[122:125], v[134:137], v[204:207], v[122:125]
	v_mfma_f32_16x16x32_f16 v[114:117], v[156:159], v[204:207], v[114:117]
	v_mfma_f32_16x16x32_f16 v[106:109], v[134:137], v[212:215], v[106:109]
	v_mfma_f32_16x16x32_f16 v[98:101], v[156:159], v[212:215], v[98:101]
	v_mfma_f32_16x16x32_f16 v[90:93], v[134:137], v[220:223], v[90:93]
	v_mfma_f32_16x16x32_f16 v[82:85], v[156:159], v[220:223], v[82:85]
	v_mfma_f32_16x16x32_f16 v[74:77], v[134:137], v[228:231], v[74:77]
	v_mfma_f32_16x16x32_f16 v[66:69], v[156:159], v[228:231], v[66:69]
	v_mfma_f32_16x16x32_f16 v[126:129], v[160:163], v[192:195], v[126:129]
	v_mfma_f32_16x16x32_f16 v[118:121], v[184:187], v[192:195], v[118:121]
	v_mfma_f32_16x16x32_f16 v[110:113], v[160:163], v[208:211], v[110:113]
	v_mfma_f32_16x16x32_f16 v[102:105], v[184:187], v[208:211], v[102:105]
	v_mfma_f32_16x16x32_f16 v[94:97], v[160:163], v[216:219], v[94:97]
	v_mfma_f32_16x16x32_f16 v[86:89], v[184:187], v[216:219], v[86:89]
	v_mfma_f32_16x16x32_f16 v[78:81], v[160:163], v[224:227], v[78:81]
	v_mfma_f32_16x16x32_f16 v[70:73], v[184:187], v[224:227], v[70:73]
	v_mfma_f32_16x16x32_f16 v[126:129], v[166:169], v[204:207], v[126:129]
	v_mfma_f32_16x16x32_f16 v[118:121], v[188:191], v[204:207], v[118:121]
	v_mfma_f32_16x16x32_f16 v[110:113], v[166:169], v[212:215], v[110:113]
	v_mfma_f32_16x16x32_f16 v[102:105], v[188:191], v[212:215], v[102:105]
	v_mfma_f32_16x16x32_f16 v[94:97], v[166:169], v[220:223], v[94:97]
	v_mfma_f32_16x16x32_f16 v[86:89], v[188:191], v[220:223], v[86:89]
	v_mfma_f32_16x16x32_f16 v[78:81], v[166:169], v[228:231], v[78:81]
	v_mfma_f32_16x16x32_f16 v[70:73], v[188:191], v[228:231], v[70:73]
	s_barrier
	s_setprio 0
	s_add_i32 s54, s83, s2
	s_add_i32 vcc_hi, s82, -2
	s_cmp_eq_u32 s74, vcc_hi
	s_cselect_b32 s99, s47, s81
	s_cselect_b32 s98, s46, s80
	s_add_u32 s98, s98, s92
	s_addc_u32 s99, s99, s93
	s_mov_b32 m0, s54
	s_nop 0
	global_load_lds_dwordx4 v142, s[98:99]
	ds_read_b128 v[192:195], v183 offset:49152
	ds_read_b128 v[204:207], v183 offset:50176
	ds_read_b128 v[208:211], v183 offset:51200
	ds_read_b128 v[212:215], v183 offset:52224
	ds_read_b128 v[216:219], v183 offset:53248
	ds_read_b128 v[220:223], v183 offset:54272
	ds_read_b128 v[224:227], v183 offset:55296
	ds_read_b128 v[228:231], v183 offset:56320
	s_add_i32 m0, s54, 0x2000
	s_nop 0
	global_load_lds_dwordx4 v138, s[98:99]
	s_add_i32 s54, s94, s2
	s_add_u32 s98, s98, s48
	s_addc_u32 s99, s99, 0
	s_mov_b32 m0, s54
	s_nop 0
	global_load_lds_dwordx4 v142, s[98:99]
	s_add_i32 m0, s54, 0x2000
	s_nop 0
	global_load_lds_dwordx4 v138, s[98:99]
	s_add_u32 s98, s52, 0x80
	s_addc_u32 s99, s53, 0
	s_cmp_eq_u32 s74, vcc_hi
	s_cselect_b32 s99, s39, s99
	s_cselect_b32 s98, s38, s98
	s_add_u32 s98, s98, s92
	s_addc_u32 s99, s99, s93
	s_mov_b32 m0, s35
	s_nop 0
	global_load_lds_dwordx4 v144, s[98:99]
	s_mov_b32 m0, s59
	s_nop 0
	global_load_lds_dwordx4 v140, s[98:99]
	s_waitcnt vmcnt(8) lgkmcnt(0)
	s_setprio 1
	s_barrier
	v_mfma_f32_16x16x32_f16 v[58:61], v[130:133], v[192:195], v[58:61]
	v_mfma_f32_16x16x32_f16 v[50:53], v[152:155], v[192:195], v[50:53]
	v_mfma_f32_16x16x32_f16 v[42:45], v[130:133], v[208:211], v[42:45]
	v_mfma_f32_16x16x32_f16 v[34:37], v[152:155], v[208:211], v[34:37]
	v_mfma_f32_16x16x32_f16 v[26:29], v[130:133], v[216:219], v[26:29]
	v_mfma_f32_16x16x32_f16 v[18:21], v[152:155], v[216:219], v[18:21]
	v_mfma_f32_16x16x32_f16 v[10:13], v[130:133], v[224:227], v[10:13]
	v_mfma_f32_16x16x32_f16 v[6:9], v[152:155], v[224:227], v[6:9]
	v_mfma_f32_16x16x32_f16 v[58:61], v[134:137], v[204:207], v[58:61]
	v_mfma_f32_16x16x32_f16 v[50:53], v[156:159], v[204:207], v[50:53]
	v_mfma_f32_16x16x32_f16 v[42:45], v[134:137], v[212:215], v[42:45]
	v_mfma_f32_16x16x32_f16 v[34:37], v[156:159], v[212:215], v[34:37]
	v_mfma_f32_16x16x32_f16 v[26:29], v[134:137], v[220:223], v[26:29]
	v_mfma_f32_16x16x32_f16 v[18:21], v[156:159], v[220:223], v[18:21]
	v_mfma_f32_16x16x32_f16 v[10:13], v[134:137], v[228:231], v[10:13]
	v_mfma_f32_16x16x32_f16 v[6:9], v[156:159], v[228:231], v[6:9]
	v_mfma_f32_16x16x32_f16 v[62:65], v[160:163], v[192:195], v[62:65]
	v_mfma_f32_16x16x32_f16 v[54:57], v[184:187], v[192:195], v[54:57]
	v_mfma_f32_16x16x32_f16 v[46:49], v[160:163], v[208:211], v[46:49]
	v_mfma_f32_16x16x32_f16 v[38:41], v[184:187], v[208:211], v[38:41]
	v_mfma_f32_16x16x32_f16 v[30:33], v[160:163], v[216:219], v[30:33]
	v_mfma_f32_16x16x32_f16 v[22:25], v[184:187], v[216:219], v[22:25]
	v_mfma_f32_16x16x32_f16 v[14:17], v[160:163], v[224:227], v[14:17]
	v_mfma_f32_16x16x32_f16 v[2:5], v[184:187], v[224:227], v[2:5]
	v_mfma_f32_16x16x32_f16 v[62:65], v[166:169], v[204:207], v[62:65]
	v_mfma_f32_16x16x32_f16 v[54:57], v[188:191], v[204:207], v[54:57]
	v_mfma_f32_16x16x32_f16 v[46:49], v[166:169], v[212:215], v[46:49]
	v_mfma_f32_16x16x32_f16 v[38:41], v[188:191], v[212:215], v[38:41]
	v_mfma_f32_16x16x32_f16 v[30:33], v[166:169], v[220:223], v[30:33]
	v_mfma_f32_16x16x32_f16 v[22:25], v[188:191], v[220:223], v[22:25]
	v_mfma_f32_16x16x32_f16 v[14:17], v[166:169], v[228:231], v[14:17]
	v_mfma_f32_16x16x32_f16 v[2:5], v[188:191], v[228:231], v[2:5]
	s_barrier
	s_setprio 0
	s_add_u32 s52, s52, 0x100
	s_addc_u32 s53, s53, 0
	s_add_u32 s80, s80, 0x100
	s_addc_u32 s81, s81, 0
	s_cmp_ge_u32 s82, s65
	s_mov_b32 s54, s82
	s_cbranch_scc0 .LBB0_310

; #define PG8_STAGE(bufoff, gbase, voff) do { _Pragma("unroll") for (int _i = 0; _i < 2; ++_i) \
;         __builtin_amdgcn_global_load_lds((const unsigned*)((const char*)(gbase) + (voff)[_i]), (PG8_LAS unsigned*)(lds + (bufoff) + ldsw + _i * 8192), 16, 0, 0); } while (0)
; #define PG8_LDA(dst, b, h) do { _Pragma("unroll") for (int m = 0; m < 4; ++m) _Pragma("unroll") for (int k = 0; k < 2; ++k) dst[m][k] = *(const PG8_LAS bf16x8*)(lds + PG8_SA(b, h) + aoff + m * 2048 + k * 1024); } while (0)
; #define PG8_LDB(dst, b, h) do { _Pragma("unroll") for (int n = 0; n < 2; ++n) _Pragma("unroll") for (int k = 0; k < 2; ++k) dst[n][k] = *(const PG8_LAS bf16x8*)(lds + PG8_SB(b, h) + boff + n * 2048 + k * 1024); } while (0)
; #define PG8_WAIT_V(n) asm volatile("s_waitcnt vmcnt(" #n ")" ::: "memory")
; #define PG8_WAIT_L(n) asm volatile("s_waitcnt lgkmcnt(" #n ")" ::: "memory")
; #define PG8_BAR __builtin_amdgcn_s_barrier()
; #define PG8_SCHED __builtin_amdgcn_sched_barrier(0)
; template <class Epi, class Sched, bool ALIGN_EPI = false, bool SP2 = false, bool F16 = false>
; __device__ __forceinline__ void gemm_phase(PG8_LAS unsigned char* lds, const Gemm g, const Sched& S, const Epi& E) {
;     ...
;         for (int t = 0; t < nt; t += 2) {
;             const bool last = (t == nt - 2);
;             const char* a1 = cA + (size_t)(t + 1) * kstep;
;             const char* a2 = last ? nA : cA + (size_t)(t + 2) * kstep; const char* b2 = last ? nB : cB + (size_t)(t + 2) * kstep;
;             const char* a3 = a2 + kstep; const char* b3 = b2 + kstep;
;             if (last && has_next) S.a_ready(nxt);
;             if constexpr (SP2) {
;             PG8_LDB(B0, 0, 0); PG8_LDB(B1, 0, 1); PG8_SCHED; PG8_LDA(At, 0, 0); PG8_STAGE(PG8_SA(1, 1), a1 + hstepA, voffA);
;             PG8_WAIT_V(8); PG8_WAIT_L(0); PG8_BAR; PG8_MMA(0, 0, At, B0); PG8_MMA(0, 1, At, B1); PG8_BAR; PG8_SCHED;
;             PG8_LDA(At, 0, 1); PG8_STAGE(PG8_SB(0, 0), b2, voffB); PG8_STAGE(PG8_SB(0, 1), b2 + hstepB, voffB); PG8_STAGE(PG8_SA(0, 0), a2, voffA);
;             PG8_WAIT_V(8); PG8_WAIT_L(0); PG8_BAR; PG8_MMA(1, 0, At, B0); PG8_MMA(1, 1, At, B1); PG8_BAR; PG8_SCHED;
.Lpk_rs:
	s_add_i32 s81, s54, 2
	s_add_u32 s82, s52, 0x80
	s_addc_u32 s55, s53, 0
	s_add_i32 s94, 0, 0x10000
	s_cmp_eq_u32 s74, s54
	s_cselect_b32 s55, s41, s55
	s_cselect_b32 s54, s40, s82
	s_cselect_b32 s83, s47, s80
	s_cselect_b32 s82, s46, s79
	s_add_i32 s95, 0, 0x14000
	ds_read_b128 v[130:133], v139
	ds_read_b128 v[134:137], v139 offset:1024
	ds_read_b128 v[148:151], v139 offset:2048
	ds_read_b128 v[152:155], v139 offset:3072
	ds_read_b128 v[162:165], v141
	ds_read_b128 v[166:169], v141 offset:1024
	ds_read_b128 v[170:173], v141 offset:2048
	ds_read_b128 v[182:185], v141 offset:3072
	s_add_i32 m0, s3, 0xc000
	ds_read_b128 v[186:189], v160
	ds_read_b128 v[190:193], v160 offset:1024
	ds_read_b128 v[194:197], v160 offset:2048
	ds_read_b128 v[204:207], v160 offset:3072
	ds_read_b128 v[208:211], v160 offset:4096
	ds_read_b128 v[212:215], v160 offset:5120
	ds_read_b128 v[216:219], v160 offset:6144
	ds_read_b128 v[220:223], v160 offset:7168
	global_load_lds_dwordx4 v144, s[52:53]
	s_add_i32 m0, s3, 0xe000
	s_nop 0
	global_load_lds_dwordx4 v146, s[52:53]
	s_waitcnt vmcnt(8) lgkmcnt(0)
	s_setprio 1
	s_barrier
	v_mfma_f32_16x16x32_bf16 v[122:125], v[130:133], v[186:189], 0
	v_mfma_f32_16x16x32_bf16 v[126:129], v[148:151], v[186:189], 0
	v_mfma_f32_16x16x32_bf16 v[110:113], v[130:133], v[194:197], 0
	v_mfma_f32_16x16x32_bf16 v[106:109], v[148:151], v[194:197], 0
	v_mfma_f32_16x16x32_bf16 v[94:97], v[130:133], v[208:211], 0
	v_mfma_f32_16x16x32_bf16 v[90:93], v[148:151], v[208:211], 0
	v_mfma_f32_16x16x32_bf16 v[78:81], v[130:133], v[216:219], 0
	v_mfma_f32_16x16x32_bf16 v[74:77], v[148:151], v[216:219], 0
	v_mfma_f32_16x16x32_bf16 v[122:125], v[134:137], v[190:193], v[122:125]
	v_mfma_f32_16x16x32_bf16 v[126:129], v[152:155], v[190:193], v[126:129]
	v_mfma_f32_16x16x32_bf16 v[110:113], v[134:137], v[204:207], v[110:113]
	v_mfma_f32_16x16x32_bf16 v[106:109], v[152:155], v[204:207], v[106:109]
	v_mfma_f32_16x16x32_bf16 v[94:97], v[134:137], v[212:215], v[94:97]
	v_mfma_f32_16x16x32_bf16 v[90:93], v[152:155], v[212:215], v[90:93]
	v_mfma_f32_16x16x32_bf16 v[78:81], v[134:137], v[220:223], v[78:81]
	v_mfma_f32_16x16x32_bf16 v[74:77], v[152:155], v[220:223], v[74:77]
	v_mfma_f32_16x16x32_bf16 v[118:121], v[162:165], v[186:189], 0
	v_mfma_f32_16x16x32_bf16 v[114:117], v[170:173], v[186:189], 0
	v_mfma_f32_16x16x32_bf16 v[102:105], v[162:165], v[194:197], 0
	v_mfma_f32_16x16x32_bf16 v[98:101], v[170:173], v[194:197], 0
	v_mfma_f32_16x16x32_bf16 v[86:89], v[162:165], v[208:211], 0
	v_mfma_f32_16x16x32_bf16 v[82:85], v[170:173], v[208:211], 0
	v_mfma_f32_16x16x32_bf16 v[70:73], v[162:165], v[216:219], 0
	v_mfma_f32_16x16x32_bf16 v[66:69], v[170:173], v[216:219], 0
	v_mfma_f32_16x16x32_bf16 v[118:121], v[166:169], v[190:193], v[118:121]
	v_mfma_f32_16x16x32_bf16 v[114:117], v[182:185], v[190:193], v[114:117]
	v_mfma_f32_16x16x32_bf16 v[102:105], v[166:169], v[204:207], v[102:105]
	v_mfma_f32_16x16x32_bf16 v[98:101], v[182:185], v[204:207], v[98:101]
	v_mfma_f32_16x16x32_bf16 v[86:89], v[166:169], v[212:215], v[86:89]
	v_mfma_f32_16x16x32_bf16 v[82:85], v[182:185], v[212:215], v[82:85]
	v_mfma_f32_16x16x32_bf16 v[70:73], v[166:169], v[220:223], v[70:73]
	v_mfma_f32_16x16x32_bf16 v[66:69], v[182:185], v[220:223], v[66:69]
	s_barrier
	s_setprio 0
	s_add_i32 s94, s94, s2
	s_mov_b32 m0, s94
	s_nop 0
	global_load_lds_dwordx4 v174, s[82:83]
	ds_read_b128 v[186:189], v160 offset:16384
	ds_read_b128 v[190:193], v160 offset:17408
	ds_read_b128 v[194:197], v160 offset:18432
	ds_read_b128 v[204:207], v160 offset:19456
	ds_read_b128 v[208:211], v160 offset:20480
	ds_read_b128 v[212:215], v160 offset:21504
	ds_read_b128 v[216:219], v160 offset:22528
	ds_read_b128 v[220:223], v160 offset:23552
	s_add_i32 m0, s94, 0x2000
	s_nop 0
	global_load_lds_dwordx4 v142, s[82:83]
	s_add_i32 s94, s95, s2
	s_add_u32 s82, s82, s48
	s_addc_u32 s83, s83, 0
	s_mov_b32 m0, s94
	s_nop 0
	global_load_lds_dwordx4 v174, s[82:83]
	s_add_i32 m0, s94, 0x2000
	s_nop 0
	global_load_lds_dwordx4 v142, s[82:83]
	s_mov_b32 m0, s3
	s_nop 0
	global_load_lds_dwordx4 v138, s[54:55]
	s_mov_b32 m0, s12
	s_nop 0
	global_load_lds_dwordx4 v140, s[54:55]
	s_waitcnt vmcnt(8) lgkmcnt(0)
	s_setprio 1
	s_barrier
	v_mfma_f32_16x16x32_bf16 v[62:65], v[130:133], v[186:189], 0
	v_mfma_f32_16x16x32_bf16 v[58:61], v[148:151], v[186:189], 0
	v_mfma_f32_16x16x32_bf16 v[46:49], v[130:133], v[194:197], 0
	v_mfma_f32_16x16x32_bf16 v[42:45], v[148:151], v[194:197], 0
	v_mfma_f32_16x16x32_bf16 v[30:33], v[130:133], v[208:211], 0
	v_mfma_f32_16x16x32_bf16 v[26:29], v[148:151], v[208:211], 0
	v_mfma_f32_16x16x32_bf16 v[14:17], v[130:133], v[216:219], 0
	v_mfma_f32_16x16x32_bf16 v[10:13], v[148:151], v[216:219], 0
	v_mfma_f32_16x16x32_bf16 v[62:65], v[134:137], v[190:193], v[62:65]
	v_mfma_f32_16x16x32_bf16 v[58:61], v[152:155], v[190:193], v[58:61]
	v_mfma_f32_16x16x32_bf16 v[46:49], v[134:137], v[204:207], v[46:49]
	v_mfma_f32_16x16x32_bf16 v[42:45], v[152:155], v[204:207], v[42:45]
	v_mfma_f32_16x16x32_bf16 v[30:33], v[134:137], v[212:215], v[30:33]
	v_mfma_f32_16x16x32_bf16 v[26:29], v[152:155], v[212:215], v[26:29]
	v_mfma_f32_16x16x32_bf16 v[14:17], v[134:137], v[220:223], v[14:17]
	v_mfma_f32_16x16x32_bf16 v[10:13], v[152:155], v[220:223], v[10:13]
	v_mfma_f32_16x16x32_bf16 v[54:57], v[162:165], v[186:189], 0
	v_mfma_f32_16x16x32_bf16 v[50:53], v[170:173], v[186:189], 0
	v_mfma_f32_16x16x32_bf16 v[38:41], v[162:165], v[194:197], 0
	v_mfma_f32_16x16x32_bf16 v[34:37], v[170:173], v[194:197], 0
	v_mfma_f32_16x16x32_bf16 v[22:25], v[162:165], v[208:211], 0
	v_mfma_f32_16x16x32_bf16 v[18:21], v[170:173], v[208:211], 0
	v_mfma_f32_16x16x32_bf16 v[6:9], v[162:165], v[216:219], 0
	v_mfma_f32_16x16x32_bf16 v[2:5], v[170:173], v[216:219], 0
	v_mfma_f32_16x16x32_bf16 v[54:57], v[166:169], v[190:193], v[54:57]
	v_mfma_f32_16x16x32_bf16 v[50:53], v[182:185], v[190:193], v[50:53]
	v_mfma_f32_16x16x32_bf16 v[38:41], v[166:169], v[204:207], v[38:41]
	v_mfma_f32_16x16x32_bf16 v[34:37], v[182:185], v[204:207], v[34:37]
	v_mfma_f32_16x16x32_bf16 v[22:25], v[166:169], v[212:215], v[22:25]
	v_mfma_f32_16x16x32_bf16 v[18:21], v[182:185], v[212:215], v[18:21]
	v_mfma_f32_16x16x32_bf16 v[6:9], v[166:169], v[220:223], v[6:9]
	v_mfma_f32_16x16x32_bf16 v[2:5], v[182:185], v[220:223], v[2:5]
	s_barrier
; #define PG8_STAGE(bufoff, gbase, voff) do { _Pragma("unroll") for (int _i = 0; _i < 2; ++_i) \
;         __builtin_amdgcn_global_load_lds((const unsigned*)((const char*)(gbase) + (voff)[_i]), (PG8_LAS unsigned*)(lds + (bufoff) + ldsw + _i * 8192), 16, 0, 0); } while (0)
; #define PG8_LDA(dst, b, h) do { _Pragma("unroll") for (int m = 0; m < 4; ++m) _Pragma("unroll") for (int k = 0; k < 2; ++k) dst[m][k] = *(const PG8_LAS bf16x8*)(lds + PG8_SA(b, h) + aoff + m * 2048 + k * 1024); } while (0)
; #define PG8_LDB(dst, b, h) do { _Pragma("unroll") for (int n = 0; n < 2; ++n) _Pragma("unroll") for (int k = 0; k < 2; ++k) dst[n][k] = *(const PG8_LAS bf16x8*)(lds + PG8_SB(b, h) + boff + n * 2048 + k * 1024); } while (0)
; #define PG8_WAIT_V(n) asm volatile("s_waitcnt vmcnt(" #n ")" ::: "memory")
; #define PG8_WAIT_L(n) asm volatile("s_waitcnt lgkmcnt(" #n ")" ::: "memory")
; #define PG8_BAR __builtin_amdgcn_s_barrier()
; #define PG8_SCHED __builtin_amdgcn_sched_barrier(0)
; template <class Epi, class Sched, bool ALIGN_EPI = false, bool SP2 = false, bool F16 = false>
; __device__ __forceinline__ void gemm_phase(PG8_LAS unsigned char* lds, const Gemm g, const Sched& S, const Epi& E) {
;     ...
;             PG8_LDB(B0, 1, 0); PG8_LDB(B1, 1, 1); PG8_SCHED; PG8_LDA(At, 1, 0); PG8_STAGE(PG8_SA(0, 1), a2 + hstepA, voffA);
;             PG8_WAIT_V(8); PG8_WAIT_L(0); PG8_BAR; PG8_MMA(0, 0, At, B0); PG8_MMA(0, 1, At, B1); PG8_BAR; PG8_SCHED;
;             PG8_LDA(At, 1, 1); PG8_STAGE(PG8_SB(1, 0), b3, voffB); PG8_STAGE(PG8_SB(1, 1), b3 + hstepB, voffB); PG8_STAGE(PG8_SA(1, 0), a3, voffA);
;             PG8_WAIT_V(8); PG8_WAIT_L(0); PG8_BAR; PG8_MMA(1, 0, At, B0); PG8_MMA(1, 1, At, B1); PG8_BAR; PG8_SCHED;
	s_setprio 0
	s_add_i32 s82, 0, 0x18000
	s_add_i32 s83, 0, 0x1c000
	ds_read_b128 v[130:133], v143
	ds_read_b128 v[134:137], v143 offset:1024
	ds_read_b128 v[148:151], v143 offset:2048
	ds_read_b128 v[152:155], v143 offset:3072
	ds_read_b128 v[162:165], v157
	ds_read_b128 v[166:169], v157 offset:1024
	ds_read_b128 v[170:173], v157 offset:2048
	ds_read_b128 v[182:185], v157 offset:3072
	s_add_u32 s54, s54, s8
	s_addc_u32 s55, s55, 0
	s_mov_b32 m0, s13
	ds_read_b128 v[186:189], v160 offset:32768
	ds_read_b128 v[190:193], v160 offset:33792
	ds_read_b128 v[194:197], v160 offset:34816
	ds_read_b128 v[204:207], v160 offset:35840
	ds_read_b128 v[208:211], v160 offset:36864
	ds_read_b128 v[212:215], v160 offset:37888
	ds_read_b128 v[216:219], v160 offset:38912
	ds_read_b128 v[220:223], v160 offset:39936
	global_load_lds_dwordx4 v138, s[54:55]
	s_mov_b32 m0, s22
	s_nop 0
	global_load_lds_dwordx4 v140, s[54:55]
	s_waitcnt vmcnt(8) lgkmcnt(0)
	s_setprio 1
	s_barrier
	v_mfma_f32_16x16x32_bf16 v[122:125], v[130:133], v[186:189], v[122:125]
	v_mfma_f32_16x16x32_bf16 v[126:129], v[148:151], v[186:189], v[126:129]
	v_mfma_f32_16x16x32_bf16 v[110:113], v[130:133], v[194:197], v[110:113]
	v_mfma_f32_16x16x32_bf16 v[106:109], v[148:151], v[194:197], v[106:109]
	v_mfma_f32_16x16x32_bf16 v[94:97], v[130:133], v[208:211], v[94:97]
	v_mfma_f32_16x16x32_bf16 v[90:93], v[148:151], v[208:211], v[90:93]
	v_mfma_f32_16x16x32_bf16 v[78:81], v[130:133], v[216:219], v[78:81]
	v_mfma_f32_16x16x32_bf16 v[74:77], v[148:151], v[216:219], v[74:77]
	v_mfma_f32_16x16x32_bf16 v[122:125], v[134:137], v[190:193], v[122:125]
	v_mfma_f32_16x16x32_bf16 v[126:129], v[152:155], v[190:193], v[126:129]
	v_mfma_f32_16x16x32_bf16 v[110:113], v[134:137], v[204:207], v[110:113]
	v_mfma_f32_16x16x32_bf16 v[106:109], v[152:155], v[204:207], v[106:109]
	v_mfma_f32_16x16x32_bf16 v[94:97], v[134:137], v[212:215], v[94:97]
	v_mfma_f32_16x16x32_bf16 v[90:93], v[152:155], v[212:215], v[90:93]
	v_mfma_f32_16x16x32_bf16 v[78:81], v[134:137], v[220:223], v[78:81]
	v_mfma_f32_16x16x32_bf16 v[74:77], v[152:155], v[220:223], v[74:77]
	v_mfma_f32_16x16x32_bf16 v[118:121], v[162:165], v[186:189], v[118:121]
	v_mfma_f32_16x16x32_bf16 v[114:117], v[170:173], v[186:189], v[114:117]
	v_mfma_f32_16x16x32_bf16 v[102:105], v[162:165], v[194:197], v[102:105]
	v_mfma_f32_16x16x32_bf16 v[98:101], v[170:173], v[194:197], v[98:101]
	v_mfma_f32_16x16x32_bf16 v[86:89], v[162:165], v[208:211], v[86:89]
	v_mfma_f32_16x16x32_bf16 v[82:85], v[170:173], v[208:211], v[82:85]
	v_mfma_f32_16x16x32_bf16 v[70:73], v[162:165], v[216:219], v[70:73]
	v_mfma_f32_16x16x32_bf16 v[66:69], v[170:173], v[216:219], v[66:69]
	v_mfma_f32_16x16x32_bf16 v[118:121], v[166:169], v[190:193], v[118:121]
	v_mfma_f32_16x16x32_bf16 v[114:117], v[182:185], v[190:193], v[114:117]
	v_mfma_f32_16x16x32_bf16 v[102:105], v[166:169], v[204:207], v[102:105]
	v_mfma_f32_16x16x32_bf16 v[98:101], v[182:185], v[204:207], v[98:101]
	v_mfma_f32_16x16x32_bf16 v[86:89], v[166:169], v[212:215], v[86:89]
	v_mfma_f32_16x16x32_bf16 v[82:85], v[182:185], v[212:215], v[82:85]
	v_mfma_f32_16x16x32_bf16 v[70:73], v[166:169], v[220:223], v[70:73]
	v_mfma_f32_16x16x32_bf16 v[66:69], v[182:185], v[220:223], v[66:69]
	s_barrier
	s_setprio 0
	s_add_i32 s54, s82, s2
	s_add_i32 vcc_hi, s81, -2
	s_cmp_eq_u32 s74, vcc_hi
	s_cselect_b32 s99, s47, s80
	s_cselect_b32 s98, s46, s79
	s_add_u32 s98, s98, s92
	s_addc_u32 s99, s99, s93
	s_mov_b32 m0, s54
	s_nop 0
	global_load_lds_dwordx4 v174, s[98:99]
	ds_read_b128 v[186:189], v160 offset:49152
	ds_read_b128 v[190:193], v160 offset:50176
	ds_read_b128 v[194:197], v160 offset:51200
	ds_read_b128 v[204:207], v160 offset:52224
	ds_read_b128 v[208:211], v160 offset:53248
	ds_read_b128 v[212:215], v160 offset:54272
	ds_read_b128 v[216:219], v160 offset:55296
	ds_read_b128 v[220:223], v160 offset:56320
	s_add_i32 m0, s54, 0x2000
	s_nop 0
	global_load_lds_dwordx4 v142, s[98:99]
	s_add_i32 s54, s83, s2
	s_add_u32 s98, s98, s48
	s_addc_u32 s99, s99, 0
	s_mov_b32 m0, s54
	s_nop 0
	global_load_lds_dwordx4 v174, s[98:99]
	s_add_i32 m0, s54, 0x2000
	s_nop 0
	global_load_lds_dwordx4 v142, s[98:99]
	s_add_u32 s98, s52, 0x80
	s_addc_u32 s99, s53, 0
	s_cmp_eq_u32 s74, vcc_hi
	s_cselect_b32 s99, s41, s99
	s_cselect_b32 s98, s40, s98
	s_add_u32 s98, s98, s92
	s_addc_u32 s99, s99, s93
	s_mov_b32 m0, s33
	s_nop 0
	global_load_lds_dwordx4 v138, s[98:99]
	s_mov_b32 m0, s35
	s_nop 0
	global_load_lds_dwordx4 v140, s[98:99]
	s_waitcnt vmcnt(8) lgkmcnt(0)
	s_setprio 1
	s_barrier
	v_mfma_f32_16x16x32_bf16 v[62:65], v[130:133], v[186:189], v[62:65]
	v_mfma_f32_16x16x32_bf16 v[58:61], v[148:151], v[186:189], v[58:61]
	v_mfma_f32_16x16x32_bf16 v[46:49], v[130:133], v[194:197], v[46:49]
	v_mfma_f32_16x16x32_bf16 v[42:45], v[148:151], v[194:197], v[42:45]
	v_mfma_f32_16x16x32_bf16 v[30:33], v[130:133], v[208:211], v[30:33]
	v_mfma_f32_16x16x32_bf16 v[26:29], v[148:151], v[208:211], v[26:29]
	v_mfma_f32_16x16x32_bf16 v[14:17], v[130:133], v[216:219], v[14:17]
	v_mfma_f32_16x16x32_bf16 v[10:13], v[148:151], v[216:219], v[10:13]
	v_mfma_f32_16x16x32_bf16 v[62:65], v[134:137], v[190:193], v[62:65]
	v_mfma_f32_16x16x32_bf16 v[58:61], v[152:155], v[190:193], v[58:61]
	v_mfma_f32_16x16x32_bf16 v[46:49], v[134:137], v[204:207], v[46:49]
	v_mfma_f32_16x16x32_bf16 v[42:45], v[152:155], v[204:207], v[42:45]
	v_mfma_f32_16x16x32_bf16 v[30:33], v[134:137], v[212:215], v[30:33]
	v_mfma_f32_16x16x32_bf16 v[26:29], v[152:155], v[212:215], v[26:29]
	v_mfma_f32_16x16x32_bf16 v[14:17], v[134:137], v[220:223], v[14:17]
	v_mfma_f32_16x16x32_bf16 v[10:13], v[152:155], v[220:223], v[10:13]
	v_mfma_f32_16x16x32_bf16 v[54:57], v[162:165], v[186:189], v[54:57]
	v_mfma_f32_16x16x32_bf16 v[50:53], v[170:173], v[186:189], v[50:53]
	v_mfma_f32_16x16x32_bf16 v[38:41], v[162:165], v[194:197], v[38:41]
	v_mfma_f32_16x16x32_bf16 v[34:37], v[170:173], v[194:197], v[34:37]
	v_mfma_f32_16x16x32_bf16 v[22:25], v[162:165], v[208:211], v[22:25]
	v_mfma_f32_16x16x32_bf16 v[18:21], v[170:173], v[208:211], v[18:21]
	v_mfma_f32_16x16x32_bf16 v[6:9], v[162:165], v[216:219], v[6:9]
	v_mfma_f32_16x16x32_bf16 v[2:5], v[170:173], v[216:219], v[2:5]
	v_mfma_f32_16x16x32_bf16 v[54:57], v[166:169], v[190:193], v[54:57]
	v_mfma_f32_16x16x32_bf16 v[50:53], v[182:185], v[190:193], v[50:53]
	v_mfma_f32_16x16x32_bf16 v[38:41], v[166:169], v[204:207], v[38:41]
	v_mfma_f32_16x16x32_bf16 v[34:37], v[182:185], v[204:207], v[34:37]
	v_mfma_f32_16x16x32_bf16 v[22:25], v[166:169], v[212:215], v[22:25]
	v_mfma_f32_16x16x32_bf16 v[18:21], v[182:185], v[212:215], v[18:21]
	v_mfma_f32_16x16x32_bf16 v[6:9], v[166:169], v[220:223], v[6:9]
	v_mfma_f32_16x16x32_bf16 v[2:5], v[182:185], v[220:223], v[2:5]
	s_barrier
	s_setprio 0
	s_add_u32 s52, s52, 0x100
	s_addc_u32 s53, s53, 0
	s_add_u32 s79, s79, 0x100
	s_addc_u32 s80, s80, 0
	s_cmp_ge_u32 s81, s65
	s_mov_b32 s54, s81
	s_cbranch_scc1 .LBB0_346
; #define PG8_STAGE(bufoff, gbase, voff) do { _Pragma("unroll") for (int _i = 0; _i < 2; ++_i) \
;         __builtin_amdgcn_global_load_lds((const unsigned*)((const char*)(gbase) + (voff)[_i]), (PG8_LAS unsigned*)(lds + (bufoff) + ldsw + _i * 8192), 16, 0, 0); } while (0)
; #define PG8_LDA(dst, b, h) do { _Pragma("unroll") for (int m = 0; m < 4; ++m) _Pragma("unroll") for (int k = 0; k < 2; ++k) dst[m][k] = *(const PG8_LAS bf16x8*)(lds + PG8_SA(b, h) + aoff + m * 2048 + k * 1024); } while (0)
; #define PG8_LDB(dst, b, h) do { _Pragma("unroll") for (int n = 0; n < 2; ++n) _Pragma("unroll") for (int k = 0; k < 2; ++k) dst[n][k] = *(const PG8_LAS bf16x8*)(lds + PG8_SB(b, h) + boff + n * 2048 + k * 1024); } while (0)
; #define PG8_WAIT_V(n) asm volatile("s_waitcnt vmcnt(" #n ")" ::: "memory")
; #define PG8_WAIT_L(n) asm volatile("s_waitcnt lgkmcnt(" #n ")" ::: "memory")
; #define PG8_BAR __builtin_amdgcn_s_barrier()
; #define PG8_SCHED __builtin_amdgcn_sched_barrier(0)
; template <class Epi, class Sched, bool ALIGN_EPI = false, bool SP2 = false, bool F16 = false>
; __device__ __forceinline__ void gemm_phase(PG8_LAS unsigned char* lds, const Gemm g, const Sched& S, const Epi& E) {
;     ...
;             PG8_LDB(B0, 0, 0); PG8_LDB(B1, 0, 1); PG8_SCHED; PG8_LDA(At, 0, 0); PG8_STAGE(PG8_SA(1, 1), a1 + hstepA, voffA);
;             PG8_WAIT_V(8); PG8_WAIT_L(0); PG8_BAR; PG8_MMA(0, 0, At, B0); PG8_MMA(0, 1, At, B1); PG8_BAR; PG8_SCHED;
;             PG8_LDA(At, 0, 1); PG8_STAGE(PG8_SB(0, 0), b2, voffB); PG8_STAGE(PG8_SB(0, 1), b2 + hstepB, voffB); PG8_STAGE(PG8_SA(0, 0), a2, voffA);
;             PG8_WAIT_V(8); PG8_WAIT_L(0); PG8_BAR; PG8_MMA(1, 0, At, B0); PG8_MMA(1, 1, At, B1); PG8_BAR; PG8_SCHED;
.LBB0_345:
	s_add_i32 s81, s54, 2
	s_add_u32 s82, s52, 0x80
	s_addc_u32 s55, s53, 0
	s_add_i32 s94, 0, 0x10000
	s_cmp_eq_u32 s74, s54
	s_cselect_b32 s55, s41, s55
	s_cselect_b32 s54, s40, s82
	s_cselect_b32 s83, s47, s80
	s_cselect_b32 s82, s46, s79
	s_add_i32 s95, 0, 0x14000
	ds_read_b128 v[130:133], v139
	ds_read_b128 v[134:137], v139 offset:1024
	ds_read_b128 v[148:151], v139 offset:2048
	ds_read_b128 v[152:155], v139 offset:3072
	ds_read_b128 v[162:165], v141
	ds_read_b128 v[166:169], v141 offset:1024
	ds_read_b128 v[170:173], v141 offset:2048
	ds_read_b128 v[182:185], v141 offset:3072
	s_add_i32 m0, s3, 0xc000
	ds_read_b128 v[186:189], v160
	ds_read_b128 v[190:193], v160 offset:1024
	ds_read_b128 v[194:197], v160 offset:2048
	ds_read_b128 v[204:207], v160 offset:3072
	ds_read_b128 v[208:211], v160 offset:4096
	ds_read_b128 v[212:215], v160 offset:5120
	ds_read_b128 v[216:219], v160 offset:6144
	ds_read_b128 v[220:223], v160 offset:7168
	global_load_lds_dwordx4 v144, s[52:53]
	s_add_i32 m0, s3, 0xe000
	s_nop 0
	global_load_lds_dwordx4 v146, s[52:53]
	s_waitcnt vmcnt(8) lgkmcnt(0)
	s_setprio 1
	s_barrier
	v_mfma_f32_16x16x32_bf16 v[122:125], v[130:133], v[186:189], v[122:125]
	v_mfma_f32_16x16x32_bf16 v[126:129], v[148:151], v[186:189], v[126:129]
	v_mfma_f32_16x16x32_bf16 v[110:113], v[130:133], v[194:197], v[110:113]
	v_mfma_f32_16x16x32_bf16 v[106:109], v[148:151], v[194:197], v[106:109]
	v_mfma_f32_16x16x32_bf16 v[94:97], v[130:133], v[208:211], v[94:97]
	v_mfma_f32_16x16x32_bf16 v[90:93], v[148:151], v[208:211], v[90:93]
	v_mfma_f32_16x16x32_bf16 v[78:81], v[130:133], v[216:219], v[78:81]
	v_mfma_f32_16x16x32_bf16 v[74:77], v[148:151], v[216:219], v[74:77]
	v_mfma_f32_16x16x32_bf16 v[122:125], v[134:137], v[190:193], v[122:125]
	v_mfma_f32_16x16x32_bf16 v[126:129], v[152:155], v[190:193], v[126:129]
	v_mfma_f32_16x16x32_bf16 v[110:113], v[134:137], v[204:207], v[110:113]
	v_mfma_f32_16x16x32_bf16 v[106:109], v[152:155], v[204:207], v[106:109]
	v_mfma_f32_16x16x32_bf16 v[94:97], v[134:137], v[212:215], v[94:97]
	v_mfma_f32_16x16x32_bf16 v[90:93], v[152:155], v[212:215], v[90:93]
	v_mfma_f32_16x16x32_bf16 v[78:81], v[134:137], v[220:223], v[78:81]
	v_mfma_f32_16x16x32_bf16 v[74:77], v[152:155], v[220:223], v[74:77]
	v_mfma_f32_16x16x32_bf16 v[118:121], v[162:165], v[186:189], v[118:121]
	v_mfma_f32_16x16x32_bf16 v[114:117], v[170:173], v[186:189], v[114:117]
	v_mfma_f32_16x16x32_bf16 v[102:105], v[162:165], v[194:197], v[102:105]
	v_mfma_f32_16x16x32_bf16 v[98:101], v[170:173], v[194:197], v[98:101]
	v_mfma_f32_16x16x32_bf16 v[86:89], v[162:165], v[208:211], v[86:89]
	v_mfma_f32_16x16x32_bf16 v[82:85], v[170:173], v[208:211], v[82:85]
	v_mfma_f32_16x16x32_bf16 v[70:73], v[162:165], v[216:219], v[70:73]
	v_mfma_f32_16x16x32_bf16 v[66:69], v[170:173], v[216:219], v[66:69]
	v_mfma_f32_16x16x32_bf16 v[118:121], v[166:169], v[190:193], v[118:121]
	v_mfma_f32_16x16x32_bf16 v[114:117], v[182:185], v[190:193], v[114:117]
	v_mfma_f32_16x16x32_bf16 v[102:105], v[166:169], v[204:207], v[102:105]
	v_mfma_f32_16x16x32_bf16 v[98:101], v[182:185], v[204:207], v[98:101]
	v_mfma_f32_16x16x32_bf16 v[86:89], v[166:169], v[212:215], v[86:89]
	v_mfma_f32_16x16x32_bf16 v[82:85], v[182:185], v[212:215], v[82:85]
	v_mfma_f32_16x16x32_bf16 v[70:73], v[166:169], v[220:223], v[70:73]
	v_mfma_f32_16x16x32_bf16 v[66:69], v[182:185], v[220:223], v[66:69]
	s_barrier
	s_setprio 0
	s_add_i32 s94, s94, s2
	s_mov_b32 m0, s94
	s_nop 0
	global_load_lds_dwordx4 v174, s[82:83]
	ds_read_b128 v[186:189], v160 offset:16384
	ds_read_b128 v[190:193], v160 offset:17408
	ds_read_b128 v[194:197], v160 offset:18432
	ds_read_b128 v[204:207], v160 offset:19456
	ds_read_b128 v[208:211], v160 offset:20480
	ds_read_b128 v[212:215], v160 offset:21504
	ds_read_b128 v[216:219], v160 offset:22528
	ds_read_b128 v[220:223], v160 offset:23552
	s_add_i32 m0, s94, 0x2000
	s_nop 0
	global_load_lds_dwordx4 v142, s[82:83]
	s_add_i32 s94, s95, s2
	s_add_u32 s82, s82, s48
	s_addc_u32 s83, s83, 0
	s_mov_b32 m0, s94
	s_nop 0
	global_load_lds_dwordx4 v174, s[82:83]
	s_add_i32 m0, s94, 0x2000
	s_nop 0
	global_load_lds_dwordx4 v142, s[82:83]
	s_mov_b32 m0, s3
	s_nop 0
	global_load_lds_dwordx4 v138, s[54:55]
	s_mov_b32 m0, s12
	s_nop 0
	global_load_lds_dwordx4 v140, s[54:55]
	s_waitcnt vmcnt(8) lgkmcnt(0)
	s_setprio 1
	s_barrier
	v_mfma_f32_16x16x32_bf16 v[62:65], v[130:133], v[186:189], v[62:65]
	v_mfma_f32_16x16x32_bf16 v[58:61], v[148:151], v[186:189], v[58:61]
	v_mfma_f32_16x16x32_bf16 v[46:49], v[130:133], v[194:197], v[46:49]
	v_mfma_f32_16x16x32_bf16 v[42:45], v[148:151], v[194:197], v[42:45]
	v_mfma_f32_16x16x32_bf16 v[30:33], v[130:133], v[208:211], v[30:33]
	v_mfma_f32_16x16x32_bf16 v[26:29], v[148:151], v[208:211], v[26:29]
	v_mfma_f32_16x16x32_bf16 v[14:17], v[130:133], v[216:219], v[14:17]
	v_mfma_f32_16x16x32_bf16 v[10:13], v[148:151], v[216:219], v[10:13]
	v_mfma_f32_16x16x32_bf16 v[62:65], v[134:137], v[190:193], v[62:65]
	v_mfma_f32_16x16x32_bf16 v[58:61], v[152:155], v[190:193], v[58:61]
	v_mfma_f32_16x16x32_bf16 v[46:49], v[134:137], v[204:207], v[46:49]
	v_mfma_f32_16x16x32_bf16 v[42:45], v[152:155], v[204:207], v[42:45]
	v_mfma_f32_16x16x32_bf16 v[30:33], v[134:137], v[212:215], v[30:33]
	v_mfma_f32_16x16x32_bf16 v[26:29], v[152:155], v[212:215], v[26:29]
	v_mfma_f32_16x16x32_bf16 v[14:17], v[134:137], v[220:223], v[14:17]
	v_mfma_f32_16x16x32_bf16 v[10:13], v[152:155], v[220:223], v[10:13]
	v_mfma_f32_16x16x32_bf16 v[54:57], v[162:165], v[186:189], v[54:57]
	v_mfma_f32_16x16x32_bf16 v[50:53], v[170:173], v[186:189], v[50:53]
	v_mfma_f32_16x16x32_bf16 v[38:41], v[162:165], v[194:197], v[38:41]
	v_mfma_f32_16x16x32_bf16 v[34:37], v[170:173], v[194:197], v[34:37]
	v_mfma_f32_16x16x32_bf16 v[22:25], v[162:165], v[208:211], v[22:25]
	v_mfma_f32_16x16x32_bf16 v[18:21], v[170:173], v[208:211], v[18:21]
	v_mfma_f32_16x16x32_bf16 v[6:9], v[162:165], v[216:219], v[6:9]
	v_mfma_f32_16x16x32_bf16 v[2:5], v[170:173], v[216:219], v[2:5]
	v_mfma_f32_16x16x32_bf16 v[54:57], v[166:169], v[190:193], v[54:57]
	v_mfma_f32_16x16x32_bf16 v[50:53], v[182:185], v[190:193], v[50:53]
	v_mfma_f32_16x16x32_bf16 v[38:41], v[166:169], v[204:207], v[38:41]
	v_mfma_f32_16x16x32_bf16 v[34:37], v[182:185], v[204:207], v[34:37]
	v_mfma_f32_16x16x32_bf16 v[22:25], v[166:169], v[212:215], v[22:25]
	v_mfma_f32_16x16x32_bf16 v[18:21], v[182:185], v[212:215], v[18:21]
	v_mfma_f32_16x16x32_bf16 v[6:9], v[166:169], v[220:223], v[6:9]
	v_mfma_f32_16x16x32_bf16 v[2:5], v[182:185], v[220:223], v[2:5]
	s_barrier
; #define PG8_STAGE(bufoff, gbase, voff) do { _Pragma("unroll") for (int _i = 0; _i < 2; ++_i) \
;         __builtin_amdgcn_global_load_lds((const unsigned*)((const char*)(gbase) + (voff)[_i]), (PG8_LAS unsigned*)(lds + (bufoff) + ldsw + _i * 8192), 16, 0, 0); } while (0)
; #define PG8_LDA(dst, b, h) do { _Pragma("unroll") for (int m = 0; m < 4; ++m) _Pragma("unroll") for (int k = 0; k < 2; ++k) dst[m][k] = *(const PG8_LAS bf16x8*)(lds + PG8_SA(b, h) + aoff + m * 2048 + k * 1024); } while (0)
; #define PG8_LDB(dst, b, h) do { _Pragma("unroll") for (int n = 0; n < 2; ++n) _Pragma("unroll") for (int k = 0; k < 2; ++k) dst[n][k] = *(const PG8_LAS bf16x8*)(lds + PG8_SB(b, h) + boff + n * 2048 + k * 1024); } while (0)
; #define PG8_WAIT_V(n) asm volatile("s_waitcnt vmcnt(" #n ")" ::: "memory")
; #define PG8_WAIT_L(n) asm volatile("s_waitcnt lgkmcnt(" #n ")" ::: "memory")
; #define PG8_BAR __builtin_amdgcn_s_barrier()
; #define PG8_SCHED __builtin_amdgcn_sched_barrier(0)
; template <class Epi, class Sched, bool ALIGN_EPI = false, bool SP2 = false, bool F16 = false>
; __device__ __forceinline__ void gemm_phase(PG8_LAS unsigned char* lds, const Gemm g, const Sched& S, const Epi& E) {
;     ...
;             PG8_LDB(B0, 1, 0); PG8_LDB(B1, 1, 1); PG8_SCHED; PG8_LDA(At, 1, 0); PG8_STAGE(PG8_SA(0, 1), a2 + hstepA, voffA);
;             PG8_WAIT_V(8); PG8_WAIT_L(0); PG8_BAR; PG8_MMA(0, 0, At, B0); PG8_MMA(0, 1, At, B1); PG8_BAR; PG8_SCHED;
;             PG8_LDA(At, 1, 1); PG8_STAGE(PG8_SB(1, 0), b3, voffB); PG8_STAGE(PG8_SB(1, 1), b3 + hstepB, voffB); PG8_STAGE(PG8_SA(1, 0), a3, voffA);
;             PG8_WAIT_V(8); PG8_WAIT_L(0); PG8_BAR; PG8_MMA(1, 0, At, B0); PG8_MMA(1, 1, At, B1); PG8_BAR; PG8_SCHED;
	s_setprio 0
	s_add_i32 s82, 0, 0x18000
	s_add_i32 s83, 0, 0x1c000
	ds_read_b128 v[130:133], v143
	ds_read_b128 v[134:137], v143 offset:1024
	ds_read_b128 v[148:151], v143 offset:2048
	ds_read_b128 v[152:155], v143 offset:3072
	ds_read_b128 v[162:165], v157
	ds_read_b128 v[166:169], v157 offset:1024
	ds_read_b128 v[170:173], v157 offset:2048
	ds_read_b128 v[182:185], v157 offset:3072
	s_add_u32 s54, s54, s8
	s_addc_u32 s55, s55, 0
	s_mov_b32 m0, s13
	ds_read_b128 v[186:189], v160 offset:32768
	ds_read_b128 v[190:193], v160 offset:33792
	ds_read_b128 v[194:197], v160 offset:34816
	ds_read_b128 v[204:207], v160 offset:35840
	ds_read_b128 v[208:211], v160 offset:36864
	ds_read_b128 v[212:215], v160 offset:37888
	ds_read_b128 v[216:219], v160 offset:38912
	ds_read_b128 v[220:223], v160 offset:39936
	global_load_lds_dwordx4 v138, s[54:55]
	s_mov_b32 m0, s22
	s_nop 0
	global_load_lds_dwordx4 v140, s[54:55]
	s_waitcnt vmcnt(8) lgkmcnt(0)
	s_setprio 1
	s_barrier
	v_mfma_f32_16x16x32_bf16 v[122:125], v[130:133], v[186:189], v[122:125]
	v_mfma_f32_16x16x32_bf16 v[126:129], v[148:151], v[186:189], v[126:129]
	v_mfma_f32_16x16x32_bf16 v[110:113], v[130:133], v[194:197], v[110:113]
	v_mfma_f32_16x16x32_bf16 v[106:109], v[148:151], v[194:197], v[106:109]
	v_mfma_f32_16x16x32_bf16 v[94:97], v[130:133], v[208:211], v[94:97]
	v_mfma_f32_16x16x32_bf16 v[90:93], v[148:151], v[208:211], v[90:93]
	v_mfma_f32_16x16x32_bf16 v[78:81], v[130:133], v[216:219], v[78:81]
	v_mfma_f32_16x16x32_bf16 v[74:77], v[148:151], v[216:219], v[74:77]
	v_mfma_f32_16x16x32_bf16 v[122:125], v[134:137], v[190:193], v[122:125]
	v_mfma_f32_16x16x32_bf16 v[126:129], v[152:155], v[190:193], v[126:129]
	v_mfma_f32_16x16x32_bf16 v[110:113], v[134:137], v[204:207], v[110:113]
	v_mfma_f32_16x16x32_bf16 v[106:109], v[152:155], v[204:207], v[106:109]
	v_mfma_f32_16x16x32_bf16 v[94:97], v[134:137], v[212:215], v[94:97]
	v_mfma_f32_16x16x32_bf16 v[90:93], v[152:155], v[212:215], v[90:93]
	v_mfma_f32_16x16x32_bf16 v[78:81], v[134:137], v[220:223], v[78:81]
	v_mfma_f32_16x16x32_bf16 v[74:77], v[152:155], v[220:223], v[74:77]
	v_mfma_f32_16x16x32_bf16 v[118:121], v[162:165], v[186:189], v[118:121]
	v_mfma_f32_16x16x32_bf16 v[114:117], v[170:173], v[186:189], v[114:117]
	v_mfma_f32_16x16x32_bf16 v[102:105], v[162:165], v[194:197], v[102:105]
	v_mfma_f32_16x16x32_bf16 v[98:101], v[170:173], v[194:197], v[98:101]
	v_mfma_f32_16x16x32_bf16 v[86:89], v[162:165], v[208:211], v[86:89]
	v_mfma_f32_16x16x32_bf16 v[82:85], v[170:173], v[208:211], v[82:85]
	v_mfma_f32_16x16x32_bf16 v[70:73], v[162:165], v[216:219], v[70:73]
	v_mfma_f32_16x16x32_bf16 v[66:69], v[170:173], v[216:219], v[66:69]
	v_mfma_f32_16x16x32_bf16 v[118:121], v[166:169], v[190:193], v[118:121]
	v_mfma_f32_16x16x32_bf16 v[114:117], v[182:185], v[190:193], v[114:117]
	v_mfma_f32_16x16x32_bf16 v[102:105], v[166:169], v[204:207], v[102:105]
	v_mfma_f32_16x16x32_bf16 v[98:101], v[182:185], v[204:207], v[98:101]
	v_mfma_f32_16x16x32_bf16 v[86:89], v[166:169], v[212:215], v[86:89]
	v_mfma_f32_16x16x32_bf16 v[82:85], v[182:185], v[212:215], v[82:85]
	v_mfma_f32_16x16x32_bf16 v[70:73], v[166:169], v[220:223], v[70:73]
	v_mfma_f32_16x16x32_bf16 v[66:69], v[182:185], v[220:223], v[66:69]
	s_barrier
	s_setprio 0
	s_add_i32 s54, s82, s2
	s_add_i32 vcc_hi, s81, -2
	s_cmp_eq_u32 s74, vcc_hi
	s_cselect_b32 s99, s47, s80
	s_cselect_b32 s98, s46, s79
	s_add_u32 s98, s98, s92
	s_addc_u32 s99, s99, s93
	s_mov_b32 m0, s54
	s_nop 0
	global_load_lds_dwordx4 v174, s[98:99]
	ds_read_b128 v[186:189], v160 offset:49152
	ds_read_b128 v[190:193], v160 offset:50176
	ds_read_b128 v[194:197], v160 offset:51200
	ds_read_b128 v[204:207], v160 offset:52224
	ds_read_b128 v[208:211], v160 offset:53248
	ds_read_b128 v[212:215], v160 offset:54272
	ds_read_b128 v[216:219], v160 offset:55296
	ds_read_b128 v[220:223], v160 offset:56320
	s_add_i32 m0, s54, 0x2000
	s_nop 0
	global_load_lds_dwordx4 v142, s[98:99]
	s_add_i32 s54, s83, s2
	s_add_u32 s98, s98, s48
	s_addc_u32 s99, s99, 0
	s_mov_b32 m0, s54
	s_nop 0
	global_load_lds_dwordx4 v174, s[98:99]
	s_add_i32 m0, s54, 0x2000
	s_nop 0
	global_load_lds_dwordx4 v142, s[98:99]
	s_add_u32 s98, s52, 0x80
	s_addc_u32 s99, s53, 0
	s_cmp_eq_u32 s74, vcc_hi
	s_cselect_b32 s99, s41, s99
	s_cselect_b32 s98, s40, s98
	s_add_u32 s98, s98, s92
	s_addc_u32 s99, s99, s93
	s_mov_b32 m0, s33
	s_nop 0
	global_load_lds_dwordx4 v138, s[98:99]
	s_mov_b32 m0, s35
	s_nop 0
	global_load_lds_dwordx4 v140, s[98:99]
	s_waitcnt vmcnt(8) lgkmcnt(0)
	s_setprio 1
	s_barrier
	v_mfma_f32_16x16x32_bf16 v[62:65], v[130:133], v[186:189], v[62:65]
	v_mfma_f32_16x16x32_bf16 v[58:61], v[148:151], v[186:189], v[58:61]
	v_mfma_f32_16x16x32_bf16 v[46:49], v[130:133], v[194:197], v[46:49]
	v_mfma_f32_16x16x32_bf16 v[42:45], v[148:151], v[194:197], v[42:45]
	v_mfma_f32_16x16x32_bf16 v[30:33], v[130:133], v[208:211], v[30:33]
	v_mfma_f32_16x16x32_bf16 v[26:29], v[148:151], v[208:211], v[26:29]
	v_mfma_f32_16x16x32_bf16 v[14:17], v[130:133], v[216:219], v[14:17]
	v_mfma_f32_16x16x32_bf16 v[10:13], v[148:151], v[216:219], v[10:13]
	v_mfma_f32_16x16x32_bf16 v[62:65], v[134:137], v[190:193], v[62:65]
	v_mfma_f32_16x16x32_bf16 v[58:61], v[152:155], v[190:193], v[58:61]
	v_mfma_f32_16x16x32_bf16 v[46:49], v[134:137], v[204:207], v[46:49]
	v_mfma_f32_16x16x32_bf16 v[42:45], v[152:155], v[204:207], v[42:45]
	v_mfma_f32_16x16x32_bf16 v[30:33], v[134:137], v[212:215], v[30:33]
	v_mfma_f32_16x16x32_bf16 v[26:29], v[152:155], v[212:215], v[26:29]
	v_mfma_f32_16x16x32_bf16 v[14:17], v[134:137], v[220:223], v[14:17]
	v_mfma_f32_16x16x32_bf16 v[10:13], v[152:155], v[220:223], v[10:13]
	v_mfma_f32_16x16x32_bf16 v[54:57], v[162:165], v[186:189], v[54:57]
	v_mfma_f32_16x16x32_bf16 v[50:53], v[170:173], v[186:189], v[50:53]
	v_mfma_f32_16x16x32_bf16 v[38:41], v[162:165], v[194:197], v[38:41]
	v_mfma_f32_16x16x32_bf16 v[34:37], v[170:173], v[194:197], v[34:37]
	v_mfma_f32_16x16x32_bf16 v[22:25], v[162:165], v[208:211], v[22:25]
	v_mfma_f32_16x16x32_bf16 v[18:21], v[170:173], v[208:211], v[18:21]
	v_mfma_f32_16x16x32_bf16 v[6:9], v[162:165], v[216:219], v[6:9]
	v_mfma_f32_16x16x32_bf16 v[2:5], v[170:173], v[216:219], v[2:5]
	v_mfma_f32_16x16x32_bf16 v[54:57], v[166:169], v[190:193], v[54:57]
	v_mfma_f32_16x16x32_bf16 v[50:53], v[182:185], v[190:193], v[50:53]
	v_mfma_f32_16x16x32_bf16 v[38:41], v[166:169], v[204:207], v[38:41]
	v_mfma_f32_16x16x32_bf16 v[34:37], v[182:185], v[204:207], v[34:37]
	v_mfma_f32_16x16x32_bf16 v[22:25], v[166:169], v[212:215], v[22:25]
	v_mfma_f32_16x16x32_bf16 v[18:21], v[182:185], v[212:215], v[18:21]
	v_mfma_f32_16x16x32_bf16 v[6:9], v[166:169], v[220:223], v[6:9]
	v_mfma_f32_16x16x32_bf16 v[2:5], v[182:185], v[220:223], v[2:5]
	s_barrier
	s_setprio 0
	s_add_u32 s52, s52, 0x100
	s_addc_u32 s53, s53, 0
	s_add_u32 s79, s79, 0x100
	s_addc_u32 s80, s80, 0
	s_cmp_ge_u32 s81, s65
	s_mov_b32 s54, s81
	s_cbranch_scc0 .LBB0_345

; #define PG8_STAGE(bufoff, gbase, voff) do { _Pragma("unroll") for (int _i = 0; _i < 2; ++_i) \
;         __builtin_amdgcn_global_load_lds((const unsigned*)((const char*)(gbase) + (voff)[_i]), (PG8_LAS unsigned*)(lds + (bufoff) + ldsw + _i * 8192), 16, 0, 0); } while (0)
; #define PG8_LDA(dst, b, h) do { _Pragma("unroll") for (int m = 0; m < 4; ++m) _Pragma("unroll") for (int k = 0; k < 2; ++k) dst[m][k] = *(const PG8_LAS bf16x8*)(lds + PG8_SA(b, h) + aoff + m * 2048 + k * 1024); } while (0)
; #define PG8_LDB(dst, b, h) do { _Pragma("unroll") for (int n = 0; n < 2; ++n) _Pragma("unroll") for (int k = 0; k < 2; ++k) dst[n][k] = *(const PG8_LAS bf16x8*)(lds + PG8_SB(b, h) + boff + n * 2048 + k * 1024); } while (0)
; #define PG8_WAIT_V(n) asm volatile("s_waitcnt vmcnt(" #n ")" ::: "memory")
; #define PG8_WAIT_L(n) asm volatile("s_waitcnt lgkmcnt(" #n ")" ::: "memory")
; #define PG8_BAR __builtin_amdgcn_s_barrier()
; #define PG8_SCHED __builtin_amdgcn_sched_barrier(0)
; template <class Epi, class Sched, bool ALIGN_EPI = false, bool SP2 = false, bool F16 = false>
; __device__ __forceinline__ void gemm_phase(PG8_LAS unsigned char* lds, const Gemm g, const Sched& S, const Epi& E) {
;     ...
;         for (int t = 0; t < nt; t += 2) {
;             const bool last = (t == nt - 2);
;             const char* a1 = cA + (size_t)(t + 1) * kstep;
;             const char* a2 = last ? nA : cA + (size_t)(t + 2) * kstep; const char* b2 = last ? nB : cB + (size_t)(t + 2) * kstep;
;             const char* a3 = a2 + kstep; const char* b3 = b2 + kstep;
;             if (last && has_next) S.a_ready(nxt);
;             if constexpr (SP2) {
;             PG8_LDB(B0, 0, 0); PG8_LDB(B1, 0, 1); PG8_SCHED; PG8_LDA(At, 0, 0); PG8_STAGE(PG8_SA(1, 1), a1 + hstepA, voffA);
;             PG8_WAIT_V(8); PG8_WAIT_L(0); PG8_BAR; PG8_MMA(0, 0, At, B0); PG8_MMA(0, 1, At, B1); PG8_BAR; PG8_SCHED;
;             PG8_LDA(At, 0, 1); PG8_STAGE(PG8_SB(0, 0), b2, voffB); PG8_STAGE(PG8_SB(0, 1), b2 + hstepB, voffB); PG8_STAGE(PG8_SA(0, 0), a2, voffA);
;             PG8_WAIT_V(8); PG8_WAIT_L(0); PG8_BAR; PG8_MMA(1, 0, At, B0); PG8_MMA(1, 1, At, B1); PG8_BAR; PG8_SCHED;
.Lpk_bf:
	s_add_i32 s78, s72, 2
	s_add_u32 s79, s46, 0x80
	s_addc_u32 s73, s47, 0
	s_add_i32 vcc_lo, 0, 0x10000
	s_cmp_eq_u32 s74, s72
	s_cselect_b32 s73, s55, s73
	s_cselect_b32 s72, s54, s79
	s_cselect_b32 s95, s53, s24
	s_cselect_b32 s94, s52, s13
	s_add_i32 s79, 0, 0x14000
	ds_read_b128 v[130:133], v155
	ds_read_b128 v[134:137], v155 offset:1024
	ds_read_b128 v[138:141], v155 offset:2048
	ds_read_b128 v[142:145], v155 offset:3072
	ds_read_b128 v[146:149], v157
	ds_read_b128 v[150:153], v157 offset:1024
	ds_read_b128 v[182:185], v157 offset:2048
	ds_read_b128 v[186:189], v157 offset:3072
	s_add_i32 m0, s36, 0xc000
	ds_read_b128 v[190:193], v204
	ds_read_b128 v[194:197], v204 offset:1024
	ds_read_b128 v[206:209], v204 offset:2048
	ds_read_b128 v[210:213], v204 offset:3072
	ds_read_b128 v[214:217], v204 offset:4096
	ds_read_b128 v[218:221], v204 offset:5120
	ds_read_b128 v[222:225], v204 offset:6144
	ds_read_b128 v[226:229], v204 offset:7168
	global_load_lds_dwordx4 v168, s[46:47]
	s_add_i32 m0, s36, 0xe000
	s_nop 0
	global_load_lds_dwordx4 v170, s[46:47]
	s_waitcnt vmcnt(8) lgkmcnt(0)
	s_setprio 1
	s_barrier
	v_mfma_f32_16x16x32_bf16 v[122:125], v[130:133], v[190:193], 0
	v_mfma_f32_16x16x32_bf16 v[126:129], v[138:141], v[190:193], 0
	v_mfma_f32_16x16x32_bf16 v[110:113], v[130:133], v[206:209], 0
	v_mfma_f32_16x16x32_bf16 v[106:109], v[138:141], v[206:209], 0
	v_mfma_f32_16x16x32_bf16 v[94:97], v[130:133], v[214:217], 0
	v_mfma_f32_16x16x32_bf16 v[90:93], v[138:141], v[214:217], 0
	v_mfma_f32_16x16x32_bf16 v[78:81], v[130:133], v[222:225], 0
	v_mfma_f32_16x16x32_bf16 v[74:77], v[138:141], v[222:225], 0
	v_mfma_f32_16x16x32_bf16 v[122:125], v[134:137], v[194:197], v[122:125]
	v_mfma_f32_16x16x32_bf16 v[126:129], v[142:145], v[194:197], v[126:129]
	v_mfma_f32_16x16x32_bf16 v[110:113], v[134:137], v[210:213], v[110:113]
	v_mfma_f32_16x16x32_bf16 v[106:109], v[142:145], v[210:213], v[106:109]
	v_mfma_f32_16x16x32_bf16 v[94:97], v[134:137], v[218:221], v[94:97]
	v_mfma_f32_16x16x32_bf16 v[90:93], v[142:145], v[218:221], v[90:93]
	v_mfma_f32_16x16x32_bf16 v[78:81], v[134:137], v[226:229], v[78:81]
	v_mfma_f32_16x16x32_bf16 v[74:77], v[142:145], v[226:229], v[74:77]
	v_mfma_f32_16x16x32_bf16 v[118:121], v[146:149], v[190:193], 0
	v_mfma_f32_16x16x32_bf16 v[114:117], v[182:185], v[190:193], 0
	v_mfma_f32_16x16x32_bf16 v[102:105], v[146:149], v[206:209], 0
	v_mfma_f32_16x16x32_bf16 v[98:101], v[182:185], v[206:209], 0
	v_mfma_f32_16x16x32_bf16 v[86:89], v[146:149], v[214:217], 0
	v_mfma_f32_16x16x32_bf16 v[82:85], v[182:185], v[214:217], 0
	v_mfma_f32_16x16x32_bf16 v[70:73], v[146:149], v[222:225], 0
	v_mfma_f32_16x16x32_bf16 v[66:69], v[182:185], v[222:225], 0
	v_mfma_f32_16x16x32_bf16 v[118:121], v[150:153], v[194:197], v[118:121]
	v_mfma_f32_16x16x32_bf16 v[114:117], v[186:189], v[194:197], v[114:117]
	v_mfma_f32_16x16x32_bf16 v[102:105], v[150:153], v[210:213], v[102:105]
	v_mfma_f32_16x16x32_bf16 v[98:101], v[186:189], v[210:213], v[98:101]
	v_mfma_f32_16x16x32_bf16 v[86:89], v[150:153], v[218:221], v[86:89]
	v_mfma_f32_16x16x32_bf16 v[82:85], v[186:189], v[218:221], v[82:85]
	v_mfma_f32_16x16x32_bf16 v[70:73], v[150:153], v[226:229], v[70:73]
	v_mfma_f32_16x16x32_bf16 v[66:69], v[186:189], v[226:229], v[66:69]
	s_barrier
	s_setprio 0
	s_add_i32 vcc_lo, vcc_lo, s75
	s_mov_b32 m0, vcc_lo
	s_nop 0
	global_load_lds_dwordx4 v156, s[94:95]
	ds_read_b128 v[190:193], v204 offset:16384
	ds_read_b128 v[194:197], v204 offset:17408
	ds_read_b128 v[206:209], v204 offset:18432
	ds_read_b128 v[210:213], v204 offset:19456
	ds_read_b128 v[214:217], v204 offset:20480
	ds_read_b128 v[218:221], v204 offset:21504
	ds_read_b128 v[222:225], v204 offset:22528
	ds_read_b128 v[226:229], v204 offset:23552
	s_add_i32 m0, vcc_lo, 0x2000
	s_nop 0
	global_load_lds_dwordx4 v160, s[94:95]
	s_add_i32 s79, s79, s75
	s_add_u32 s94, s94, s48
	s_addc_u32 s95, s95, 0
	s_mov_b32 m0, s79
	s_nop 0
	global_load_lds_dwordx4 v156, s[94:95]
	s_add_i32 m0, s79, 0x2000
	s_nop 0
	global_load_lds_dwordx4 v160, s[94:95]
	s_mov_b32 m0, s36
	s_nop 0
	global_load_lds_dwordx4 v154, s[72:73]
	s_mov_b32 m0, s37
	s_nop 0
	global_load_lds_dwordx4 v158, s[72:73]
	s_waitcnt vmcnt(8) lgkmcnt(0)
	s_setprio 1
	s_barrier
	v_mfma_f32_16x16x32_bf16 v[62:65], v[130:133], v[190:193], 0
	v_mfma_f32_16x16x32_bf16 v[58:61], v[138:141], v[190:193], 0
	v_mfma_f32_16x16x32_bf16 v[46:49], v[130:133], v[206:209], 0
	v_mfma_f32_16x16x32_bf16 v[42:45], v[138:141], v[206:209], 0
	v_mfma_f32_16x16x32_bf16 v[30:33], v[130:133], v[214:217], 0
	v_mfma_f32_16x16x32_bf16 v[26:29], v[138:141], v[214:217], 0
	v_mfma_f32_16x16x32_bf16 v[14:17], v[130:133], v[222:225], 0
	v_mfma_f32_16x16x32_bf16 v[10:13], v[138:141], v[222:225], 0
	v_mfma_f32_16x16x32_bf16 v[62:65], v[134:137], v[194:197], v[62:65]
	v_mfma_f32_16x16x32_bf16 v[58:61], v[142:145], v[194:197], v[58:61]
	v_mfma_f32_16x16x32_bf16 v[46:49], v[134:137], v[210:213], v[46:49]
	v_mfma_f32_16x16x32_bf16 v[42:45], v[142:145], v[210:213], v[42:45]
	v_mfma_f32_16x16x32_bf16 v[30:33], v[134:137], v[218:221], v[30:33]
	v_mfma_f32_16x16x32_bf16 v[26:29], v[142:145], v[218:221], v[26:29]
	v_mfma_f32_16x16x32_bf16 v[14:17], v[134:137], v[226:229], v[14:17]
	v_mfma_f32_16x16x32_bf16 v[10:13], v[142:145], v[226:229], v[10:13]
	v_mfma_f32_16x16x32_bf16 v[54:57], v[146:149], v[190:193], 0
	v_mfma_f32_16x16x32_bf16 v[50:53], v[182:185], v[190:193], 0
	v_mfma_f32_16x16x32_bf16 v[38:41], v[146:149], v[206:209], 0
	v_mfma_f32_16x16x32_bf16 v[34:37], v[182:185], v[206:209], 0
	v_mfma_f32_16x16x32_bf16 v[22:25], v[146:149], v[214:217], 0
	v_mfma_f32_16x16x32_bf16 v[18:21], v[182:185], v[214:217], 0
	v_mfma_f32_16x16x32_bf16 v[6:9], v[146:149], v[222:225], 0
	v_mfma_f32_16x16x32_bf16 v[2:5], v[182:185], v[222:225], 0
	v_mfma_f32_16x16x32_bf16 v[54:57], v[150:153], v[194:197], v[54:57]
	v_mfma_f32_16x16x32_bf16 v[50:53], v[186:189], v[194:197], v[50:53]
	v_mfma_f32_16x16x32_bf16 v[38:41], v[150:153], v[210:213], v[38:41]
	v_mfma_f32_16x16x32_bf16 v[34:37], v[186:189], v[210:213], v[34:37]
	v_mfma_f32_16x16x32_bf16 v[22:25], v[150:153], v[218:221], v[22:25]
	v_mfma_f32_16x16x32_bf16 v[18:21], v[186:189], v[218:221], v[18:21]
	v_mfma_f32_16x16x32_bf16 v[6:9], v[150:153], v[226:229], v[6:9]
	v_mfma_f32_16x16x32_bf16 v[2:5], v[186:189], v[226:229], v[2:5]
	s_barrier
; #define PG8_STAGE(bufoff, gbase, voff) do { _Pragma("unroll") for (int _i = 0; _i < 2; ++_i) \
;         __builtin_amdgcn_global_load_lds((const unsigned*)((const char*)(gbase) + (voff)[_i]), (PG8_LAS unsigned*)(lds + (bufoff) + ldsw + _i * 8192), 16, 0, 0); } while (0)
; #define PG8_LDA(dst, b, h) do { _Pragma("unroll") for (int m = 0; m < 4; ++m) _Pragma("unroll") for (int k = 0; k < 2; ++k) dst[m][k] = *(const PG8_LAS bf16x8*)(lds + PG8_SA(b, h) + aoff + m * 2048 + k * 1024); } while (0)
; #define PG8_LDB(dst, b, h) do { _Pragma("unroll") for (int n = 0; n < 2; ++n) _Pragma("unroll") for (int k = 0; k < 2; ++k) dst[n][k] = *(const PG8_LAS bf16x8*)(lds + PG8_SB(b, h) + boff + n * 2048 + k * 1024); } while (0)
; #define PG8_WAIT_V(n) asm volatile("s_waitcnt vmcnt(" #n ")" ::: "memory")
; #define PG8_WAIT_L(n) asm volatile("s_waitcnt lgkmcnt(" #n ")" ::: "memory")
; #define PG8_BAR __builtin_amdgcn_s_barrier()
; #define PG8_SCHED __builtin_amdgcn_sched_barrier(0)
; template <class Epi, class Sched, bool ALIGN_EPI = false, bool SP2 = false, bool F16 = false>
; __device__ __forceinline__ void gemm_phase(PG8_LAS unsigned char* lds, const Gemm g, const Sched& S, const Epi& E) {
;     ...
;         for (int t = 0; t < nt; t += 2) {
;             const bool last = (t == nt - 2);
;             const char* a1 = cA + (size_t)(t + 1) * kstep;
;             const char* a2 = last ? nA : cA + (size_t)(t + 2) * kstep; const char* b2 = last ? nB : cB + (size_t)(t + 2) * kstep;
;             const char* a3 = a2 + kstep; const char* b3 = b2 + kstep;
;     ...
;             PG8_LDB(B0, 1, 0); PG8_LDB(B1, 1, 1); PG8_SCHED; PG8_LDA(At, 1, 0); PG8_STAGE(PG8_SA(0, 1), a2 + hstepA, voffA);
;             PG8_WAIT_V(8); PG8_WAIT_L(0); PG8_BAR; PG8_MMA(0, 0, At, B0); PG8_MMA(0, 1, At, B1); PG8_BAR; PG8_SCHED;
;             PG8_LDA(At, 1, 1); PG8_STAGE(PG8_SB(1, 0), b3, voffB); PG8_STAGE(PG8_SB(1, 1), b3 + hstepB, voffB); PG8_STAGE(PG8_SA(1, 0), a3, voffA);
;             PG8_WAIT_V(8); PG8_WAIT_L(0); PG8_BAR; PG8_MMA(1, 0, At, B0); PG8_MMA(1, 1, At, B1); PG8_BAR; PG8_SCHED;
	s_setprio 0
	s_add_i32 s79, 0, 0x18000
	s_add_i32 s94, 0, 0x1c000
	ds_read_b128 v[130:133], v159
	ds_read_b128 v[134:137], v159 offset:1024
	ds_read_b128 v[138:141], v159 offset:2048
	ds_read_b128 v[142:145], v159 offset:3072
	ds_read_b128 v[146:149], v161
	ds_read_b128 v[150:153], v161 offset:1024
	ds_read_b128 v[182:185], v161 offset:2048
	ds_read_b128 v[186:189], v161 offset:3072
	s_add_u32 s72, s72, s8
	s_addc_u32 s73, s73, 0
	s_mov_b32 m0, s35
	ds_read_b128 v[190:193], v204 offset:32768
	ds_read_b128 v[194:197], v204 offset:33792
	ds_read_b128 v[206:209], v204 offset:34816
	ds_read_b128 v[210:213], v204 offset:35840
	ds_read_b128 v[214:217], v204 offset:36864
	ds_read_b128 v[218:221], v204 offset:37888
	ds_read_b128 v[222:225], v204 offset:38912
	ds_read_b128 v[226:229], v204 offset:39936
	global_load_lds_dwordx4 v154, s[72:73]
	s_mov_b32 m0, s2
	s_nop 0
	global_load_lds_dwordx4 v158, s[72:73]
	s_waitcnt vmcnt(8) lgkmcnt(0)
	s_setprio 1
	s_barrier
	v_mfma_f32_16x16x32_bf16 v[122:125], v[130:133], v[190:193], v[122:125]
	v_mfma_f32_16x16x32_bf16 v[126:129], v[138:141], v[190:193], v[126:129]
	v_mfma_f32_16x16x32_bf16 v[110:113], v[130:133], v[206:209], v[110:113]
	v_mfma_f32_16x16x32_bf16 v[106:109], v[138:141], v[206:209], v[106:109]
	v_mfma_f32_16x16x32_bf16 v[94:97], v[130:133], v[214:217], v[94:97]
	v_mfma_f32_16x16x32_bf16 v[90:93], v[138:141], v[214:217], v[90:93]
	v_mfma_f32_16x16x32_bf16 v[78:81], v[130:133], v[222:225], v[78:81]
	v_mfma_f32_16x16x32_bf16 v[74:77], v[138:141], v[222:225], v[74:77]
	v_mfma_f32_16x16x32_bf16 v[122:125], v[134:137], v[194:197], v[122:125]
	v_mfma_f32_16x16x32_bf16 v[126:129], v[142:145], v[194:197], v[126:129]
	v_mfma_f32_16x16x32_bf16 v[110:113], v[134:137], v[210:213], v[110:113]
	v_mfma_f32_16x16x32_bf16 v[106:109], v[142:145], v[210:213], v[106:109]
	v_mfma_f32_16x16x32_bf16 v[94:97], v[134:137], v[218:221], v[94:97]
	v_mfma_f32_16x16x32_bf16 v[90:93], v[142:145], v[218:221], v[90:93]
	v_mfma_f32_16x16x32_bf16 v[78:81], v[134:137], v[226:229], v[78:81]
	v_mfma_f32_16x16x32_bf16 v[74:77], v[142:145], v[226:229], v[74:77]
	v_mfma_f32_16x16x32_bf16 v[118:121], v[146:149], v[190:193], v[118:121]
	v_mfma_f32_16x16x32_bf16 v[114:117], v[182:185], v[190:193], v[114:117]
	v_mfma_f32_16x16x32_bf16 v[102:105], v[146:149], v[206:209], v[102:105]
	v_mfma_f32_16x16x32_bf16 v[98:101], v[182:185], v[206:209], v[98:101]
	v_mfma_f32_16x16x32_bf16 v[86:89], v[146:149], v[214:217], v[86:89]
	v_mfma_f32_16x16x32_bf16 v[82:85], v[182:185], v[214:217], v[82:85]
	v_mfma_f32_16x16x32_bf16 v[70:73], v[146:149], v[222:225], v[70:73]
	v_mfma_f32_16x16x32_bf16 v[66:69], v[182:185], v[222:225], v[66:69]
	v_mfma_f32_16x16x32_bf16 v[118:121], v[150:153], v[194:197], v[118:121]
	v_mfma_f32_16x16x32_bf16 v[114:117], v[186:189], v[194:197], v[114:117]
	v_mfma_f32_16x16x32_bf16 v[102:105], v[150:153], v[210:213], v[102:105]
	v_mfma_f32_16x16x32_bf16 v[98:101], v[186:189], v[210:213], v[98:101]
	v_mfma_f32_16x16x32_bf16 v[86:89], v[150:153], v[218:221], v[86:89]
	v_mfma_f32_16x16x32_bf16 v[82:85], v[186:189], v[218:221], v[82:85]
	v_mfma_f32_16x16x32_bf16 v[70:73], v[150:153], v[226:229], v[70:73]
	v_mfma_f32_16x16x32_bf16 v[66:69], v[186:189], v[226:229], v[66:69]
	s_barrier
	s_setprio 0
	s_add_i32 s72, s79, s75
	s_add_i32 vcc_hi, s78, -2
	s_cmp_eq_u32 s74, vcc_hi
	s_cselect_b32 s99, s53, s24
	s_cselect_b32 s98, s52, s13
	s_add_u32 s98, s98, s92
	s_addc_u32 s99, s99, s93
	s_mov_b32 m0, s72
	s_nop 0
	global_load_lds_dwordx4 v156, s[98:99]
	ds_read_b128 v[190:193], v204 offset:49152
	ds_read_b128 v[194:197], v204 offset:50176
	ds_read_b128 v[206:209], v204 offset:51200
	ds_read_b128 v[210:213], v204 offset:52224
	ds_read_b128 v[214:217], v204 offset:53248
	ds_read_b128 v[218:221], v204 offset:54272
	ds_read_b128 v[222:225], v204 offset:55296
	ds_read_b128 v[226:229], v204 offset:56320
	s_add_i32 m0, s72, 0x2000
	s_nop 0
	global_load_lds_dwordx4 v160, s[98:99]
	s_add_i32 s72, s94, s75
	s_add_u32 s98, s98, s48
	s_addc_u32 s99, s99, 0
	s_mov_b32 m0, s72
	s_nop 0
	global_load_lds_dwordx4 v156, s[98:99]
	s_add_i32 m0, s72, 0x2000
	s_nop 0
	global_load_lds_dwordx4 v160, s[98:99]
	s_add_u32 s98, s46, 0x80
	s_addc_u32 s99, s47, 0
	s_cmp_eq_u32 s74, vcc_hi
	s_cselect_b32 s99, s55, s99
	s_cselect_b32 s98, s54, s98
	s_add_u32 s98, s98, s92
	s_addc_u32 s99, s99, s93
	s_mov_b32 m0, s22
	s_nop 0
	global_load_lds_dwordx4 v154, s[98:99]
	s_mov_b32 m0, s23
	s_nop 0
	global_load_lds_dwordx4 v158, s[98:99]
	s_waitcnt vmcnt(8) lgkmcnt(0)
	s_setprio 1
	s_barrier
	v_mfma_f32_16x16x32_bf16 v[62:65], v[130:133], v[190:193], v[62:65]
	v_mfma_f32_16x16x32_bf16 v[58:61], v[138:141], v[190:193], v[58:61]
	v_mfma_f32_16x16x32_bf16 v[46:49], v[130:133], v[206:209], v[46:49]
	v_mfma_f32_16x16x32_bf16 v[42:45], v[138:141], v[206:209], v[42:45]
	v_mfma_f32_16x16x32_bf16 v[30:33], v[130:133], v[214:217], v[30:33]
	v_mfma_f32_16x16x32_bf16 v[26:29], v[138:141], v[214:217], v[26:29]
	v_mfma_f32_16x16x32_bf16 v[14:17], v[130:133], v[222:225], v[14:17]
	v_mfma_f32_16x16x32_bf16 v[10:13], v[138:141], v[222:225], v[10:13]
	v_mfma_f32_16x16x32_bf16 v[62:65], v[134:137], v[194:197], v[62:65]
	v_mfma_f32_16x16x32_bf16 v[58:61], v[142:145], v[194:197], v[58:61]
	v_mfma_f32_16x16x32_bf16 v[46:49], v[134:137], v[210:213], v[46:49]
	v_mfma_f32_16x16x32_bf16 v[42:45], v[142:145], v[210:213], v[42:45]
	v_mfma_f32_16x16x32_bf16 v[30:33], v[134:137], v[218:221], v[30:33]
	v_mfma_f32_16x16x32_bf16 v[26:29], v[142:145], v[218:221], v[26:29]
	v_mfma_f32_16x16x32_bf16 v[14:17], v[134:137], v[226:229], v[14:17]
	v_mfma_f32_16x16x32_bf16 v[10:13], v[142:145], v[226:229], v[10:13]
	v_mfma_f32_16x16x32_bf16 v[54:57], v[146:149], v[190:193], v[54:57]
	v_mfma_f32_16x16x32_bf16 v[50:53], v[182:185], v[190:193], v[50:53]
	v_mfma_f32_16x16x32_bf16 v[38:41], v[146:149], v[206:209], v[38:41]
	v_mfma_f32_16x16x32_bf16 v[34:37], v[182:185], v[206:209], v[34:37]
	v_mfma_f32_16x16x32_bf16 v[22:25], v[146:149], v[214:217], v[22:25]
	v_mfma_f32_16x16x32_bf16 v[18:21], v[182:185], v[214:217], v[18:21]
	v_mfma_f32_16x16x32_bf16 v[6:9], v[146:149], v[222:225], v[6:9]
	v_mfma_f32_16x16x32_bf16 v[2:5], v[182:185], v[222:225], v[2:5]
	v_mfma_f32_16x16x32_bf16 v[54:57], v[150:153], v[194:197], v[54:57]
	v_mfma_f32_16x16x32_bf16 v[50:53], v[186:189], v[194:197], v[50:53]
	v_mfma_f32_16x16x32_bf16 v[38:41], v[150:153], v[210:213], v[38:41]
	v_mfma_f32_16x16x32_bf16 v[34:37], v[186:189], v[210:213], v[34:37]
	v_mfma_f32_16x16x32_bf16 v[22:25], v[150:153], v[218:221], v[22:25]
	v_mfma_f32_16x16x32_bf16 v[18:21], v[186:189], v[218:221], v[18:21]
	v_mfma_f32_16x16x32_bf16 v[6:9], v[150:153], v[226:229], v[6:9]
	v_mfma_f32_16x16x32_bf16 v[2:5], v[186:189], v[226:229], v[2:5]
	s_barrier
	s_setprio 0
	s_add_u32 s46, s46, 0x100
	s_addc_u32 s47, s47, 0
	s_add_u32 s13, s13, 0x100
	s_addc_u32 s24, s24, 0
	s_cmp_ge_u32 s78, s65
	s_mov_b32 s72, s78
	s_cbranch_scc1 .LBB0_399
; #define PG8_STAGE(bufoff, gbase, voff) do { _Pragma("unroll") for (int _i = 0; _i < 2; ++_i) \
;         __builtin_amdgcn_global_load_lds((const unsigned*)((const char*)(gbase) + (voff)[_i]), (PG8_LAS unsigned*)(lds + (bufoff) + ldsw + _i * 8192), 16, 0, 0); } while (0)
; #define PG8_LDA(dst, b, h) do { _Pragma("unroll") for (int m = 0; m < 4; ++m) _Pragma("unroll") for (int k = 0; k < 2; ++k) dst[m][k] = *(const PG8_LAS bf16x8*)(lds + PG8_SA(b, h) + aoff + m * 2048 + k * 1024); } while (0)
; #define PG8_LDB(dst, b, h) do { _Pragma("unroll") for (int n = 0; n < 2; ++n) _Pragma("unroll") for (int k = 0; k < 2; ++k) dst[n][k] = *(const PG8_LAS bf16x8*)(lds + PG8_SB(b, h) + boff + n * 2048 + k * 1024); } while (0)
; #define PG8_WAIT_V(n) asm volatile("s_waitcnt vmcnt(" #n ")" ::: "memory")
; #define PG8_WAIT_L(n) asm volatile("s_waitcnt lgkmcnt(" #n ")" ::: "memory")
; #define PG8_BAR __builtin_amdgcn_s_barrier()
; #define PG8_SCHED __builtin_amdgcn_sched_barrier(0)
; template <class Epi, class Sched, bool ALIGN_EPI = false, bool SP2 = false, bool F16 = false>
; __device__ __forceinline__ void gemm_phase(PG8_LAS unsigned char* lds, const Gemm g, const Sched& S, const Epi& E) {
;     ...
;             const bool last = (t == nt - 2);
;             const char* a1 = cA + (size_t)(t + 1) * kstep;
;             const char* a2 = last ? nA : cA + (size_t)(t + 2) * kstep; const char* b2 = last ? nB : cB + (size_t)(t + 2) * kstep;
;             const char* a3 = a2 + kstep; const char* b3 = b2 + kstep;
;             if (last && has_next) S.a_ready(nxt);
;             if constexpr (SP2) {
;             PG8_LDB(B0, 0, 0); PG8_LDB(B1, 0, 1); PG8_SCHED; PG8_LDA(At, 0, 0); PG8_STAGE(PG8_SA(1, 1), a1 + hstepA, voffA);
;             PG8_WAIT_V(8); PG8_WAIT_L(0); PG8_BAR; PG8_MMA(0, 0, At, B0); PG8_MMA(0, 1, At, B1); PG8_BAR; PG8_SCHED;
;             PG8_LDA(At, 0, 1); PG8_STAGE(PG8_SB(0, 0), b2, voffB); PG8_STAGE(PG8_SB(0, 1), b2 + hstepB, voffB); PG8_STAGE(PG8_SA(0, 0), a2, voffA);
;             PG8_WAIT_V(8); PG8_WAIT_L(0); PG8_BAR; PG8_MMA(1, 0, At, B0); PG8_MMA(1, 1, At, B1); PG8_BAR; PG8_SCHED;
.LBB0_398:
	s_add_i32 s78, s72, 2
	s_add_u32 s79, s46, 0x80
	s_addc_u32 s73, s47, 0
	s_add_i32 vcc_lo, 0, 0x10000
	s_cmp_eq_u32 s74, s72
	s_cselect_b32 s73, s55, s73
	s_cselect_b32 s72, s54, s79
	s_cselect_b32 s95, s53, s24
	s_cselect_b32 s94, s52, s13
	s_add_i32 s79, 0, 0x14000
	ds_read_b128 v[130:133], v155
	ds_read_b128 v[134:137], v155 offset:1024
	ds_read_b128 v[138:141], v155 offset:2048
	ds_read_b128 v[142:145], v155 offset:3072
	ds_read_b128 v[146:149], v157
	ds_read_b128 v[150:153], v157 offset:1024
	ds_read_b128 v[182:185], v157 offset:2048
	ds_read_b128 v[186:189], v157 offset:3072
	s_add_i32 m0, s36, 0xc000
	ds_read_b128 v[190:193], v204
	ds_read_b128 v[194:197], v204 offset:1024
	ds_read_b128 v[206:209], v204 offset:2048
	ds_read_b128 v[210:213], v204 offset:3072
	ds_read_b128 v[214:217], v204 offset:4096
	ds_read_b128 v[218:221], v204 offset:5120
	ds_read_b128 v[222:225], v204 offset:6144
	ds_read_b128 v[226:229], v204 offset:7168
	global_load_lds_dwordx4 v168, s[46:47]
	s_add_i32 m0, s36, 0xe000
	s_nop 0
	global_load_lds_dwordx4 v170, s[46:47]
	s_waitcnt vmcnt(8) lgkmcnt(0)
	s_setprio 1
	s_barrier
	v_mfma_f32_16x16x32_bf16 v[122:125], v[130:133], v[190:193], v[122:125]
	v_mfma_f32_16x16x32_bf16 v[126:129], v[138:141], v[190:193], v[126:129]
	v_mfma_f32_16x16x32_bf16 v[110:113], v[130:133], v[206:209], v[110:113]
	v_mfma_f32_16x16x32_bf16 v[106:109], v[138:141], v[206:209], v[106:109]
	v_mfma_f32_16x16x32_bf16 v[94:97], v[130:133], v[214:217], v[94:97]
	v_mfma_f32_16x16x32_bf16 v[90:93], v[138:141], v[214:217], v[90:93]
	v_mfma_f32_16x16x32_bf16 v[78:81], v[130:133], v[222:225], v[78:81]
	v_mfma_f32_16x16x32_bf16 v[74:77], v[138:141], v[222:225], v[74:77]
	v_mfma_f32_16x16x32_bf16 v[122:125], v[134:137], v[194:197], v[122:125]
	v_mfma_f32_16x16x32_bf16 v[126:129], v[142:145], v[194:197], v[126:129]
	v_mfma_f32_16x16x32_bf16 v[110:113], v[134:137], v[210:213], v[110:113]
	v_mfma_f32_16x16x32_bf16 v[106:109], v[142:145], v[210:213], v[106:109]
	v_mfma_f32_16x16x32_bf16 v[94:97], v[134:137], v[218:221], v[94:97]
	v_mfma_f32_16x16x32_bf16 v[90:93], v[142:145], v[218:221], v[90:93]
	v_mfma_f32_16x16x32_bf16 v[78:81], v[134:137], v[226:229], v[78:81]
	v_mfma_f32_16x16x32_bf16 v[74:77], v[142:145], v[226:229], v[74:77]
	v_mfma_f32_16x16x32_bf16 v[118:121], v[146:149], v[190:193], v[118:121]
	v_mfma_f32_16x16x32_bf16 v[114:117], v[182:185], v[190:193], v[114:117]
	v_mfma_f32_16x16x32_bf16 v[102:105], v[146:149], v[206:209], v[102:105]
	v_mfma_f32_16x16x32_bf16 v[98:101], v[182:185], v[206:209], v[98:101]
	v_mfma_f32_16x16x32_bf16 v[86:89], v[146:149], v[214:217], v[86:89]
	v_mfma_f32_16x16x32_bf16 v[82:85], v[182:185], v[214:217], v[82:85]
	v_mfma_f32_16x16x32_bf16 v[70:73], v[146:149], v[222:225], v[70:73]
	v_mfma_f32_16x16x32_bf16 v[66:69], v[182:185], v[222:225], v[66:69]
	v_mfma_f32_16x16x32_bf16 v[118:121], v[150:153], v[194:197], v[118:121]
	v_mfma_f32_16x16x32_bf16 v[114:117], v[186:189], v[194:197], v[114:117]
	v_mfma_f32_16x16x32_bf16 v[102:105], v[150:153], v[210:213], v[102:105]
	v_mfma_f32_16x16x32_bf16 v[98:101], v[186:189], v[210:213], v[98:101]
	v_mfma_f32_16x16x32_bf16 v[86:89], v[150:153], v[218:221], v[86:89]
	v_mfma_f32_16x16x32_bf16 v[82:85], v[186:189], v[218:221], v[82:85]
	v_mfma_f32_16x16x32_bf16 v[70:73], v[150:153], v[226:229], v[70:73]
	v_mfma_f32_16x16x32_bf16 v[66:69], v[186:189], v[226:229], v[66:69]
	s_barrier
	s_setprio 0
	s_add_i32 vcc_lo, vcc_lo, s75
	s_mov_b32 m0, vcc_lo
	s_nop 0
	global_load_lds_dwordx4 v156, s[94:95]
	ds_read_b128 v[190:193], v204 offset:16384
	ds_read_b128 v[194:197], v204 offset:17408
	ds_read_b128 v[206:209], v204 offset:18432
	ds_read_b128 v[210:213], v204 offset:19456
	ds_read_b128 v[214:217], v204 offset:20480
	ds_read_b128 v[218:221], v204 offset:21504
	ds_read_b128 v[222:225], v204 offset:22528
	ds_read_b128 v[226:229], v204 offset:23552
	s_add_i32 m0, vcc_lo, 0x2000
	s_nop 0
	global_load_lds_dwordx4 v160, s[94:95]
	s_add_i32 s79, s79, s75
	s_add_u32 s94, s94, s48
	s_addc_u32 s95, s95, 0
	s_mov_b32 m0, s79
	s_nop 0
	global_load_lds_dwordx4 v156, s[94:95]
	s_add_i32 m0, s79, 0x2000
	s_nop 0
	global_load_lds_dwordx4 v160, s[94:95]
	s_mov_b32 m0, s36
	s_nop 0
	global_load_lds_dwordx4 v154, s[72:73]
	s_mov_b32 m0, s37
	s_nop 0
	global_load_lds_dwordx4 v158, s[72:73]
	s_waitcnt vmcnt(8) lgkmcnt(0)
	s_setprio 1
	s_barrier
	v_mfma_f32_16x16x32_bf16 v[62:65], v[130:133], v[190:193], v[62:65]
	v_mfma_f32_16x16x32_bf16 v[58:61], v[138:141], v[190:193], v[58:61]
	v_mfma_f32_16x16x32_bf16 v[46:49], v[130:133], v[206:209], v[46:49]
	v_mfma_f32_16x16x32_bf16 v[42:45], v[138:141], v[206:209], v[42:45]
	v_mfma_f32_16x16x32_bf16 v[30:33], v[130:133], v[214:217], v[30:33]
	v_mfma_f32_16x16x32_bf16 v[26:29], v[138:141], v[214:217], v[26:29]
	v_mfma_f32_16x16x32_bf16 v[14:17], v[130:133], v[222:225], v[14:17]
	v_mfma_f32_16x16x32_bf16 v[10:13], v[138:141], v[222:225], v[10:13]
	v_mfma_f32_16x16x32_bf16 v[62:65], v[134:137], v[194:197], v[62:65]
	v_mfma_f32_16x16x32_bf16 v[58:61], v[142:145], v[194:197], v[58:61]
	v_mfma_f32_16x16x32_bf16 v[46:49], v[134:137], v[210:213], v[46:49]
	v_mfma_f32_16x16x32_bf16 v[42:45], v[142:145], v[210:213], v[42:45]
	v_mfma_f32_16x16x32_bf16 v[30:33], v[134:137], v[218:221], v[30:33]
	v_mfma_f32_16x16x32_bf16 v[26:29], v[142:145], v[218:221], v[26:29]
	v_mfma_f32_16x16x32_bf16 v[14:17], v[134:137], v[226:229], v[14:17]
	v_mfma_f32_16x16x32_bf16 v[10:13], v[142:145], v[226:229], v[10:13]
	v_mfma_f32_16x16x32_bf16 v[54:57], v[146:149], v[190:193], v[54:57]
	v_mfma_f32_16x16x32_bf16 v[50:53], v[182:185], v[190:193], v[50:53]
	v_mfma_f32_16x16x32_bf16 v[38:41], v[146:149], v[206:209], v[38:41]
	v_mfma_f32_16x16x32_bf16 v[34:37], v[182:185], v[206:209], v[34:37]
	v_mfma_f32_16x16x32_bf16 v[22:25], v[146:149], v[214:217], v[22:25]
	v_mfma_f32_16x16x32_bf16 v[18:21], v[182:185], v[214:217], v[18:21]
	v_mfma_f32_16x16x32_bf16 v[6:9], v[146:149], v[222:225], v[6:9]
	v_mfma_f32_16x16x32_bf16 v[2:5], v[182:185], v[222:225], v[2:5]
	v_mfma_f32_16x16x32_bf16 v[54:57], v[150:153], v[194:197], v[54:57]
	v_mfma_f32_16x16x32_bf16 v[50:53], v[186:189], v[194:197], v[50:53]
	v_mfma_f32_16x16x32_bf16 v[38:41], v[150:153], v[210:213], v[38:41]
	v_mfma_f32_16x16x32_bf16 v[34:37], v[186:189], v[210:213], v[34:37]
	v_mfma_f32_16x16x32_bf16 v[22:25], v[150:153], v[218:221], v[22:25]
	v_mfma_f32_16x16x32_bf16 v[18:21], v[186:189], v[218:221], v[18:21]
	v_mfma_f32_16x16x32_bf16 v[6:9], v[150:153], v[226:229], v[6:9]
	v_mfma_f32_16x16x32_bf16 v[2:5], v[186:189], v[226:229], v[2:5]
	s_barrier
; #define PG8_STAGE(bufoff, gbase, voff) do { _Pragma("unroll") for (int _i = 0; _i < 2; ++_i) \
;         __builtin_amdgcn_global_load_lds((const unsigned*)((const char*)(gbase) + (voff)[_i]), (PG8_LAS unsigned*)(lds + (bufoff) + ldsw + _i * 8192), 16, 0, 0); } while (0)
; #define PG8_LDA(dst, b, h) do { _Pragma("unroll") for (int m = 0; m < 4; ++m) _Pragma("unroll") for (int k = 0; k < 2; ++k) dst[m][k] = *(const PG8_LAS bf16x8*)(lds + PG8_SA(b, h) + aoff + m * 2048 + k * 1024); } while (0)
; #define PG8_LDB(dst, b, h) do { _Pragma("unroll") for (int n = 0; n < 2; ++n) _Pragma("unroll") for (int k = 0; k < 2; ++k) dst[n][k] = *(const PG8_LAS bf16x8*)(lds + PG8_SB(b, h) + boff + n * 2048 + k * 1024); } while (0)
; #define PG8_WAIT_V(n) asm volatile("s_waitcnt vmcnt(" #n ")" ::: "memory")
; #define PG8_WAIT_L(n) asm volatile("s_waitcnt lgkmcnt(" #n ")" ::: "memory")
; #define PG8_BAR __builtin_amdgcn_s_barrier()
; #define PG8_SCHED __builtin_amdgcn_sched_barrier(0)
; template <class Epi, class Sched, bool ALIGN_EPI = false, bool SP2 = false, bool F16 = false>
; __device__ __forceinline__ void gemm_phase(PG8_LAS unsigned char* lds, const Gemm g, const Sched& S, const Epi& E) {
;     ...
;         for (int t = 0; t < nt; t += 2) {
;             const bool last = (t == nt - 2);
;             const char* a1 = cA + (size_t)(t + 1) * kstep;
;             const char* a2 = last ? nA : cA + (size_t)(t + 2) * kstep; const char* b2 = last ? nB : cB + (size_t)(t + 2) * kstep;
;             const char* a3 = a2 + kstep; const char* b3 = b2 + kstep;
;     ...
;             PG8_LDB(B0, 1, 0); PG8_LDB(B1, 1, 1); PG8_SCHED; PG8_LDA(At, 1, 0); PG8_STAGE(PG8_SA(0, 1), a2 + hstepA, voffA);
;             PG8_WAIT_V(8); PG8_WAIT_L(0); PG8_BAR; PG8_MMA(0, 0, At, B0); PG8_MMA(0, 1, At, B1); PG8_BAR; PG8_SCHED;
;             PG8_LDA(At, 1, 1); PG8_STAGE(PG8_SB(1, 0), b3, voffB); PG8_STAGE(PG8_SB(1, 1), b3 + hstepB, voffB); PG8_STAGE(PG8_SA(1, 0), a3, voffA);
;             PG8_WAIT_V(8); PG8_WAIT_L(0); PG8_BAR; PG8_MMA(1, 0, At, B0); PG8_MMA(1, 1, At, B1); PG8_BAR; PG8_SCHED;
	s_setprio 0
	s_add_i32 s79, 0, 0x18000
	s_add_i32 s94, 0, 0x1c000
	ds_read_b128 v[130:133], v159
	ds_read_b128 v[134:137], v159 offset:1024
	ds_read_b128 v[138:141], v159 offset:2048
	ds_read_b128 v[142:145], v159 offset:3072
	ds_read_b128 v[146:149], v161
	ds_read_b128 v[150:153], v161 offset:1024
	ds_read_b128 v[182:185], v161 offset:2048
	ds_read_b128 v[186:189], v161 offset:3072
	s_add_u32 s72, s72, s8
	s_addc_u32 s73, s73, 0
	s_mov_b32 m0, s35
	ds_read_b128 v[190:193], v204 offset:32768
	ds_read_b128 v[194:197], v204 offset:33792
	ds_read_b128 v[206:209], v204 offset:34816
	ds_read_b128 v[210:213], v204 offset:35840
	ds_read_b128 v[214:217], v204 offset:36864
	ds_read_b128 v[218:221], v204 offset:37888
	ds_read_b128 v[222:225], v204 offset:38912
	ds_read_b128 v[226:229], v204 offset:39936
	global_load_lds_dwordx4 v154, s[72:73]
	s_mov_b32 m0, s2
	s_nop 0
	global_load_lds_dwordx4 v158, s[72:73]
	s_waitcnt vmcnt(8) lgkmcnt(0)
	s_setprio 1
	s_barrier
	v_mfma_f32_16x16x32_bf16 v[122:125], v[130:133], v[190:193], v[122:125]
	v_mfma_f32_16x16x32_bf16 v[126:129], v[138:141], v[190:193], v[126:129]
	v_mfma_f32_16x16x32_bf16 v[110:113], v[130:133], v[206:209], v[110:113]
	v_mfma_f32_16x16x32_bf16 v[106:109], v[138:141], v[206:209], v[106:109]
	v_mfma_f32_16x16x32_bf16 v[94:97], v[130:133], v[214:217], v[94:97]
	v_mfma_f32_16x16x32_bf16 v[90:93], v[138:141], v[214:217], v[90:93]
	v_mfma_f32_16x16x32_bf16 v[78:81], v[130:133], v[222:225], v[78:81]
	v_mfma_f32_16x16x32_bf16 v[74:77], v[138:141], v[222:225], v[74:77]
	v_mfma_f32_16x16x32_bf16 v[122:125], v[134:137], v[194:197], v[122:125]
	v_mfma_f32_16x16x32_bf16 v[126:129], v[142:145], v[194:197], v[126:129]
	v_mfma_f32_16x16x32_bf16 v[110:113], v[134:137], v[210:213], v[110:113]
	v_mfma_f32_16x16x32_bf16 v[106:109], v[142:145], v[210:213], v[106:109]
	v_mfma_f32_16x16x32_bf16 v[94:97], v[134:137], v[218:221], v[94:97]
	v_mfma_f32_16x16x32_bf16 v[90:93], v[142:145], v[218:221], v[90:93]
	v_mfma_f32_16x16x32_bf16 v[78:81], v[134:137], v[226:229], v[78:81]
	v_mfma_f32_16x16x32_bf16 v[74:77], v[142:145], v[226:229], v[74:77]
	v_mfma_f32_16x16x32_bf16 v[118:121], v[146:149], v[190:193], v[118:121]
	v_mfma_f32_16x16x32_bf16 v[114:117], v[182:185], v[190:193], v[114:117]
	v_mfma_f32_16x16x32_bf16 v[102:105], v[146:149], v[206:209], v[102:105]
	v_mfma_f32_16x16x32_bf16 v[98:101], v[182:185], v[206:209], v[98:101]
	v_mfma_f32_16x16x32_bf16 v[86:89], v[146:149], v[214:217], v[86:89]
	v_mfma_f32_16x16x32_bf16 v[82:85], v[182:185], v[214:217], v[82:85]
	v_mfma_f32_16x16x32_bf16 v[70:73], v[146:149], v[222:225], v[70:73]
	v_mfma_f32_16x16x32_bf16 v[66:69], v[182:185], v[222:225], v[66:69]
	v_mfma_f32_16x16x32_bf16 v[118:121], v[150:153], v[194:197], v[118:121]
	v_mfma_f32_16x16x32_bf16 v[114:117], v[186:189], v[194:197], v[114:117]
	v_mfma_f32_16x16x32_bf16 v[102:105], v[150:153], v[210:213], v[102:105]
	v_mfma_f32_16x16x32_bf16 v[98:101], v[186:189], v[210:213], v[98:101]
	v_mfma_f32_16x16x32_bf16 v[86:89], v[150:153], v[218:221], v[86:89]
	v_mfma_f32_16x16x32_bf16 v[82:85], v[186:189], v[218:221], v[82:85]
	v_mfma_f32_16x16x32_bf16 v[70:73], v[150:153], v[226:229], v[70:73]
	v_mfma_f32_16x16x32_bf16 v[66:69], v[186:189], v[226:229], v[66:69]
	s_barrier
	s_setprio 0
	s_add_i32 s72, s79, s75
	s_add_i32 vcc_hi, s78, -2
	s_cmp_eq_u32 s74, vcc_hi
	s_cselect_b32 s99, s53, s24
	s_cselect_b32 s98, s52, s13
	s_add_u32 s98, s98, s92
	s_addc_u32 s99, s99, s93
	s_mov_b32 m0, s72
	s_nop 0
	global_load_lds_dwordx4 v156, s[98:99]
	ds_read_b128 v[190:193], v204 offset:49152
	ds_read_b128 v[194:197], v204 offset:50176
	ds_read_b128 v[206:209], v204 offset:51200
	ds_read_b128 v[210:213], v204 offset:52224
	ds_read_b128 v[214:217], v204 offset:53248
	ds_read_b128 v[218:221], v204 offset:54272
	ds_read_b128 v[222:225], v204 offset:55296
	ds_read_b128 v[226:229], v204 offset:56320
	s_add_i32 m0, s72, 0x2000
	s_nop 0
	global_load_lds_dwordx4 v160, s[98:99]
	s_add_i32 s72, s94, s75
	s_add_u32 s98, s98, s48
	s_addc_u32 s99, s99, 0
	s_mov_b32 m0, s72
	s_nop 0
	global_load_lds_dwordx4 v156, s[98:99]
	s_add_i32 m0, s72, 0x2000
	s_nop 0
	global_load_lds_dwordx4 v160, s[98:99]
	s_add_u32 s98, s46, 0x80
	s_addc_u32 s99, s47, 0
	s_cmp_eq_u32 s74, vcc_hi
	s_cselect_b32 s99, s55, s99
	s_cselect_b32 s98, s54, s98
	s_add_u32 s98, s98, s92
	s_addc_u32 s99, s99, s93
	s_mov_b32 m0, s22
	s_nop 0
	global_load_lds_dwordx4 v154, s[98:99]
	s_mov_b32 m0, s23
	s_nop 0
	global_load_lds_dwordx4 v158, s[98:99]
	s_waitcnt vmcnt(8) lgkmcnt(0)
	s_setprio 1
	s_barrier
	v_mfma_f32_16x16x32_bf16 v[62:65], v[130:133], v[190:193], v[62:65]
	v_mfma_f32_16x16x32_bf16 v[58:61], v[138:141], v[190:193], v[58:61]
	v_mfma_f32_16x16x32_bf16 v[46:49], v[130:133], v[206:209], v[46:49]
	v_mfma_f32_16x16x32_bf16 v[42:45], v[138:141], v[206:209], v[42:45]
	v_mfma_f32_16x16x32_bf16 v[30:33], v[130:133], v[214:217], v[30:33]
	v_mfma_f32_16x16x32_bf16 v[26:29], v[138:141], v[214:217], v[26:29]
	v_mfma_f32_16x16x32_bf16 v[14:17], v[130:133], v[222:225], v[14:17]
	v_mfma_f32_16x16x32_bf16 v[10:13], v[138:141], v[222:225], v[10:13]
	v_mfma_f32_16x16x32_bf16 v[62:65], v[134:137], v[194:197], v[62:65]
	v_mfma_f32_16x16x32_bf16 v[58:61], v[142:145], v[194:197], v[58:61]
	v_mfma_f32_16x16x32_bf16 v[46:49], v[134:137], v[210:213], v[46:49]
	v_mfma_f32_16x16x32_bf16 v[42:45], v[142:145], v[210:213], v[42:45]
	v_mfma_f32_16x16x32_bf16 v[30:33], v[134:137], v[218:221], v[30:33]
	v_mfma_f32_16x16x32_bf16 v[26:29], v[142:145], v[218:221], v[26:29]
	v_mfma_f32_16x16x32_bf16 v[14:17], v[134:137], v[226:229], v[14:17]
	v_mfma_f32_16x16x32_bf16 v[10:13], v[142:145], v[226:229], v[10:13]
	v_mfma_f32_16x16x32_bf16 v[54:57], v[146:149], v[190:193], v[54:57]
	v_mfma_f32_16x16x32_bf16 v[50:53], v[182:185], v[190:193], v[50:53]
	v_mfma_f32_16x16x32_bf16 v[38:41], v[146:149], v[206:209], v[38:41]
	v_mfma_f32_16x16x32_bf16 v[34:37], v[182:185], v[206:209], v[34:37]
	v_mfma_f32_16x16x32_bf16 v[22:25], v[146:149], v[214:217], v[22:25]
	v_mfma_f32_16x16x32_bf16 v[18:21], v[182:185], v[214:217], v[18:21]
	v_mfma_f32_16x16x32_bf16 v[6:9], v[146:149], v[222:225], v[6:9]
	v_mfma_f32_16x16x32_bf16 v[2:5], v[182:185], v[222:225], v[2:5]
	v_mfma_f32_16x16x32_bf16 v[54:57], v[150:153], v[194:197], v[54:57]
	v_mfma_f32_16x16x32_bf16 v[50:53], v[186:189], v[194:197], v[50:53]
	v_mfma_f32_16x16x32_bf16 v[38:41], v[150:153], v[210:213], v[38:41]
	v_mfma_f32_16x16x32_bf16 v[34:37], v[186:189], v[210:213], v[34:37]
	v_mfma_f32_16x16x32_bf16 v[22:25], v[150:153], v[218:221], v[22:25]
	v_mfma_f32_16x16x32_bf16 v[18:21], v[186:189], v[218:221], v[18:21]
	v_mfma_f32_16x16x32_bf16 v[6:9], v[150:153], v[226:229], v[6:9]
	v_mfma_f32_16x16x32_bf16 v[2:5], v[186:189], v[226:229], v[2:5]
	s_barrier
	s_setprio 0
	s_add_u32 s46, s46, 0x100
	s_addc_u32 s47, s47, 0
	s_add_u32 s13, s13, 0x100
	s_addc_u32 s24, s24, 0
	s_cmp_ge_u32 s78, s65
	s_mov_b32 s72, s78
	s_cbranch_scc0 .LBB0_398

; #define PG8_STAGE(bufoff, gbase, voff) do { _Pragma("unroll") for (int _i = 0; _i < 2; ++_i) \
;         __builtin_amdgcn_global_load_lds((const unsigned*)((const char*)(gbase) + (voff)[_i]), (PG8_LAS unsigned*)(lds + (bufoff) + ldsw + _i * 8192), 16, 0, 0); } while (0)
; #define PG8_LDA(dst, b, h) do { _Pragma("unroll") for (int m = 0; m < 4; ++m) _Pragma("unroll") for (int k = 0; k < 2; ++k) dst[m][k] = *(const PG8_LAS bf16x8*)(lds + PG8_SA(b, h) + aoff + m * 2048 + k * 1024); } while (0)
; #define PG8_LDB(dst, b, h) do { _Pragma("unroll") for (int n = 0; n < 2; ++n) _Pragma("unroll") for (int k = 0; k < 2; ++k) dst[n][k] = *(const PG8_LAS bf16x8*)(lds + PG8_SB(b, h) + boff + n * 2048 + k * 1024); } while (0)
; #define PG8_WAIT_V(n) asm volatile("s_waitcnt vmcnt(" #n ")" ::: "memory")
; #define PG8_WAIT_L(n) asm volatile("s_waitcnt lgkmcnt(" #n ")" ::: "memory")
; #define PG8_BAR __builtin_amdgcn_s_barrier()
; #define PG8_SCHED __builtin_amdgcn_sched_barrier(0)
; template <class Epi, class Sched, bool ALIGN_EPI = false, bool SP2 = false, bool F16 = false>
; __device__ __forceinline__ void gemm_phase(PG8_LAS unsigned char* lds, const Gemm g, const Sched& S, const Epi& E) {
;     ...
;         for (int t = 0; t < nt; t += 2) {
;             const bool last = (t == nt - 2);
;             const char* a1 = cA + (size_t)(t + 1) * kstep;
;             const char* a2 = last ? nA : cA + (size_t)(t + 2) * kstep; const char* b2 = last ? nB : cB + (size_t)(t + 2) * kstep;
;             const char* a3 = a2 + kstep; const char* b3 = b2 + kstep;
;             if (last && has_next) S.a_ready(nxt);
;             if constexpr (SP2) {
;             PG8_LDB(B0, 0, 0); PG8_LDB(B1, 0, 1); PG8_SCHED; PG8_LDA(At, 0, 0); PG8_STAGE(PG8_SA(1, 1), a1 + hstepA, voffA);
;             PG8_WAIT_V(8); PG8_WAIT_L(0); PG8_BAR; PG8_MMA(0, 0, At, B0); PG8_MMA(0, 1, At, B1); PG8_BAR; PG8_SCHED;
;             PG8_LDA(At, 0, 1); PG8_STAGE(PG8_SB(0, 0), b2, voffB); PG8_STAGE(PG8_SB(0, 1), b2 + hstepB, voffB); PG8_STAGE(PG8_SA(0, 0), a2, voffA);
;             PG8_WAIT_V(8); PG8_WAIT_L(0); PG8_BAR; PG8_MMA(1, 0, At, B0); PG8_MMA(1, 1, At, B1); PG8_BAR; PG8_SCHED;
.Lpk_bh:
	s_add_i32 s73, s52, 2
	s_add_u32 s82, s44, 0x80
	s_addc_u32 s53, s45, 0
	s_add_i32 s94, 0, 0x10000
	s_cmp_eq_u32 s74, s52
	s_cselect_b32 s53, s79, s53
	s_cselect_b32 s52, s78, s82
	s_cselect_b32 s83, s55, s72
	s_cselect_b32 s82, s54, s24
	s_add_i32 s95, 0, 0x14000
	ds_read_b128 v[130:133], v155
	ds_read_b128 v[134:137], v155 offset:1024
	ds_read_b128 v[138:141], v155 offset:2048
	ds_read_b128 v[142:145], v155 offset:3072
	ds_read_b128 v[146:149], v157
	ds_read_b128 v[150:153], v157 offset:1024
	ds_read_b128 v[182:185], v157 offset:2048
	ds_read_b128 v[186:189], v157 offset:3072
	s_add_i32 m0, s35, 0xc000
	ds_read_b128 v[190:193], v204
	ds_read_b128 v[194:197], v204 offset:1024
	ds_read_b128 v[206:209], v204 offset:2048
	ds_read_b128 v[210:213], v204 offset:3072
	ds_read_b128 v[214:217], v204 offset:4096
	ds_read_b128 v[218:221], v204 offset:5120
	ds_read_b128 v[222:225], v204 offset:6144
	ds_read_b128 v[226:229], v204 offset:7168
	global_load_lds_dwordx4 v168, s[44:45]
	s_add_i32 m0, s35, 0xe000
	s_nop 0
	global_load_lds_dwordx4 v170, s[44:45]
	s_waitcnt vmcnt(8) lgkmcnt(0)
	s_setprio 1
	s_barrier
	v_mfma_f32_16x16x32_f16 v[122:125], v[130:133], v[190:193], 0
	v_mfma_f32_16x16x32_f16 v[126:129], v[138:141], v[190:193], 0
	v_mfma_f32_16x16x32_f16 v[110:113], v[130:133], v[206:209], 0
	v_mfma_f32_16x16x32_f16 v[106:109], v[138:141], v[206:209], 0
	v_mfma_f32_16x16x32_f16 v[94:97], v[130:133], v[214:217], 0
	v_mfma_f32_16x16x32_f16 v[90:93], v[138:141], v[214:217], 0
	v_mfma_f32_16x16x32_f16 v[78:81], v[130:133], v[222:225], 0
	v_mfma_f32_16x16x32_f16 v[74:77], v[138:141], v[222:225], 0
	v_mfma_f32_16x16x32_f16 v[122:125], v[134:137], v[194:197], v[122:125]
	v_mfma_f32_16x16x32_f16 v[126:129], v[142:145], v[194:197], v[126:129]
	v_mfma_f32_16x16x32_f16 v[110:113], v[134:137], v[210:213], v[110:113]
	v_mfma_f32_16x16x32_f16 v[106:109], v[142:145], v[210:213], v[106:109]
	v_mfma_f32_16x16x32_f16 v[94:97], v[134:137], v[218:221], v[94:97]
	v_mfma_f32_16x16x32_f16 v[90:93], v[142:145], v[218:221], v[90:93]
	v_mfma_f32_16x16x32_f16 v[78:81], v[134:137], v[226:229], v[78:81]
	v_mfma_f32_16x16x32_f16 v[74:77], v[142:145], v[226:229], v[74:77]
	v_mfma_f32_16x16x32_f16 v[118:121], v[146:149], v[190:193], 0
	v_mfma_f32_16x16x32_f16 v[114:117], v[182:185], v[190:193], 0
	v_mfma_f32_16x16x32_f16 v[102:105], v[146:149], v[206:209], 0
	v_mfma_f32_16x16x32_f16 v[98:101], v[182:185], v[206:209], 0
	v_mfma_f32_16x16x32_f16 v[86:89], v[146:149], v[214:217], 0
	v_mfma_f32_16x16x32_f16 v[82:85], v[182:185], v[214:217], 0
	v_mfma_f32_16x16x32_f16 v[70:73], v[146:149], v[222:225], 0
	v_mfma_f32_16x16x32_f16 v[66:69], v[182:185], v[222:225], 0
	v_mfma_f32_16x16x32_f16 v[118:121], v[150:153], v[194:197], v[118:121]
	v_mfma_f32_16x16x32_f16 v[114:117], v[186:189], v[194:197], v[114:117]
	v_mfma_f32_16x16x32_f16 v[102:105], v[150:153], v[210:213], v[102:105]
	v_mfma_f32_16x16x32_f16 v[98:101], v[186:189], v[210:213], v[98:101]
	v_mfma_f32_16x16x32_f16 v[86:89], v[150:153], v[218:221], v[86:89]
	v_mfma_f32_16x16x32_f16 v[82:85], v[186:189], v[218:221], v[82:85]
	v_mfma_f32_16x16x32_f16 v[70:73], v[150:153], v[226:229], v[70:73]
	v_mfma_f32_16x16x32_f16 v[66:69], v[186:189], v[226:229], v[66:69]
	s_barrier
	s_setprio 0
	s_add_i32 s94, s94, s75
	s_mov_b32 m0, s94
	s_nop 0
	global_load_lds_dwordx4 v156, s[82:83]
	ds_read_b128 v[190:193], v204 offset:16384
	ds_read_b128 v[194:197], v204 offset:17408
	ds_read_b128 v[206:209], v204 offset:18432
	ds_read_b128 v[210:213], v204 offset:19456
	ds_read_b128 v[214:217], v204 offset:20480
	ds_read_b128 v[218:221], v204 offset:21504
	ds_read_b128 v[222:225], v204 offset:22528
	ds_read_b128 v[226:229], v204 offset:23552
	s_add_i32 m0, s94, 0x2000
	s_nop 0
	global_load_lds_dwordx4 v160, s[82:83]
	s_add_i32 s94, s95, s75
	s_add_u32 s82, s82, s48
	s_addc_u32 s83, s83, 0
	s_mov_b32 m0, s94
	s_nop 0
	global_load_lds_dwordx4 v156, s[82:83]
	s_add_i32 m0, s94, 0x2000
	s_nop 0
	global_load_lds_dwordx4 v160, s[82:83]
	s_mov_b32 m0, s35
	s_nop 0
	global_load_lds_dwordx4 v154, s[52:53]
	s_mov_b32 m0, s2
	s_nop 0
	global_load_lds_dwordx4 v158, s[52:53]
	s_waitcnt vmcnt(8) lgkmcnt(0)
	s_setprio 1
	s_barrier
	v_mfma_f32_16x16x32_f16 v[62:65], v[130:133], v[190:193], 0
	v_mfma_f32_16x16x32_f16 v[58:61], v[138:141], v[190:193], 0
	v_mfma_f32_16x16x32_f16 v[46:49], v[130:133], v[206:209], 0
	v_mfma_f32_16x16x32_f16 v[42:45], v[138:141], v[206:209], 0
	v_mfma_f32_16x16x32_f16 v[30:33], v[130:133], v[214:217], 0
	v_mfma_f32_16x16x32_f16 v[26:29], v[138:141], v[214:217], 0
	v_mfma_f32_16x16x32_f16 v[14:17], v[130:133], v[222:225], 0
	v_mfma_f32_16x16x32_f16 v[10:13], v[138:141], v[222:225], 0
	v_mfma_f32_16x16x32_f16 v[62:65], v[134:137], v[194:197], v[62:65]
	v_mfma_f32_16x16x32_f16 v[58:61], v[142:145], v[194:197], v[58:61]
	v_mfma_f32_16x16x32_f16 v[46:49], v[134:137], v[210:213], v[46:49]
	v_mfma_f32_16x16x32_f16 v[42:45], v[142:145], v[210:213], v[42:45]
	v_mfma_f32_16x16x32_f16 v[30:33], v[134:137], v[218:221], v[30:33]
	v_mfma_f32_16x16x32_f16 v[26:29], v[142:145], v[218:221], v[26:29]
	v_mfma_f32_16x16x32_f16 v[14:17], v[134:137], v[226:229], v[14:17]
	v_mfma_f32_16x16x32_f16 v[10:13], v[142:145], v[226:229], v[10:13]
	v_mfma_f32_16x16x32_f16 v[54:57], v[146:149], v[190:193], 0
	v_mfma_f32_16x16x32_f16 v[50:53], v[182:185], v[190:193], 0
	v_mfma_f32_16x16x32_f16 v[38:41], v[146:149], v[206:209], 0
	v_mfma_f32_16x16x32_f16 v[34:37], v[182:185], v[206:209], 0
	v_mfma_f32_16x16x32_f16 v[22:25], v[146:149], v[214:217], 0
	v_mfma_f32_16x16x32_f16 v[18:21], v[182:185], v[214:217], 0
	v_mfma_f32_16x16x32_f16 v[6:9], v[146:149], v[222:225], 0
	v_mfma_f32_16x16x32_f16 v[2:5], v[182:185], v[222:225], 0
	v_mfma_f32_16x16x32_f16 v[54:57], v[150:153], v[194:197], v[54:57]
	v_mfma_f32_16x16x32_f16 v[50:53], v[186:189], v[194:197], v[50:53]
	v_mfma_f32_16x16x32_f16 v[38:41], v[150:153], v[210:213], v[38:41]
	v_mfma_f32_16x16x32_f16 v[34:37], v[186:189], v[210:213], v[34:37]
	v_mfma_f32_16x16x32_f16 v[22:25], v[150:153], v[218:221], v[22:25]
	v_mfma_f32_16x16x32_f16 v[18:21], v[186:189], v[218:221], v[18:21]
	v_mfma_f32_16x16x32_f16 v[6:9], v[150:153], v[226:229], v[6:9]
	v_mfma_f32_16x16x32_f16 v[2:5], v[186:189], v[226:229], v[2:5]
	s_barrier
; #define PG8_STAGE(bufoff, gbase, voff) do { _Pragma("unroll") for (int _i = 0; _i < 2; ++_i) \
;         __builtin_amdgcn_global_load_lds((const unsigned*)((const char*)(gbase) + (voff)[_i]), (PG8_LAS unsigned*)(lds + (bufoff) + ldsw + _i * 8192), 16, 0, 0); } while (0)
; #define PG8_LDA(dst, b, h) do { _Pragma("unroll") for (int m = 0; m < 4; ++m) _Pragma("unroll") for (int k = 0; k < 2; ++k) dst[m][k] = *(const PG8_LAS bf16x8*)(lds + PG8_SA(b, h) + aoff + m * 2048 + k * 1024); } while (0)
; #define PG8_LDB(dst, b, h) do { _Pragma("unroll") for (int n = 0; n < 2; ++n) _Pragma("unroll") for (int k = 0; k < 2; ++k) dst[n][k] = *(const PG8_LAS bf16x8*)(lds + PG8_SB(b, h) + boff + n * 2048 + k * 1024); } while (0)
; #define PG8_WAIT_V(n) asm volatile("s_waitcnt vmcnt(" #n ")" ::: "memory")
; #define PG8_WAIT_L(n) asm volatile("s_waitcnt lgkmcnt(" #n ")" ::: "memory")
; #define PG8_BAR __builtin_amdgcn_s_barrier()
; #define PG8_SCHED __builtin_amdgcn_sched_barrier(0)
; template <class Epi, class Sched, bool ALIGN_EPI = false, bool SP2 = false, bool F16 = false>
; __device__ __forceinline__ void gemm_phase(PG8_LAS unsigned char* lds, const Gemm g, const Sched& S, const Epi& E) {
;     ...
;         for (int t = 0; t < nt; t += 2) {
;             const bool last = (t == nt - 2);
;             const char* a1 = cA + (size_t)(t + 1) * kstep;
;             const char* a2 = last ? nA : cA + (size_t)(t + 2) * kstep; const char* b2 = last ? nB : cB + (size_t)(t + 2) * kstep;
;             const char* a3 = a2 + kstep; const char* b3 = b2 + kstep;
;     ...
;             PG8_LDB(B0, 1, 0); PG8_LDB(B1, 1, 1); PG8_SCHED; PG8_LDA(At, 1, 0); PG8_STAGE(PG8_SA(0, 1), a2 + hstepA, voffA);
;             PG8_WAIT_V(8); PG8_WAIT_L(0); PG8_BAR; PG8_MMA(0, 0, At, B0); PG8_MMA(0, 1, At, B1); PG8_BAR; PG8_SCHED;
;             PG8_LDA(At, 1, 1); PG8_STAGE(PG8_SB(1, 0), b3, voffB); PG8_STAGE(PG8_SB(1, 1), b3 + hstepB, voffB); PG8_STAGE(PG8_SA(1, 0), a3, voffA);
;             PG8_WAIT_V(8); PG8_WAIT_L(0); PG8_BAR; PG8_MMA(1, 0, At, B0); PG8_MMA(1, 1, At, B1); PG8_BAR; PG8_SCHED;
	s_setprio 0
	s_add_i32 s82, 0, 0x18000
	s_add_i32 s83, 0, 0x1c000
	ds_read_b128 v[130:133], v159
	ds_read_b128 v[134:137], v159 offset:1024
	ds_read_b128 v[138:141], v159 offset:2048
	ds_read_b128 v[142:145], v159 offset:3072
	ds_read_b128 v[146:149], v161
	ds_read_b128 v[150:153], v161 offset:1024
	ds_read_b128 v[182:185], v161 offset:2048
	ds_read_b128 v[186:189], v161 offset:3072
	s_add_u32 s52, s52, s8
	s_addc_u32 s53, s53, 0
	s_mov_b32 m0, s22
	ds_read_b128 v[190:193], v204 offset:32768
	ds_read_b128 v[194:197], v204 offset:33792
	ds_read_b128 v[206:209], v204 offset:34816
	ds_read_b128 v[210:213], v204 offset:35840
	ds_read_b128 v[214:217], v204 offset:36864
	ds_read_b128 v[218:221], v204 offset:37888
	ds_read_b128 v[222:225], v204 offset:38912
	ds_read_b128 v[226:229], v204 offset:39936
	global_load_lds_dwordx4 v154, s[52:53]
	s_mov_b32 m0, s23
	s_nop 0
	global_load_lds_dwordx4 v158, s[52:53]
	s_waitcnt vmcnt(8) lgkmcnt(0)
	s_setprio 1
	s_barrier
	v_mfma_f32_16x16x32_f16 v[122:125], v[130:133], v[190:193], v[122:125]
	v_mfma_f32_16x16x32_f16 v[126:129], v[138:141], v[190:193], v[126:129]
	v_mfma_f32_16x16x32_f16 v[110:113], v[130:133], v[206:209], v[110:113]
	v_mfma_f32_16x16x32_f16 v[106:109], v[138:141], v[206:209], v[106:109]
	v_mfma_f32_16x16x32_f16 v[94:97], v[130:133], v[214:217], v[94:97]
	v_mfma_f32_16x16x32_f16 v[90:93], v[138:141], v[214:217], v[90:93]
	v_mfma_f32_16x16x32_f16 v[78:81], v[130:133], v[222:225], v[78:81]
	v_mfma_f32_16x16x32_f16 v[74:77], v[138:141], v[222:225], v[74:77]
	v_mfma_f32_16x16x32_f16 v[122:125], v[134:137], v[194:197], v[122:125]
	v_mfma_f32_16x16x32_f16 v[126:129], v[142:145], v[194:197], v[126:129]
	v_mfma_f32_16x16x32_f16 v[110:113], v[134:137], v[210:213], v[110:113]
	v_mfma_f32_16x16x32_f16 v[106:109], v[142:145], v[210:213], v[106:109]
	v_mfma_f32_16x16x32_f16 v[94:97], v[134:137], v[218:221], v[94:97]
	v_mfma_f32_16x16x32_f16 v[90:93], v[142:145], v[218:221], v[90:93]
	v_mfma_f32_16x16x32_f16 v[78:81], v[134:137], v[226:229], v[78:81]
	v_mfma_f32_16x16x32_f16 v[74:77], v[142:145], v[226:229], v[74:77]
	v_mfma_f32_16x16x32_f16 v[118:121], v[146:149], v[190:193], v[118:121]
	v_mfma_f32_16x16x32_f16 v[114:117], v[182:185], v[190:193], v[114:117]
	v_mfma_f32_16x16x32_f16 v[102:105], v[146:149], v[206:209], v[102:105]
	v_mfma_f32_16x16x32_f16 v[98:101], v[182:185], v[206:209], v[98:101]
	v_mfma_f32_16x16x32_f16 v[86:89], v[146:149], v[214:217], v[86:89]
	v_mfma_f32_16x16x32_f16 v[82:85], v[182:185], v[214:217], v[82:85]
	v_mfma_f32_16x16x32_f16 v[70:73], v[146:149], v[222:225], v[70:73]
	v_mfma_f32_16x16x32_f16 v[66:69], v[182:185], v[222:225], v[66:69]
	v_mfma_f32_16x16x32_f16 v[118:121], v[150:153], v[194:197], v[118:121]
	v_mfma_f32_16x16x32_f16 v[114:117], v[186:189], v[194:197], v[114:117]
	v_mfma_f32_16x16x32_f16 v[102:105], v[150:153], v[210:213], v[102:105]
	v_mfma_f32_16x16x32_f16 v[98:101], v[186:189], v[210:213], v[98:101]
	v_mfma_f32_16x16x32_f16 v[86:89], v[150:153], v[218:221], v[86:89]
	v_mfma_f32_16x16x32_f16 v[82:85], v[186:189], v[218:221], v[82:85]
	v_mfma_f32_16x16x32_f16 v[70:73], v[150:153], v[226:229], v[70:73]
	v_mfma_f32_16x16x32_f16 v[66:69], v[186:189], v[226:229], v[66:69]
	s_barrier
	s_setprio 0
	s_add_i32 s52, s82, s75
	s_add_i32 vcc_hi, s73, -2
	s_cmp_eq_u32 s74, vcc_hi
	s_cselect_b32 s99, s55, s72
	s_cselect_b32 s98, s54, s24
	s_add_u32 s98, s98, s92
	s_addc_u32 s99, s99, s93
	s_mov_b32 m0, s52
	s_nop 0
	global_load_lds_dwordx4 v156, s[98:99]
	ds_read_b128 v[190:193], v204 offset:49152
	ds_read_b128 v[194:197], v204 offset:50176
	ds_read_b128 v[206:209], v204 offset:51200
	ds_read_b128 v[210:213], v204 offset:52224
	ds_read_b128 v[214:217], v204 offset:53248
	ds_read_b128 v[218:221], v204 offset:54272
	ds_read_b128 v[222:225], v204 offset:55296
	ds_read_b128 v[226:229], v204 offset:56320
	s_add_i32 m0, s52, 0x2000
	s_nop 0
	global_load_lds_dwordx4 v160, s[98:99]
	s_add_i32 s52, s83, s75
	s_add_u32 s98, s98, s48
	s_addc_u32 s99, s99, 0
	s_mov_b32 m0, s52
	s_nop 0
	global_load_lds_dwordx4 v156, s[98:99]
	s_add_i32 m0, s52, 0x2000
	s_nop 0
	global_load_lds_dwordx4 v160, s[98:99]
	s_add_u32 s98, s44, 0x80
	s_addc_u32 s99, s45, 0
	s_cmp_eq_u32 s74, vcc_hi
	s_cselect_b32 s99, s79, s99
	s_cselect_b32 s98, s78, s98
	s_add_u32 s98, s98, s92
	s_addc_u32 s99, s99, s93
	s_mov_b32 m0, s61
	s_nop 0
	global_load_lds_dwordx4 v154, s[98:99]
	s_mov_b32 m0, s18
	s_nop 0
	global_load_lds_dwordx4 v158, s[98:99]
	s_waitcnt vmcnt(8) lgkmcnt(0)
	s_setprio 1
	s_barrier
	v_mfma_f32_16x16x32_f16 v[62:65], v[130:133], v[190:193], v[62:65]
	v_mfma_f32_16x16x32_f16 v[58:61], v[138:141], v[190:193], v[58:61]
	v_mfma_f32_16x16x32_f16 v[46:49], v[130:133], v[206:209], v[46:49]
	v_mfma_f32_16x16x32_f16 v[42:45], v[138:141], v[206:209], v[42:45]
	v_mfma_f32_16x16x32_f16 v[30:33], v[130:133], v[214:217], v[30:33]
	v_mfma_f32_16x16x32_f16 v[26:29], v[138:141], v[214:217], v[26:29]
	v_mfma_f32_16x16x32_f16 v[14:17], v[130:133], v[222:225], v[14:17]
	v_mfma_f32_16x16x32_f16 v[10:13], v[138:141], v[222:225], v[10:13]
	v_mfma_f32_16x16x32_f16 v[62:65], v[134:137], v[194:197], v[62:65]
	v_mfma_f32_16x16x32_f16 v[58:61], v[142:145], v[194:197], v[58:61]
	v_mfma_f32_16x16x32_f16 v[46:49], v[134:137], v[210:213], v[46:49]
	v_mfma_f32_16x16x32_f16 v[42:45], v[142:145], v[210:213], v[42:45]
	v_mfma_f32_16x16x32_f16 v[30:33], v[134:137], v[218:221], v[30:33]
	v_mfma_f32_16x16x32_f16 v[26:29], v[142:145], v[218:221], v[26:29]
	v_mfma_f32_16x16x32_f16 v[14:17], v[134:137], v[226:229], v[14:17]
	v_mfma_f32_16x16x32_f16 v[10:13], v[142:145], v[226:229], v[10:13]
	v_mfma_f32_16x16x32_f16 v[54:57], v[146:149], v[190:193], v[54:57]
	v_mfma_f32_16x16x32_f16 v[50:53], v[182:185], v[190:193], v[50:53]
	v_mfma_f32_16x16x32_f16 v[38:41], v[146:149], v[206:209], v[38:41]
	v_mfma_f32_16x16x32_f16 v[34:37], v[182:185], v[206:209], v[34:37]
	v_mfma_f32_16x16x32_f16 v[22:25], v[146:149], v[214:217], v[22:25]
	v_mfma_f32_16x16x32_f16 v[18:21], v[182:185], v[214:217], v[18:21]
	v_mfma_f32_16x16x32_f16 v[6:9], v[146:149], v[222:225], v[6:9]
	v_mfma_f32_16x16x32_f16 v[2:5], v[182:185], v[222:225], v[2:5]
	v_mfma_f32_16x16x32_f16 v[54:57], v[150:153], v[194:197], v[54:57]
	v_mfma_f32_16x16x32_f16 v[50:53], v[186:189], v[194:197], v[50:53]
	v_mfma_f32_16x16x32_f16 v[38:41], v[150:153], v[210:213], v[38:41]
	v_mfma_f32_16x16x32_f16 v[34:37], v[186:189], v[210:213], v[34:37]
	v_mfma_f32_16x16x32_f16 v[22:25], v[150:153], v[218:221], v[22:25]
	v_mfma_f32_16x16x32_f16 v[18:21], v[186:189], v[218:221], v[18:21]
	v_mfma_f32_16x16x32_f16 v[6:9], v[150:153], v[226:229], v[6:9]
	v_mfma_f32_16x16x32_f16 v[2:5], v[186:189], v[226:229], v[2:5]
	s_barrier
	s_setprio 0
	s_add_u32 s44, s44, 0x100
	s_addc_u32 s45, s45, 0
	s_add_u32 s24, s24, 0x100
	s_addc_u32 s72, s72, 0
	s_cmp_ge_u32 s73, s65
	s_mov_b32 s52, s73
	s_cbranch_scc1 .LBB0_565
; #define PG8_STAGE(bufoff, gbase, voff) do { _Pragma("unroll") for (int _i = 0; _i < 2; ++_i) \
;         __builtin_amdgcn_global_load_lds((const unsigned*)((const char*)(gbase) + (voff)[_i]), (PG8_LAS unsigned*)(lds + (bufoff) + ldsw + _i * 8192), 16, 0, 0); } while (0)
; #define PG8_LDA(dst, b, h) do { _Pragma("unroll") for (int m = 0; m < 4; ++m) _Pragma("unroll") for (int k = 0; k < 2; ++k) dst[m][k] = *(const PG8_LAS bf16x8*)(lds + PG8_SA(b, h) + aoff + m * 2048 + k * 1024); } while (0)
; #define PG8_LDB(dst, b, h) do { _Pragma("unroll") for (int n = 0; n < 2; ++n) _Pragma("unroll") for (int k = 0; k < 2; ++k) dst[n][k] = *(const PG8_LAS bf16x8*)(lds + PG8_SB(b, h) + boff + n * 2048 + k * 1024); } while (0)
; #define PG8_WAIT_V(n) asm volatile("s_waitcnt vmcnt(" #n ")" ::: "memory")
; #define PG8_WAIT_L(n) asm volatile("s_waitcnt lgkmcnt(" #n ")" ::: "memory")
; #define PG8_BAR __builtin_amdgcn_s_barrier()
; #define PG8_SCHED __builtin_amdgcn_sched_barrier(0)
; template <class Epi, class Sched, bool ALIGN_EPI = false, bool SP2 = false, bool F16 = false>
; __device__ __forceinline__ void gemm_phase(PG8_LAS unsigned char* lds, const Gemm g, const Sched& S, const Epi& E) {
;     ...
;             const bool last = (t == nt - 2);
;             const char* a1 = cA + (size_t)(t + 1) * kstep;
;             const char* a2 = last ? nA : cA + (size_t)(t + 2) * kstep; const char* b2 = last ? nB : cB + (size_t)(t + 2) * kstep;
;             const char* a3 = a2 + kstep; const char* b3 = b2 + kstep;
;             if (last && has_next) S.a_ready(nxt);
;             if constexpr (SP2) {
;             PG8_LDB(B0, 0, 0); PG8_LDB(B1, 0, 1); PG8_SCHED; PG8_LDA(At, 0, 0); PG8_STAGE(PG8_SA(1, 1), a1 + hstepA, voffA);
;             PG8_WAIT_V(8); PG8_WAIT_L(0); PG8_BAR; PG8_MMA(0, 0, At, B0); PG8_MMA(0, 1, At, B1); PG8_BAR; PG8_SCHED;
;             PG8_LDA(At, 0, 1); PG8_STAGE(PG8_SB(0, 0), b2, voffB); PG8_STAGE(PG8_SB(0, 1), b2 + hstepB, voffB); PG8_STAGE(PG8_SA(0, 0), a2, voffA);
;             PG8_WAIT_V(8); PG8_WAIT_L(0); PG8_BAR; PG8_MMA(1, 0, At, B0); PG8_MMA(1, 1, At, B1); PG8_BAR; PG8_SCHED;
.LBB0_564:
	s_add_i32 s73, s52, 2
	s_add_u32 s82, s44, 0x80
	s_addc_u32 s53, s45, 0
	s_add_i32 s94, 0, 0x10000
	s_cmp_eq_u32 s74, s52
	s_cselect_b32 s53, s79, s53
	s_cselect_b32 s52, s78, s82
	s_cselect_b32 s83, s55, s72
	s_cselect_b32 s82, s54, s24
	s_add_i32 s95, 0, 0x14000
	ds_read_b128 v[130:133], v155
	ds_read_b128 v[134:137], v155 offset:1024
	ds_read_b128 v[138:141], v155 offset:2048
	ds_read_b128 v[142:145], v155 offset:3072
	ds_read_b128 v[146:149], v157
	ds_read_b128 v[150:153], v157 offset:1024
	ds_read_b128 v[182:185], v157 offset:2048
	ds_read_b128 v[186:189], v157 offset:3072
	s_add_i32 m0, s35, 0xc000
	ds_read_b128 v[190:193], v204
	ds_read_b128 v[194:197], v204 offset:1024
	ds_read_b128 v[206:209], v204 offset:2048
	ds_read_b128 v[210:213], v204 offset:3072
	ds_read_b128 v[214:217], v204 offset:4096
	ds_read_b128 v[218:221], v204 offset:5120
	ds_read_b128 v[222:225], v204 offset:6144
	ds_read_b128 v[226:229], v204 offset:7168
	global_load_lds_dwordx4 v168, s[44:45]
	s_add_i32 m0, s35, 0xe000
	s_nop 0
	global_load_lds_dwordx4 v170, s[44:45]
	s_waitcnt vmcnt(8) lgkmcnt(0)
	s_setprio 1
	s_barrier
	v_mfma_f32_16x16x32_f16 v[122:125], v[130:133], v[190:193], v[122:125]
	v_mfma_f32_16x16x32_f16 v[126:129], v[138:141], v[190:193], v[126:129]
	v_mfma_f32_16x16x32_f16 v[110:113], v[130:133], v[206:209], v[110:113]
	v_mfma_f32_16x16x32_f16 v[106:109], v[138:141], v[206:209], v[106:109]
	v_mfma_f32_16x16x32_f16 v[94:97], v[130:133], v[214:217], v[94:97]
	v_mfma_f32_16x16x32_f16 v[90:93], v[138:141], v[214:217], v[90:93]
	v_mfma_f32_16x16x32_f16 v[78:81], v[130:133], v[222:225], v[78:81]
	v_mfma_f32_16x16x32_f16 v[74:77], v[138:141], v[222:225], v[74:77]
	v_mfma_f32_16x16x32_f16 v[122:125], v[134:137], v[194:197], v[122:125]
	v_mfma_f32_16x16x32_f16 v[126:129], v[142:145], v[194:197], v[126:129]
	v_mfma_f32_16x16x32_f16 v[110:113], v[134:137], v[210:213], v[110:113]
	v_mfma_f32_16x16x32_f16 v[106:109], v[142:145], v[210:213], v[106:109]
	v_mfma_f32_16x16x32_f16 v[94:97], v[134:137], v[218:221], v[94:97]
	v_mfma_f32_16x16x32_f16 v[90:93], v[142:145], v[218:221], v[90:93]
	v_mfma_f32_16x16x32_f16 v[78:81], v[134:137], v[226:229], v[78:81]
	v_mfma_f32_16x16x32_f16 v[74:77], v[142:145], v[226:229], v[74:77]
	v_mfma_f32_16x16x32_f16 v[118:121], v[146:149], v[190:193], v[118:121]
	v_mfma_f32_16x16x32_f16 v[114:117], v[182:185], v[190:193], v[114:117]
	v_mfma_f32_16x16x32_f16 v[102:105], v[146:149], v[206:209], v[102:105]
	v_mfma_f32_16x16x32_f16 v[98:101], v[182:185], v[206:209], v[98:101]
	v_mfma_f32_16x16x32_f16 v[86:89], v[146:149], v[214:217], v[86:89]
	v_mfma_f32_16x16x32_f16 v[82:85], v[182:185], v[214:217], v[82:85]
	v_mfma_f32_16x16x32_f16 v[70:73], v[146:149], v[222:225], v[70:73]
	v_mfma_f32_16x16x32_f16 v[66:69], v[182:185], v[222:225], v[66:69]
	v_mfma_f32_16x16x32_f16 v[118:121], v[150:153], v[194:197], v[118:121]
	v_mfma_f32_16x16x32_f16 v[114:117], v[186:189], v[194:197], v[114:117]
	v_mfma_f32_16x16x32_f16 v[102:105], v[150:153], v[210:213], v[102:105]
	v_mfma_f32_16x16x32_f16 v[98:101], v[186:189], v[210:213], v[98:101]
	v_mfma_f32_16x16x32_f16 v[86:89], v[150:153], v[218:221], v[86:89]
	v_mfma_f32_16x16x32_f16 v[82:85], v[186:189], v[218:221], v[82:85]
	v_mfma_f32_16x16x32_f16 v[70:73], v[150:153], v[226:229], v[70:73]
	v_mfma_f32_16x16x32_f16 v[66:69], v[186:189], v[226:229], v[66:69]
	s_barrier
	s_setprio 0
	s_add_i32 s94, s94, s75
	s_mov_b32 m0, s94
	s_nop 0
	global_load_lds_dwordx4 v156, s[82:83]
	ds_read_b128 v[190:193], v204 offset:16384
	ds_read_b128 v[194:197], v204 offset:17408
	ds_read_b128 v[206:209], v204 offset:18432
	ds_read_b128 v[210:213], v204 offset:19456
	ds_read_b128 v[214:217], v204 offset:20480
	ds_read_b128 v[218:221], v204 offset:21504
	ds_read_b128 v[222:225], v204 offset:22528
	ds_read_b128 v[226:229], v204 offset:23552
	s_add_i32 m0, s94, 0x2000
	s_nop 0
	global_load_lds_dwordx4 v160, s[82:83]
	s_add_i32 s94, s95, s75
	s_add_u32 s82, s82, s48
	s_addc_u32 s83, s83, 0
	s_mov_b32 m0, s94
	s_nop 0
	global_load_lds_dwordx4 v156, s[82:83]
	s_add_i32 m0, s94, 0x2000
	s_nop 0
	global_load_lds_dwordx4 v160, s[82:83]
	s_mov_b32 m0, s35
	s_nop 0
	global_load_lds_dwordx4 v154, s[52:53]
	s_mov_b32 m0, s2
	s_nop 0
	global_load_lds_dwordx4 v158, s[52:53]
	s_waitcnt vmcnt(8) lgkmcnt(0)
	s_setprio 1
	s_barrier
	v_mfma_f32_16x16x32_f16 v[62:65], v[130:133], v[190:193], v[62:65]
	v_mfma_f32_16x16x32_f16 v[58:61], v[138:141], v[190:193], v[58:61]
	v_mfma_f32_16x16x32_f16 v[46:49], v[130:133], v[206:209], v[46:49]
	v_mfma_f32_16x16x32_f16 v[42:45], v[138:141], v[206:209], v[42:45]
	v_mfma_f32_16x16x32_f16 v[30:33], v[130:133], v[214:217], v[30:33]
	v_mfma_f32_16x16x32_f16 v[26:29], v[138:141], v[214:217], v[26:29]
	v_mfma_f32_16x16x32_f16 v[14:17], v[130:133], v[222:225], v[14:17]
	v_mfma_f32_16x16x32_f16 v[10:13], v[138:141], v[222:225], v[10:13]
	v_mfma_f32_16x16x32_f16 v[62:65], v[134:137], v[194:197], v[62:65]
	v_mfma_f32_16x16x32_f16 v[58:61], v[142:145], v[194:197], v[58:61]
	v_mfma_f32_16x16x32_f16 v[46:49], v[134:137], v[210:213], v[46:49]
	v_mfma_f32_16x16x32_f16 v[42:45], v[142:145], v[210:213], v[42:45]
	v_mfma_f32_16x16x32_f16 v[30:33], v[134:137], v[218:221], v[30:33]
	v_mfma_f32_16x16x32_f16 v[26:29], v[142:145], v[218:221], v[26:29]
	v_mfma_f32_16x16x32_f16 v[14:17], v[134:137], v[226:229], v[14:17]
	v_mfma_f32_16x16x32_f16 v[10:13], v[142:145], v[226:229], v[10:13]
	v_mfma_f32_16x16x32_f16 v[54:57], v[146:149], v[190:193], v[54:57]
	v_mfma_f32_16x16x32_f16 v[50:53], v[182:185], v[190:193], v[50:53]
	v_mfma_f32_16x16x32_f16 v[38:41], v[146:149], v[206:209], v[38:41]
	v_mfma_f32_16x16x32_f16 v[34:37], v[182:185], v[206:209], v[34:37]
	v_mfma_f32_16x16x32_f16 v[22:25], v[146:149], v[214:217], v[22:25]
	v_mfma_f32_16x16x32_f16 v[18:21], v[182:185], v[214:217], v[18:21]
	v_mfma_f32_16x16x32_f16 v[6:9], v[146:149], v[222:225], v[6:9]
	v_mfma_f32_16x16x32_f16 v[2:5], v[182:185], v[222:225], v[2:5]
	v_mfma_f32_16x16x32_f16 v[54:57], v[150:153], v[194:197], v[54:57]
	v_mfma_f32_16x16x32_f16 v[50:53], v[186:189], v[194:197], v[50:53]
	v_mfma_f32_16x16x32_f16 v[38:41], v[150:153], v[210:213], v[38:41]
	v_mfma_f32_16x16x32_f16 v[34:37], v[186:189], v[210:213], v[34:37]
	v_mfma_f32_16x16x32_f16 v[22:25], v[150:153], v[218:221], v[22:25]
	v_mfma_f32_16x16x32_f16 v[18:21], v[186:189], v[218:221], v[18:21]
	v_mfma_f32_16x16x32_f16 v[6:9], v[150:153], v[226:229], v[6:9]
	v_mfma_f32_16x16x32_f16 v[2:5], v[186:189], v[226:229], v[2:5]
	s_barrier
; #define PG8_STAGE(bufoff, gbase, voff) do { _Pragma("unroll") for (int _i = 0; _i < 2; ++_i) \
;         __builtin_amdgcn_global_load_lds((const unsigned*)((const char*)(gbase) + (voff)[_i]), (PG8_LAS unsigned*)(lds + (bufoff) + ldsw + _i * 8192), 16, 0, 0); } while (0)
; #define PG8_LDA(dst, b, h) do { _Pragma("unroll") for (int m = 0; m < 4; ++m) _Pragma("unroll") for (int k = 0; k < 2; ++k) dst[m][k] = *(const PG8_LAS bf16x8*)(lds + PG8_SA(b, h) + aoff + m * 2048 + k * 1024); } while (0)
; #define PG8_LDB(dst, b, h) do { _Pragma("unroll") for (int n = 0; n < 2; ++n) _Pragma("unroll") for (int k = 0; k < 2; ++k) dst[n][k] = *(const PG8_LAS bf16x8*)(lds + PG8_SB(b, h) + boff + n * 2048 + k * 1024); } while (0)
; #define PG8_WAIT_V(n) asm volatile("s_waitcnt vmcnt(" #n ")" ::: "memory")
; #define PG8_WAIT_L(n) asm volatile("s_waitcnt lgkmcnt(" #n ")" ::: "memory")
; #define PG8_BAR __builtin_amdgcn_s_barrier()
; #define PG8_SCHED __builtin_amdgcn_sched_barrier(0)
; template <class Epi, class Sched, bool ALIGN_EPI = false, bool SP2 = false, bool F16 = false>
; __device__ __forceinline__ void gemm_phase(PG8_LAS unsigned char* lds, const Gemm g, const Sched& S, const Epi& E) {
;     ...
;         for (int t = 0; t < nt; t += 2) {
;             const bool last = (t == nt - 2);
;             const char* a1 = cA + (size_t)(t + 1) * kstep;
;             const char* a2 = last ? nA : cA + (size_t)(t + 2) * kstep; const char* b2 = last ? nB : cB + (size_t)(t + 2) * kstep;
;             const char* a3 = a2 + kstep; const char* b3 = b2 + kstep;
;     ...
;             PG8_LDB(B0, 1, 0); PG8_LDB(B1, 1, 1); PG8_SCHED; PG8_LDA(At, 1, 0); PG8_STAGE(PG8_SA(0, 1), a2 + hstepA, voffA);
;             PG8_WAIT_V(8); PG8_WAIT_L(0); PG8_BAR; PG8_MMA(0, 0, At, B0); PG8_MMA(0, 1, At, B1); PG8_BAR; PG8_SCHED;
;             PG8_LDA(At, 1, 1); PG8_STAGE(PG8_SB(1, 0), b3, voffB); PG8_STAGE(PG8_SB(1, 1), b3 + hstepB, voffB); PG8_STAGE(PG8_SA(1, 0), a3, voffA);
;             PG8_WAIT_V(8); PG8_WAIT_L(0); PG8_BAR; PG8_MMA(1, 0, At, B0); PG8_MMA(1, 1, At, B1); PG8_BAR; PG8_SCHED;
	s_setprio 0
	s_add_i32 s82, 0, 0x18000
	s_add_i32 s83, 0, 0x1c000
	ds_read_b128 v[130:133], v159
	ds_read_b128 v[134:137], v159 offset:1024
	ds_read_b128 v[138:141], v159 offset:2048
	ds_read_b128 v[142:145], v159 offset:3072
	ds_read_b128 v[146:149], v161
	ds_read_b128 v[150:153], v161 offset:1024
	ds_read_b128 v[182:185], v161 offset:2048
	ds_read_b128 v[186:189], v161 offset:3072
	s_add_u32 s52, s52, s8
	s_addc_u32 s53, s53, 0
	s_mov_b32 m0, s22
	ds_read_b128 v[190:193], v204 offset:32768
	ds_read_b128 v[194:197], v204 offset:33792
	ds_read_b128 v[206:209], v204 offset:34816
	ds_read_b128 v[210:213], v204 offset:35840
	ds_read_b128 v[214:217], v204 offset:36864
	ds_read_b128 v[218:221], v204 offset:37888
	ds_read_b128 v[222:225], v204 offset:38912
	ds_read_b128 v[226:229], v204 offset:39936
	global_load_lds_dwordx4 v154, s[52:53]
	s_mov_b32 m0, s23
	s_nop 0
	global_load_lds_dwordx4 v158, s[52:53]
	s_waitcnt vmcnt(8) lgkmcnt(0)
	s_setprio 1
	s_barrier
	v_mfma_f32_16x16x32_f16 v[122:125], v[130:133], v[190:193], v[122:125]
	v_mfma_f32_16x16x32_f16 v[126:129], v[138:141], v[190:193], v[126:129]
	v_mfma_f32_16x16x32_f16 v[110:113], v[130:133], v[206:209], v[110:113]
	v_mfma_f32_16x16x32_f16 v[106:109], v[138:141], v[206:209], v[106:109]
	v_mfma_f32_16x16x32_f16 v[94:97], v[130:133], v[214:217], v[94:97]
	v_mfma_f32_16x16x32_f16 v[90:93], v[138:141], v[214:217], v[90:93]
	v_mfma_f32_16x16x32_f16 v[78:81], v[130:133], v[222:225], v[78:81]
	v_mfma_f32_16x16x32_f16 v[74:77], v[138:141], v[222:225], v[74:77]
	v_mfma_f32_16x16x32_f16 v[122:125], v[134:137], v[194:197], v[122:125]
	v_mfma_f32_16x16x32_f16 v[126:129], v[142:145], v[194:197], v[126:129]
	v_mfma_f32_16x16x32_f16 v[110:113], v[134:137], v[210:213], v[110:113]
	v_mfma_f32_16x16x32_f16 v[106:109], v[142:145], v[210:213], v[106:109]
	v_mfma_f32_16x16x32_f16 v[94:97], v[134:137], v[218:221], v[94:97]
	v_mfma_f32_16x16x32_f16 v[90:93], v[142:145], v[218:221], v[90:93]
	v_mfma_f32_16x16x32_f16 v[78:81], v[134:137], v[226:229], v[78:81]
	v_mfma_f32_16x16x32_f16 v[74:77], v[142:145], v[226:229], v[74:77]
	v_mfma_f32_16x16x32_f16 v[118:121], v[146:149], v[190:193], v[118:121]
	v_mfma_f32_16x16x32_f16 v[114:117], v[182:185], v[190:193], v[114:117]
	v_mfma_f32_16x16x32_f16 v[102:105], v[146:149], v[206:209], v[102:105]
	v_mfma_f32_16x16x32_f16 v[98:101], v[182:185], v[206:209], v[98:101]
	v_mfma_f32_16x16x32_f16 v[86:89], v[146:149], v[214:217], v[86:89]
	v_mfma_f32_16x16x32_f16 v[82:85], v[182:185], v[214:217], v[82:85]
	v_mfma_f32_16x16x32_f16 v[70:73], v[146:149], v[222:225], v[70:73]
	v_mfma_f32_16x16x32_f16 v[66:69], v[182:185], v[222:225], v[66:69]
	v_mfma_f32_16x16x32_f16 v[118:121], v[150:153], v[194:197], v[118:121]
	v_mfma_f32_16x16x32_f16 v[114:117], v[186:189], v[194:197], v[114:117]
	v_mfma_f32_16x16x32_f16 v[102:105], v[150:153], v[210:213], v[102:105]
	v_mfma_f32_16x16x32_f16 v[98:101], v[186:189], v[210:213], v[98:101]
	v_mfma_f32_16x16x32_f16 v[86:89], v[150:153], v[218:221], v[86:89]
	v_mfma_f32_16x16x32_f16 v[82:85], v[186:189], v[218:221], v[82:85]
	v_mfma_f32_16x16x32_f16 v[70:73], v[150:153], v[226:229], v[70:73]
	v_mfma_f32_16x16x32_f16 v[66:69], v[186:189], v[226:229], v[66:69]
	s_barrier
	s_setprio 0
	s_add_i32 s52, s82, s75
	s_add_i32 vcc_hi, s73, -2
	s_cmp_eq_u32 s74, vcc_hi
	s_cselect_b32 s99, s55, s72
	s_cselect_b32 s98, s54, s24
	s_add_u32 s98, s98, s92
	s_addc_u32 s99, s99, s93
	s_mov_b32 m0, s52
	s_nop 0
	global_load_lds_dwordx4 v156, s[98:99]
	ds_read_b128 v[190:193], v204 offset:49152
	ds_read_b128 v[194:197], v204 offset:50176
	ds_read_b128 v[206:209], v204 offset:51200
	ds_read_b128 v[210:213], v204 offset:52224
	ds_read_b128 v[214:217], v204 offset:53248
	ds_read_b128 v[218:221], v204 offset:54272
	ds_read_b128 v[222:225], v204 offset:55296
	ds_read_b128 v[226:229], v204 offset:56320
	s_add_i32 m0, s52, 0x2000
	s_nop 0
	global_load_lds_dwordx4 v160, s[98:99]
	s_add_i32 s52, s83, s75
	s_add_u32 s98, s98, s48
	s_addc_u32 s99, s99, 0
	s_mov_b32 m0, s52
	s_nop 0
	global_load_lds_dwordx4 v156, s[98:99]
	s_add_i32 m0, s52, 0x2000
	s_nop 0
	global_load_lds_dwordx4 v160, s[98:99]
	s_add_u32 s98, s44, 0x80
	s_addc_u32 s99, s45, 0
	s_cmp_eq_u32 s74, vcc_hi
	s_cselect_b32 s99, s79, s99
	s_cselect_b32 s98, s78, s98
	s_add_u32 s98, s98, s92
	s_addc_u32 s99, s99, s93
	s_mov_b32 m0, s61
	s_nop 0
	global_load_lds_dwordx4 v154, s[98:99]
	s_mov_b32 m0, s18
	s_nop 0
	global_load_lds_dwordx4 v158, s[98:99]
	s_waitcnt vmcnt(8) lgkmcnt(0)
	s_setprio 1
	s_barrier
	v_mfma_f32_16x16x32_f16 v[62:65], v[130:133], v[190:193], v[62:65]
	v_mfma_f32_16x16x32_f16 v[58:61], v[138:141], v[190:193], v[58:61]
	v_mfma_f32_16x16x32_f16 v[46:49], v[130:133], v[206:209], v[46:49]
	v_mfma_f32_16x16x32_f16 v[42:45], v[138:141], v[206:209], v[42:45]
	v_mfma_f32_16x16x32_f16 v[30:33], v[130:133], v[214:217], v[30:33]
	v_mfma_f32_16x16x32_f16 v[26:29], v[138:141], v[214:217], v[26:29]
	v_mfma_f32_16x16x32_f16 v[14:17], v[130:133], v[222:225], v[14:17]
	v_mfma_f32_16x16x32_f16 v[10:13], v[138:141], v[222:225], v[10:13]
	v_mfma_f32_16x16x32_f16 v[62:65], v[134:137], v[194:197], v[62:65]
	v_mfma_f32_16x16x32_f16 v[58:61], v[142:145], v[194:197], v[58:61]
	v_mfma_f32_16x16x32_f16 v[46:49], v[134:137], v[210:213], v[46:49]
	v_mfma_f32_16x16x32_f16 v[42:45], v[142:145], v[210:213], v[42:45]
	v_mfma_f32_16x16x32_f16 v[30:33], v[134:137], v[218:221], v[30:33]
	v_mfma_f32_16x16x32_f16 v[26:29], v[142:145], v[218:221], v[26:29]
	v_mfma_f32_16x16x32_f16 v[14:17], v[134:137], v[226:229], v[14:17]
	v_mfma_f32_16x16x32_f16 v[10:13], v[142:145], v[226:229], v[10:13]
	v_mfma_f32_16x16x32_f16 v[54:57], v[146:149], v[190:193], v[54:57]
	v_mfma_f32_16x16x32_f16 v[50:53], v[182:185], v[190:193], v[50:53]
	v_mfma_f32_16x16x32_f16 v[38:41], v[146:149], v[206:209], v[38:41]
	v_mfma_f32_16x16x32_f16 v[34:37], v[182:185], v[206:209], v[34:37]
	v_mfma_f32_16x16x32_f16 v[22:25], v[146:149], v[214:217], v[22:25]
	v_mfma_f32_16x16x32_f16 v[18:21], v[182:185], v[214:217], v[18:21]
	v_mfma_f32_16x16x32_f16 v[6:9], v[146:149], v[222:225], v[6:9]
	v_mfma_f32_16x16x32_f16 v[2:5], v[182:185], v[222:225], v[2:5]
	v_mfma_f32_16x16x32_f16 v[54:57], v[150:153], v[194:197], v[54:57]
	v_mfma_f32_16x16x32_f16 v[50:53], v[186:189], v[194:197], v[50:53]
	v_mfma_f32_16x16x32_f16 v[38:41], v[150:153], v[210:213], v[38:41]
	v_mfma_f32_16x16x32_f16 v[34:37], v[186:189], v[210:213], v[34:37]
	v_mfma_f32_16x16x32_f16 v[22:25], v[150:153], v[218:221], v[22:25]
	v_mfma_f32_16x16x32_f16 v[18:21], v[186:189], v[218:221], v[18:21]
	v_mfma_f32_16x16x32_f16 v[6:9], v[150:153], v[226:229], v[6:9]
	v_mfma_f32_16x16x32_f16 v[2:5], v[186:189], v[226:229], v[2:5]
	s_barrier
	s_setprio 0
	s_add_u32 s44, s44, 0x100
	s_addc_u32 s45, s45, 0
	s_add_u32 s24, s24, 0x100
	s_addc_u32 s72, s72, 0
	s_cmp_ge_u32 s73, s65
	s_mov_b32 s52, s73
	s_cbranch_scc0 .LBB0_564
